# hand-scheduled gemm256 K-loop (1 barrier per 32-deep stage, DMA interleaved with MFMA) in all 8 GEMM phases
# speedup vs baseline: 1.0533x; 1.0533x over previous
; #define LGKM0_BAR asm volatile("s_waitcnt lgkmcnt(0)\n\ts_barrier" ::: "memory");
; __device__ __forceinline__ void gemm256_tile(const u16* Ab, int lda, const u16* Bb, int ldb, int K, char* smem,
;                                              f32x16 (&acc)[2][4]) {
;     ...
;   const int xsw = (lane >> 2) & 3, hh = lane >> 5;
;   const unsigned fo0 = (unsigned)((hh ^ xsw) * 16), fo1 = (unsigned)(((2 + hh) ^ xsw) * 16);
;   const unsigned fa = (unsigned)((wm * 64 + (lane & 31)) * 64);
;   const unsigned fb = (unsigned)(16384 + (wn * 128 + (lane & 31)) * 64);
;     ...
;   asm volatile("s_waitcnt vmcnt(0)" ::: "memory");
;   const bool h1 = __builtin_amdgcn_readfirstlane(wid) >= 4;
;     ...
;   DMA_STAGE(0)
;   if (nks > 1) DMA_STAGE(1)
;   if (nks > 2) DMA_STAGE(2)
;   if (nks > 3) DMA_STAGE(3)
;   if (nks > 3)      asm volatile("s_waitcnt vmcnt(12)\n\ts_barrier" ::: "memory");
;   else if (nks > 2) asm volatile("s_waitcnt vmcnt(8)\n\ts_barrier" ::: "memory");
;   else if (nks > 1) asm volatile("s_waitcnt vmcnt(4)\n\ts_barrier" ::: "memory");
;   else              asm volatile("s_waitcnt vmcnt(0)\n\ts_barrier" ::: "memory");
;   bf16x8 afA[2], bfA[4], afB[2], bfB[4];
;   if (!h1) {
;     G_FRAGS(afA, bfA, 0, fo0)
;     LGKM0_BAR
;     for (int s = 0; s < nks; ++s) {
;       const int q = s & 3;
;       G_MMA(afA, bfA)
;       __builtin_amdgcn_sched_barrier(0);
;       LGKM0_BAR
;       G_FRAGS(afB, bfB, q, fo1)
;       __builtin_amdgcn_sched_barrier(0);
;       LGKM0_BAR
;       G_MMA(afB, bfB)
;       __builtin_amdgcn_sched_barrier(0);
;       G_WAIT_BAR(s)
;       if (s + 4 < nks) DMA_STAGE(s + 4)
;       if (s + 1 < nks) G_FRAGS(afA, bfA, (s + 1) & 3, fo0)
;       __builtin_amdgcn_sched_barrier(0);
;       LGKM0_BAR
;     }
.LBB0_197:
	v_lshrrev_b32_e32 v192, 6, v152
	v_bfe_u32 v193, v152, 2, 2
	v_readfirstlane_b32 s98, v192
	v_bfe_u32 v194, v152, 5, 1
	v_xor_b32_e32 v193, v194, v193
	v_lshlrev_b32_e32 v193, 4, v193
	v_xor_b32_e32 v194, 32, v193
	v_and_b32_e32 v195, 31, v152
	v_lshrrev_b32_e32 v196, 7, v152
	v_lshl_add_u32 v196, v196, 6, v195
	v_lshlrev_b32_e32 v196, 6, v196
	v_bfe_u32 v197, v152, 6, 1
	v_lshl_add_u32 v197, v197, 7, v195
	v_lshlrev_b32_e32 v197, 6, v197
	v_add3_u32 v154, v196, v193, 16
	v_add3_u32 v253, v196, v194, 16
	v_add3_u32 v254, v197, v193, 16
	v_add3_u32 v255, v197, v194, 16
	s_lshl_b32 s98, s98, 10
	s_add_u32 s98, s98, 16
	v_lshl_add_u64 v[164:165], 64, 2, v[164:165]
	v_lshl_add_u64 v[160:161], 64, 2, v[160:161]
	v_lshl_add_u64 v[166:167], 64, 2, v[166:167]
	v_lshl_add_u64 v[162:163], 64, 2, v[162:163]
	s_barrier
	ds_read_b128 v[128:131], v154
	ds_read_b128 v[132:135], v154 offset:2048
	ds_read_b128 v[136:139], v254 offset:16384
	ds_read_b128 v[140:143], v254 offset:18432
	ds_read_b128 v[144:147], v254 offset:20480
	ds_read_b128 v[148:151], v254 offset:22528
	s_waitcnt lgkmcnt(0)
	v_mfma_f32_32x32x16_bf16 v[112:127], v[128:131], v[136:139], 0
	v_mfma_f32_32x32x16_bf16 v[96:111], v[128:131], v[140:143], 0
	ds_read_b128 v[192:195], v253
	ds_read_b128 v[196:199], v253 offset:2048
	v_mfma_f32_32x32x16_bf16 v[80:95], v[128:131], v[144:147], 0
	ds_read_b128 v[200:203], v255 offset:16384
	ds_read_b128 v[206:209], v255 offset:18432
	v_mfma_f32_32x32x16_bf16 v[64:79], v[128:131], v[148:151], 0
	ds_read_b128 v[210:213], v255 offset:20480
	ds_read_b128 v[214:217], v255 offset:22528
	v_mfma_f32_32x32x16_bf16 v[48:63], v[132:135], v[136:139], 0
	v_mfma_f32_32x32x16_bf16 v[32:47], v[132:135], v[140:143], 0
	v_mfma_f32_32x32x16_bf16 v[16:31], v[132:135], v[144:147], 0
	v_mfma_f32_32x32x16_bf16 v[0:15], v[132:135], v[148:151], 0
	s_waitcnt vmcnt(8)
	s_waitcnt lgkmcnt(0)
	s_barrier
	ds_read_b128 v[128:131], v154 offset:32768
	ds_read_b128 v[132:135], v154 offset:34816
	ds_read_b128 v[136:139], v254 offset:49152
	ds_read_b128 v[140:143], v254 offset:51200
	ds_read_b128 v[144:147], v254 offset:53248
	ds_read_b128 v[148:151], v254 offset:55296
	v_xor_b32_e32 v154, 0x10000, v154
	v_xor_b32_e32 v254, 0x10000, v254
	s_add_u32 m0, s98, 0x0
	v_mfma_f32_32x32x16_bf16 v[112:127], v[192:195], v[200:203], v[112:127]
	global_load_lds_dwordx4 v[164:165], off
	v_mfma_f32_32x32x16_bf16 v[96:111], v[192:195], v[206:209], v[96:111]
	s_add_u32 m0, s98, 0x2000
	v_mfma_f32_32x32x16_bf16 v[80:95], v[192:195], v[210:213], v[80:95]
	global_load_lds_dwordx4 v[160:161], off
	v_mfma_f32_32x32x16_bf16 v[64:79], v[192:195], v[214:217], v[64:79]
	s_add_u32 m0, s98, 0x4000
	v_mfma_f32_32x32x16_bf16 v[48:63], v[196:199], v[200:203], v[48:63]
	global_load_lds_dwordx4 v[166:167], off
	v_mfma_f32_32x32x16_bf16 v[32:47], v[196:199], v[206:209], v[32:47]
	s_add_u32 m0, s98, 0x6000
	v_mfma_f32_32x32x16_bf16 v[16:31], v[196:199], v[210:213], v[16:31]
	global_load_lds_dwordx4 v[162:163], off
	v_mfma_f32_32x32x16_bf16 v[0:15], v[196:199], v[214:217], v[0:15]
	v_lshl_add_u64 v[164:165], v[164:165], 0, 64
	v_lshl_add_u64 v[160:161], v[160:161], 0, 64
	v_lshl_add_u64 v[166:167], v[166:167], 0, 64
	v_lshl_add_u64 v[162:163], v[162:163], 0, 64
	s_waitcnt lgkmcnt(0)
	v_mfma_f32_32x32x16_bf16 v[112:127], v[128:131], v[136:139], v[112:127]
	v_mfma_f32_32x32x16_bf16 v[96:111], v[128:131], v[140:143], v[96:111]
	ds_read_b128 v[192:195], v253 offset:32768
	ds_read_b128 v[196:199], v253 offset:34816
	v_mfma_f32_32x32x16_bf16 v[80:95], v[128:131], v[144:147], v[80:95]
	ds_read_b128 v[200:203], v255 offset:49152
	ds_read_b128 v[206:209], v255 offset:51200
	v_mfma_f32_32x32x16_bf16 v[64:79], v[128:131], v[148:151], v[64:79]
	ds_read_b128 v[210:213], v255 offset:53248
	ds_read_b128 v[214:217], v255 offset:55296
	v_mfma_f32_32x32x16_bf16 v[48:63], v[132:135], v[136:139], v[48:63]
	v_mfma_f32_32x32x16_bf16 v[32:47], v[132:135], v[140:143], v[32:47]
	v_mfma_f32_32x32x16_bf16 v[16:31], v[132:135], v[144:147], v[16:31]
	v_mfma_f32_32x32x16_bf16 v[0:15], v[132:135], v[148:151], v[0:15]
	v_xor_b32_e32 v253, 0x10000, v253
	v_xor_b32_e32 v255, 0x10000, v255
	s_waitcnt vmcnt(8)
	s_waitcnt lgkmcnt(0)
	s_barrier
	ds_read_b128 v[128:131], v154
	ds_read_b128 v[132:135], v154 offset:2048
	ds_read_b128 v[136:139], v254 offset:16384
	ds_read_b128 v[140:143], v254 offset:18432
	ds_read_b128 v[144:147], v254 offset:20480
	ds_read_b128 v[148:151], v254 offset:22528
	s_add_u32 m0, s98, 0x8000
	v_mfma_f32_32x32x16_bf16 v[112:127], v[192:195], v[200:203], v[112:127]
	global_load_lds_dwordx4 v[164:165], off
	v_mfma_f32_32x32x16_bf16 v[96:111], v[192:195], v[206:209], v[96:111]
	s_add_u32 m0, s98, 0xa000
	v_mfma_f32_32x32x16_bf16 v[80:95], v[192:195], v[210:213], v[80:95]
	global_load_lds_dwordx4 v[160:161], off
	v_mfma_f32_32x32x16_bf16 v[64:79], v[192:195], v[214:217], v[64:79]
	s_add_u32 m0, s98, 0xc000
	v_mfma_f32_32x32x16_bf16 v[48:63], v[196:199], v[200:203], v[48:63]
	global_load_lds_dwordx4 v[166:167], off
	v_mfma_f32_32x32x16_bf16 v[32:47], v[196:199], v[206:209], v[32:47]
	s_add_u32 m0, s98, 0xe000
	v_mfma_f32_32x32x16_bf16 v[16:31], v[196:199], v[210:213], v[16:31]
	global_load_lds_dwordx4 v[162:163], off
	v_mfma_f32_32x32x16_bf16 v[0:15], v[196:199], v[214:217], v[0:15]
	v_lshl_add_u64 v[164:165], v[164:165], 0, 64
	v_lshl_add_u64 v[160:161], v[160:161], 0, 64
	v_lshl_add_u64 v[166:167], v[166:167], 0, 64
	v_lshl_add_u64 v[162:163], v[162:163], 0, 64
	s_waitcnt lgkmcnt(0)
	v_mfma_f32_32x32x16_bf16 v[112:127], v[128:131], v[136:139], v[112:127]
	v_mfma_f32_32x32x16_bf16 v[96:111], v[128:131], v[140:143], v[96:111]
	ds_read_b128 v[192:195], v253
	ds_read_b128 v[196:199], v253 offset:2048
	v_mfma_f32_32x32x16_bf16 v[80:95], v[128:131], v[144:147], v[80:95]
	ds_read_b128 v[200:203], v255 offset:16384
	ds_read_b128 v[206:209], v255 offset:18432
	v_mfma_f32_32x32x16_bf16 v[64:79], v[128:131], v[148:151], v[64:79]
	ds_read_b128 v[210:213], v255 offset:20480
	ds_read_b128 v[214:217], v255 offset:22528
	v_mfma_f32_32x32x16_bf16 v[48:63], v[132:135], v[136:139], v[48:63]
	v_mfma_f32_32x32x16_bf16 v[32:47], v[132:135], v[140:143], v[32:47]
	v_mfma_f32_32x32x16_bf16 v[16:31], v[132:135], v[144:147], v[16:31]
	v_mfma_f32_32x32x16_bf16 v[0:15], v[132:135], v[148:151], v[0:15]
	s_waitcnt vmcnt(8)
	s_waitcnt lgkmcnt(0)
	s_barrier
; #define LGKM0_BAR asm volatile("s_waitcnt lgkmcnt(0)\n\ts_barrier" ::: "memory");
; __device__ __forceinline__ void gemm256_tile(const u16* Ab, int lda, const u16* Bb, int ldb, int K, char* smem,
;                                              f32x16 (&acc)[2][4]) {
;     ...
;     for (int s = 0; s < nks; ++s) {
;       const int q = s & 3;
;       G_MMA(afA, bfA)
;       __builtin_amdgcn_sched_barrier(0);
;       LGKM0_BAR
;       G_FRAGS(afB, bfB, q, fo1)
;       __builtin_amdgcn_sched_barrier(0);
;       LGKM0_BAR
;       G_MMA(afB, bfB)
;       __builtin_amdgcn_sched_barrier(0);
;       G_WAIT_BAR(s)
;       if (s + 4 < nks) DMA_STAGE(s + 4)
;       if (s + 1 < nks) G_FRAGS(afA, bfA, (s + 1) & 3, fo0)
;       __builtin_amdgcn_sched_barrier(0);
;       LGKM0_BAR
;     }
	ds_read_b128 v[128:131], v154 offset:32768
	ds_read_b128 v[132:135], v154 offset:34816
	ds_read_b128 v[136:139], v254 offset:49152
	ds_read_b128 v[140:143], v254 offset:51200
	ds_read_b128 v[144:147], v254 offset:53248
	ds_read_b128 v[148:151], v254 offset:55296
	v_xor_b32_e32 v154, 0x10000, v154
	v_xor_b32_e32 v254, 0x10000, v254
	s_add_u32 m0, s98, 0x10000
	v_mfma_f32_32x32x16_bf16 v[112:127], v[192:195], v[200:203], v[112:127]
	global_load_lds_dwordx4 v[164:165], off
	v_mfma_f32_32x32x16_bf16 v[96:111], v[192:195], v[206:209], v[96:111]
	s_add_u32 m0, s98, 0x12000
	v_mfma_f32_32x32x16_bf16 v[80:95], v[192:195], v[210:213], v[80:95]
	global_load_lds_dwordx4 v[160:161], off
	v_mfma_f32_32x32x16_bf16 v[64:79], v[192:195], v[214:217], v[64:79]
	s_add_u32 m0, s98, 0x14000
	v_mfma_f32_32x32x16_bf16 v[48:63], v[196:199], v[200:203], v[48:63]
	global_load_lds_dwordx4 v[166:167], off
	v_mfma_f32_32x32x16_bf16 v[32:47], v[196:199], v[206:209], v[32:47]
	s_add_u32 m0, s98, 0x16000
	v_mfma_f32_32x32x16_bf16 v[16:31], v[196:199], v[210:213], v[16:31]
	global_load_lds_dwordx4 v[162:163], off
	v_mfma_f32_32x32x16_bf16 v[0:15], v[196:199], v[214:217], v[0:15]
	v_lshl_add_u64 v[164:165], v[164:165], 0, 64
	v_lshl_add_u64 v[160:161], v[160:161], 0, 64
	v_lshl_add_u64 v[166:167], v[166:167], 0, 64
	v_lshl_add_u64 v[162:163], v[162:163], 0, 64
	s_waitcnt lgkmcnt(0)
	v_mfma_f32_32x32x16_bf16 v[112:127], v[128:131], v[136:139], v[112:127]
	v_mfma_f32_32x32x16_bf16 v[96:111], v[128:131], v[140:143], v[96:111]
	ds_read_b128 v[192:195], v253 offset:32768
	ds_read_b128 v[196:199], v253 offset:34816
	v_mfma_f32_32x32x16_bf16 v[80:95], v[128:131], v[144:147], v[80:95]
	ds_read_b128 v[200:203], v255 offset:49152
	ds_read_b128 v[206:209], v255 offset:51200
	v_mfma_f32_32x32x16_bf16 v[64:79], v[128:131], v[148:151], v[64:79]
	ds_read_b128 v[210:213], v255 offset:53248
	ds_read_b128 v[214:217], v255 offset:55296
	v_mfma_f32_32x32x16_bf16 v[48:63], v[132:135], v[136:139], v[48:63]
	v_mfma_f32_32x32x16_bf16 v[32:47], v[132:135], v[140:143], v[32:47]
	v_mfma_f32_32x32x16_bf16 v[16:31], v[132:135], v[144:147], v[16:31]
	v_mfma_f32_32x32x16_bf16 v[0:15], v[132:135], v[148:151], v[0:15]
	v_xor_b32_e32 v253, 0x10000, v253
	v_xor_b32_e32 v255, 0x10000, v255
	s_waitcnt vmcnt(8)
	s_waitcnt lgkmcnt(0)
	s_mov_b32 s99, 6
.Lmy_gemm_i0_loop:
	s_barrier
	ds_read_b128 v[128:131], v154
	ds_read_b128 v[132:135], v154 offset:2048
	ds_read_b128 v[136:139], v254 offset:16384
	ds_read_b128 v[140:143], v254 offset:18432
	ds_read_b128 v[144:147], v254 offset:20480
	ds_read_b128 v[148:151], v254 offset:22528
	s_add_u32 m0, s98, 0x18000
	v_mfma_f32_32x32x16_bf16 v[112:127], v[192:195], v[200:203], v[112:127]
	global_load_lds_dwordx4 v[164:165], off
	v_mfma_f32_32x32x16_bf16 v[96:111], v[192:195], v[206:209], v[96:111]
	s_add_u32 m0, s98, 0x1a000
	v_mfma_f32_32x32x16_bf16 v[80:95], v[192:195], v[210:213], v[80:95]
	global_load_lds_dwordx4 v[160:161], off
	v_mfma_f32_32x32x16_bf16 v[64:79], v[192:195], v[214:217], v[64:79]
	s_add_u32 m0, s98, 0x1c000
	v_mfma_f32_32x32x16_bf16 v[48:63], v[196:199], v[200:203], v[48:63]
	global_load_lds_dwordx4 v[166:167], off
	v_mfma_f32_32x32x16_bf16 v[32:47], v[196:199], v[206:209], v[32:47]
	s_add_u32 m0, s98, 0x1e000
	v_mfma_f32_32x32x16_bf16 v[16:31], v[196:199], v[210:213], v[16:31]
	global_load_lds_dwordx4 v[162:163], off
	v_mfma_f32_32x32x16_bf16 v[0:15], v[196:199], v[214:217], v[0:15]
	v_lshl_add_u64 v[164:165], v[164:165], 0, 64
	v_lshl_add_u64 v[160:161], v[160:161], 0, 64
	v_lshl_add_u64 v[166:167], v[166:167], 0, 64
	v_lshl_add_u64 v[162:163], v[162:163], 0, 64
	s_waitcnt lgkmcnt(0)
	v_mfma_f32_32x32x16_bf16 v[112:127], v[128:131], v[136:139], v[112:127]
	v_mfma_f32_32x32x16_bf16 v[96:111], v[128:131], v[140:143], v[96:111]
	ds_read_b128 v[192:195], v253
	ds_read_b128 v[196:199], v253 offset:2048
	v_mfma_f32_32x32x16_bf16 v[80:95], v[128:131], v[144:147], v[80:95]
	ds_read_b128 v[200:203], v255 offset:16384
	ds_read_b128 v[206:209], v255 offset:18432
	v_mfma_f32_32x32x16_bf16 v[64:79], v[128:131], v[148:151], v[64:79]
	ds_read_b128 v[210:213], v255 offset:20480
	ds_read_b128 v[214:217], v255 offset:22528
	v_mfma_f32_32x32x16_bf16 v[48:63], v[132:135], v[136:139], v[48:63]
	v_mfma_f32_32x32x16_bf16 v[32:47], v[132:135], v[140:143], v[32:47]
	v_mfma_f32_32x32x16_bf16 v[16:31], v[132:135], v[144:147], v[16:31]
	v_mfma_f32_32x32x16_bf16 v[0:15], v[132:135], v[148:151], v[0:15]
	s_waitcnt vmcnt(8)
	s_waitcnt lgkmcnt(0)
	s_barrier
; #define LGKM0_BAR asm volatile("s_waitcnt lgkmcnt(0)\n\ts_barrier" ::: "memory");
; __device__ __forceinline__ void gemm256_tile(const u16* Ab, int lda, const u16* Bb, int ldb, int K, char* smem,
;                                              f32x16 (&acc)[2][4]) {
;     ...
;     for (int s = 0; s < nks; ++s) {
;       const int q = s & 3;
;       G_MMA(afA, bfA)
;       __builtin_amdgcn_sched_barrier(0);
;       LGKM0_BAR
;       G_FRAGS(afB, bfB, q, fo1)
;       __builtin_amdgcn_sched_barrier(0);
;       LGKM0_BAR
;       G_MMA(afB, bfB)
;       __builtin_amdgcn_sched_barrier(0);
;       G_WAIT_BAR(s)
;       if (s + 4 < nks) DMA_STAGE(s + 4)
;       if (s + 1 < nks) G_FRAGS(afA, bfA, (s + 1) & 3, fo0)
;       __builtin_amdgcn_sched_barrier(0);
;       LGKM0_BAR
;     }
	ds_read_b128 v[128:131], v154 offset:32768
	ds_read_b128 v[132:135], v154 offset:34816
	ds_read_b128 v[136:139], v254 offset:49152
	ds_read_b128 v[140:143], v254 offset:51200
	ds_read_b128 v[144:147], v254 offset:53248
	ds_read_b128 v[148:151], v254 offset:55296
	v_xor_b32_e32 v154, 0x10000, v154
	v_xor_b32_e32 v254, 0x10000, v254
	s_add_u32 m0, s98, 0x0
	v_mfma_f32_32x32x16_bf16 v[112:127], v[192:195], v[200:203], v[112:127]
	global_load_lds_dwordx4 v[164:165], off
	v_mfma_f32_32x32x16_bf16 v[96:111], v[192:195], v[206:209], v[96:111]
	s_add_u32 m0, s98, 0x2000
	v_mfma_f32_32x32x16_bf16 v[80:95], v[192:195], v[210:213], v[80:95]
	global_load_lds_dwordx4 v[160:161], off
	v_mfma_f32_32x32x16_bf16 v[64:79], v[192:195], v[214:217], v[64:79]
	s_add_u32 m0, s98, 0x4000
	v_mfma_f32_32x32x16_bf16 v[48:63], v[196:199], v[200:203], v[48:63]
	global_load_lds_dwordx4 v[166:167], off
	v_mfma_f32_32x32x16_bf16 v[32:47], v[196:199], v[206:209], v[32:47]
	s_add_u32 m0, s98, 0x6000
	v_mfma_f32_32x32x16_bf16 v[16:31], v[196:199], v[210:213], v[16:31]
	global_load_lds_dwordx4 v[162:163], off
	v_mfma_f32_32x32x16_bf16 v[0:15], v[196:199], v[214:217], v[0:15]
	v_lshl_add_u64 v[164:165], v[164:165], 0, 64
	v_lshl_add_u64 v[160:161], v[160:161], 0, 64
	v_lshl_add_u64 v[166:167], v[166:167], 0, 64
	v_lshl_add_u64 v[162:163], v[162:163], 0, 64
	s_waitcnt lgkmcnt(0)
	v_mfma_f32_32x32x16_bf16 v[112:127], v[128:131], v[136:139], v[112:127]
	v_mfma_f32_32x32x16_bf16 v[96:111], v[128:131], v[140:143], v[96:111]
	ds_read_b128 v[192:195], v253 offset:32768
	ds_read_b128 v[196:199], v253 offset:34816
	v_mfma_f32_32x32x16_bf16 v[80:95], v[128:131], v[144:147], v[80:95]
	ds_read_b128 v[200:203], v255 offset:49152
	ds_read_b128 v[206:209], v255 offset:51200
	v_mfma_f32_32x32x16_bf16 v[64:79], v[128:131], v[148:151], v[64:79]
	ds_read_b128 v[210:213], v255 offset:53248
	ds_read_b128 v[214:217], v255 offset:55296
	v_mfma_f32_32x32x16_bf16 v[48:63], v[132:135], v[136:139], v[48:63]
	v_mfma_f32_32x32x16_bf16 v[32:47], v[132:135], v[140:143], v[32:47]
	v_mfma_f32_32x32x16_bf16 v[16:31], v[132:135], v[144:147], v[16:31]
	v_mfma_f32_32x32x16_bf16 v[0:15], v[132:135], v[148:151], v[0:15]
	v_xor_b32_e32 v253, 0x10000, v253
	v_xor_b32_e32 v255, 0x10000, v255
	s_waitcnt vmcnt(8)
	s_waitcnt lgkmcnt(0)
	s_barrier
	ds_read_b128 v[128:131], v154
	ds_read_b128 v[132:135], v154 offset:2048
	ds_read_b128 v[136:139], v254 offset:16384
	ds_read_b128 v[140:143], v254 offset:18432
	ds_read_b128 v[144:147], v254 offset:20480
	ds_read_b128 v[148:151], v254 offset:22528
	s_add_u32 m0, s98, 0x8000
	v_mfma_f32_32x32x16_bf16 v[112:127], v[192:195], v[200:203], v[112:127]
	global_load_lds_dwordx4 v[164:165], off
	v_mfma_f32_32x32x16_bf16 v[96:111], v[192:195], v[206:209], v[96:111]
	s_add_u32 m0, s98, 0xa000
	v_mfma_f32_32x32x16_bf16 v[80:95], v[192:195], v[210:213], v[80:95]
	global_load_lds_dwordx4 v[160:161], off
	v_mfma_f32_32x32x16_bf16 v[64:79], v[192:195], v[214:217], v[64:79]
	s_add_u32 m0, s98, 0xc000
	v_mfma_f32_32x32x16_bf16 v[48:63], v[196:199], v[200:203], v[48:63]
	global_load_lds_dwordx4 v[166:167], off
	v_mfma_f32_32x32x16_bf16 v[32:47], v[196:199], v[206:209], v[32:47]
	s_add_u32 m0, s98, 0xe000
	v_mfma_f32_32x32x16_bf16 v[16:31], v[196:199], v[210:213], v[16:31]
	global_load_lds_dwordx4 v[162:163], off
	v_mfma_f32_32x32x16_bf16 v[0:15], v[196:199], v[214:217], v[0:15]
	v_lshl_add_u64 v[164:165], v[164:165], 0, 64
	v_lshl_add_u64 v[160:161], v[160:161], 0, 64
	v_lshl_add_u64 v[166:167], v[166:167], 0, 64
	v_lshl_add_u64 v[162:163], v[162:163], 0, 64
	s_waitcnt lgkmcnt(0)
	v_mfma_f32_32x32x16_bf16 v[112:127], v[128:131], v[136:139], v[112:127]
	v_mfma_f32_32x32x16_bf16 v[96:111], v[128:131], v[140:143], v[96:111]
	ds_read_b128 v[192:195], v253
	ds_read_b128 v[196:199], v253 offset:2048
	v_mfma_f32_32x32x16_bf16 v[80:95], v[128:131], v[144:147], v[80:95]
	ds_read_b128 v[200:203], v255 offset:16384
	ds_read_b128 v[206:209], v255 offset:18432
	v_mfma_f32_32x32x16_bf16 v[64:79], v[128:131], v[148:151], v[64:79]
	ds_read_b128 v[210:213], v255 offset:20480
	ds_read_b128 v[214:217], v255 offset:22528
	v_mfma_f32_32x32x16_bf16 v[48:63], v[132:135], v[136:139], v[48:63]
	v_mfma_f32_32x32x16_bf16 v[32:47], v[132:135], v[140:143], v[32:47]
	v_mfma_f32_32x32x16_bf16 v[16:31], v[132:135], v[144:147], v[16:31]
	v_mfma_f32_32x32x16_bf16 v[0:15], v[132:135], v[148:151], v[0:15]
	s_waitcnt vmcnt(8)
	s_waitcnt lgkmcnt(0)
	s_barrier
; #define LGKM0_BAR asm volatile("s_waitcnt lgkmcnt(0)\n\ts_barrier" ::: "memory");
; __device__ __forceinline__ void gemm256_tile(const u16* Ab, int lda, const u16* Bb, int ldb, int K, char* smem,
;                                              f32x16 (&acc)[2][4]) {
;     ...
;     for (int s = 0; s < nks; ++s) {
;       const int q = s & 3;
;       G_MMA(afA, bfA)
;       __builtin_amdgcn_sched_barrier(0);
;       LGKM0_BAR
;       G_FRAGS(afB, bfB, q, fo1)
;       __builtin_amdgcn_sched_barrier(0);
;       LGKM0_BAR
;       G_MMA(afB, bfB)
;       __builtin_amdgcn_sched_barrier(0);
;       G_WAIT_BAR(s)
;       if (s + 4 < nks) DMA_STAGE(s + 4)
;       if (s + 1 < nks) G_FRAGS(afA, bfA, (s + 1) & 3, fo0)
;       __builtin_amdgcn_sched_barrier(0);
;       LGKM0_BAR
;     }
	ds_read_b128 v[128:131], v154 offset:32768
	ds_read_b128 v[132:135], v154 offset:34816
	ds_read_b128 v[136:139], v254 offset:49152
	ds_read_b128 v[140:143], v254 offset:51200
	ds_read_b128 v[144:147], v254 offset:53248
	ds_read_b128 v[148:151], v254 offset:55296
	v_xor_b32_e32 v154, 0x10000, v154
	v_xor_b32_e32 v254, 0x10000, v254
	s_add_u32 m0, s98, 0x10000
	v_mfma_f32_32x32x16_bf16 v[112:127], v[192:195], v[200:203], v[112:127]
	global_load_lds_dwordx4 v[164:165], off
	v_mfma_f32_32x32x16_bf16 v[96:111], v[192:195], v[206:209], v[96:111]
	s_add_u32 m0, s98, 0x12000
	v_mfma_f32_32x32x16_bf16 v[80:95], v[192:195], v[210:213], v[80:95]
	global_load_lds_dwordx4 v[160:161], off
	v_mfma_f32_32x32x16_bf16 v[64:79], v[192:195], v[214:217], v[64:79]
	s_add_u32 m0, s98, 0x14000
	v_mfma_f32_32x32x16_bf16 v[48:63], v[196:199], v[200:203], v[48:63]
	global_load_lds_dwordx4 v[166:167], off
	v_mfma_f32_32x32x16_bf16 v[32:47], v[196:199], v[206:209], v[32:47]
	s_add_u32 m0, s98, 0x16000
	v_mfma_f32_32x32x16_bf16 v[16:31], v[196:199], v[210:213], v[16:31]
	global_load_lds_dwordx4 v[162:163], off
	v_mfma_f32_32x32x16_bf16 v[0:15], v[196:199], v[214:217], v[0:15]
	v_lshl_add_u64 v[164:165], v[164:165], 0, 64
	v_lshl_add_u64 v[160:161], v[160:161], 0, 64
	v_lshl_add_u64 v[166:167], v[166:167], 0, 64
	v_lshl_add_u64 v[162:163], v[162:163], 0, 64
	s_waitcnt lgkmcnt(0)
	v_mfma_f32_32x32x16_bf16 v[112:127], v[128:131], v[136:139], v[112:127]
	v_mfma_f32_32x32x16_bf16 v[96:111], v[128:131], v[140:143], v[96:111]
	ds_read_b128 v[192:195], v253 offset:32768
	ds_read_b128 v[196:199], v253 offset:34816
	v_mfma_f32_32x32x16_bf16 v[80:95], v[128:131], v[144:147], v[80:95]
	ds_read_b128 v[200:203], v255 offset:49152
	ds_read_b128 v[206:209], v255 offset:51200
	v_mfma_f32_32x32x16_bf16 v[64:79], v[128:131], v[148:151], v[64:79]
	ds_read_b128 v[210:213], v255 offset:53248
	ds_read_b128 v[214:217], v255 offset:55296
	v_mfma_f32_32x32x16_bf16 v[48:63], v[132:135], v[136:139], v[48:63]
	v_mfma_f32_32x32x16_bf16 v[32:47], v[132:135], v[140:143], v[32:47]
	v_mfma_f32_32x32x16_bf16 v[16:31], v[132:135], v[144:147], v[16:31]
	v_mfma_f32_32x32x16_bf16 v[0:15], v[132:135], v[148:151], v[0:15]
	v_xor_b32_e32 v253, 0x10000, v253
	v_xor_b32_e32 v255, 0x10000, v255
	s_waitcnt vmcnt(8)
	s_waitcnt lgkmcnt(0)
	s_sub_u32 s99, s99, 1
	s_cmp_lg_u32 s99, 0
	s_cbranch_scc1 .Lmy_gemm_i0_loop
	s_barrier
	ds_read_b128 v[128:131], v154
	ds_read_b128 v[132:135], v154 offset:2048
	ds_read_b128 v[136:139], v254 offset:16384
	ds_read_b128 v[140:143], v254 offset:18432
	ds_read_b128 v[144:147], v254 offset:20480
	ds_read_b128 v[148:151], v254 offset:22528
	s_add_u32 m0, s98, 0x18000
	v_mfma_f32_32x32x16_bf16 v[112:127], v[192:195], v[200:203], v[112:127]
	global_load_lds_dwordx4 v[164:165], off
	v_mfma_f32_32x32x16_bf16 v[96:111], v[192:195], v[206:209], v[96:111]
	s_add_u32 m0, s98, 0x1a000
	v_mfma_f32_32x32x16_bf16 v[80:95], v[192:195], v[210:213], v[80:95]
	global_load_lds_dwordx4 v[160:161], off
	v_mfma_f32_32x32x16_bf16 v[64:79], v[192:195], v[214:217], v[64:79]
	s_add_u32 m0, s98, 0x1c000
	v_mfma_f32_32x32x16_bf16 v[48:63], v[196:199], v[200:203], v[48:63]
	global_load_lds_dwordx4 v[166:167], off
	v_mfma_f32_32x32x16_bf16 v[32:47], v[196:199], v[206:209], v[32:47]
	s_add_u32 m0, s98, 0x1e000
	v_mfma_f32_32x32x16_bf16 v[16:31], v[196:199], v[210:213], v[16:31]
	global_load_lds_dwordx4 v[162:163], off
	v_mfma_f32_32x32x16_bf16 v[0:15], v[196:199], v[214:217], v[0:15]
	v_lshl_add_u64 v[164:165], v[164:165], 0, 64
	v_lshl_add_u64 v[160:161], v[160:161], 0, 64
	v_lshl_add_u64 v[166:167], v[166:167], 0, 64
	v_lshl_add_u64 v[162:163], v[162:163], 0, 64
	s_waitcnt lgkmcnt(0)
	v_mfma_f32_32x32x16_bf16 v[112:127], v[128:131], v[136:139], v[112:127]
	v_mfma_f32_32x32x16_bf16 v[96:111], v[128:131], v[140:143], v[96:111]
	ds_read_b128 v[192:195], v253
	ds_read_b128 v[196:199], v253 offset:2048
	v_mfma_f32_32x32x16_bf16 v[80:95], v[128:131], v[144:147], v[80:95]
	ds_read_b128 v[200:203], v255 offset:16384
	ds_read_b128 v[206:209], v255 offset:18432
	v_mfma_f32_32x32x16_bf16 v[64:79], v[128:131], v[148:151], v[64:79]
	ds_read_b128 v[210:213], v255 offset:20480
	ds_read_b128 v[214:217], v255 offset:22528
	v_mfma_f32_32x32x16_bf16 v[48:63], v[132:135], v[136:139], v[48:63]
	v_mfma_f32_32x32x16_bf16 v[32:47], v[132:135], v[140:143], v[32:47]
	v_mfma_f32_32x32x16_bf16 v[16:31], v[132:135], v[144:147], v[16:31]
	v_mfma_f32_32x32x16_bf16 v[0:15], v[132:135], v[148:151], v[0:15]
	s_waitcnt vmcnt(8)
	s_waitcnt lgkmcnt(0)
	s_barrier
; #define LGKM0_BAR asm volatile("s_waitcnt lgkmcnt(0)\n\ts_barrier" ::: "memory");
; __device__ __forceinline__ void gemm256_tile(const u16* Ab, int lda, const u16* Bb, int ldb, int K, char* smem,
;                                              f32x16 (&acc)[2][4]) {
;     ...
;     for (int s = 0; s < nks; ++s) {
;       const int q = s & 3;
;       G_MMA(afA, bfA)
;       __builtin_amdgcn_sched_barrier(0);
;       LGKM0_BAR
;       G_FRAGS(afB, bfB, q, fo1)
;       __builtin_amdgcn_sched_barrier(0);
;       LGKM0_BAR
;       G_MMA(afB, bfB)
;       __builtin_amdgcn_sched_barrier(0);
;       G_WAIT_BAR(s)
;       if (s + 4 < nks) DMA_STAGE(s + 4)
;       if (s + 1 < nks) G_FRAGS(afA, bfA, (s + 1) & 3, fo0)
;       __builtin_amdgcn_sched_barrier(0);
;       LGKM0_BAR
;     }
;   } else {
;     LGKM0_BAR
;     for (int s = 0; s < nks; ++s) {
;       const int q = s & 3;
;       G_FRAGS(afA, bfA, q, fo0)
;       __builtin_amdgcn_sched_barrier(0);
;       LGKM0_BAR
;       G_MMA(afA, bfA)
;       __builtin_amdgcn_sched_barrier(0);
;       LGKM0_BAR
;       G_FRAGS(afB, bfB, q, fo1)
;       __builtin_amdgcn_sched_barrier(0);
;       G_WAIT_BAR(s)
;       G_MMA(afB, bfB)
;       __builtin_amdgcn_sched_barrier(0);
;       if (s + 4 < nks) DMA_STAGE(s + 4)
;       __builtin_amdgcn_sched_barrier(0);
;       LGKM0_BAR
;     }
;   }
;     ...
;   __syncthreads();
	ds_read_b128 v[128:131], v154 offset:32768
	ds_read_b128 v[132:135], v154 offset:34816
	ds_read_b128 v[136:139], v254 offset:49152
	ds_read_b128 v[140:143], v254 offset:51200
	ds_read_b128 v[144:147], v254 offset:53248
	ds_read_b128 v[148:151], v254 offset:55296
	v_xor_b32_e32 v154, 0x10000, v154
	v_xor_b32_e32 v254, 0x10000, v254
	v_mfma_f32_32x32x16_bf16 v[112:127], v[192:195], v[200:203], v[112:127]
	v_mfma_f32_32x32x16_bf16 v[96:111], v[192:195], v[206:209], v[96:111]
	v_mfma_f32_32x32x16_bf16 v[80:95], v[192:195], v[210:213], v[80:95]
	v_mfma_f32_32x32x16_bf16 v[64:79], v[192:195], v[214:217], v[64:79]
	v_mfma_f32_32x32x16_bf16 v[48:63], v[196:199], v[200:203], v[48:63]
	v_mfma_f32_32x32x16_bf16 v[32:47], v[196:199], v[206:209], v[32:47]
	v_mfma_f32_32x32x16_bf16 v[16:31], v[196:199], v[210:213], v[16:31]
	v_mfma_f32_32x32x16_bf16 v[0:15], v[196:199], v[214:217], v[0:15]
	s_waitcnt lgkmcnt(0)
	v_mfma_f32_32x32x16_bf16 v[112:127], v[128:131], v[136:139], v[112:127]
	v_mfma_f32_32x32x16_bf16 v[96:111], v[128:131], v[140:143], v[96:111]
	ds_read_b128 v[192:195], v253 offset:32768
	ds_read_b128 v[196:199], v253 offset:34816
	v_mfma_f32_32x32x16_bf16 v[80:95], v[128:131], v[144:147], v[80:95]
	ds_read_b128 v[200:203], v255 offset:49152
	ds_read_b128 v[206:209], v255 offset:51200
	v_mfma_f32_32x32x16_bf16 v[64:79], v[128:131], v[148:151], v[64:79]
	ds_read_b128 v[210:213], v255 offset:53248
	ds_read_b128 v[214:217], v255 offset:55296
	v_mfma_f32_32x32x16_bf16 v[48:63], v[132:135], v[136:139], v[48:63]
	v_mfma_f32_32x32x16_bf16 v[32:47], v[132:135], v[140:143], v[32:47]
	v_mfma_f32_32x32x16_bf16 v[16:31], v[132:135], v[144:147], v[16:31]
	v_mfma_f32_32x32x16_bf16 v[0:15], v[132:135], v[148:151], v[0:15]
	v_xor_b32_e32 v253, 0x10000, v253
	v_xor_b32_e32 v255, 0x10000, v255
	s_waitcnt vmcnt(4)
	s_waitcnt lgkmcnt(0)
	s_barrier
	ds_read_b128 v[128:131], v154
	ds_read_b128 v[132:135], v154 offset:2048
	ds_read_b128 v[136:139], v254 offset:16384
	ds_read_b128 v[140:143], v254 offset:18432
	ds_read_b128 v[144:147], v254 offset:20480
	ds_read_b128 v[148:151], v254 offset:22528
	v_mfma_f32_32x32x16_bf16 v[112:127], v[192:195], v[200:203], v[112:127]
	v_mfma_f32_32x32x16_bf16 v[96:111], v[192:195], v[206:209], v[96:111]
	v_mfma_f32_32x32x16_bf16 v[80:95], v[192:195], v[210:213], v[80:95]
	v_mfma_f32_32x32x16_bf16 v[64:79], v[192:195], v[214:217], v[64:79]
	v_mfma_f32_32x32x16_bf16 v[48:63], v[196:199], v[200:203], v[48:63]
	v_mfma_f32_32x32x16_bf16 v[32:47], v[196:199], v[206:209], v[32:47]
	v_mfma_f32_32x32x16_bf16 v[16:31], v[196:199], v[210:213], v[16:31]
	v_mfma_f32_32x32x16_bf16 v[0:15], v[196:199], v[214:217], v[0:15]
	s_waitcnt lgkmcnt(0)
	v_mfma_f32_32x32x16_bf16 v[112:127], v[128:131], v[136:139], v[112:127]
	v_mfma_f32_32x32x16_bf16 v[96:111], v[128:131], v[140:143], v[96:111]
	ds_read_b128 v[192:195], v253
	ds_read_b128 v[196:199], v253 offset:2048
	v_mfma_f32_32x32x16_bf16 v[80:95], v[128:131], v[144:147], v[80:95]
	ds_read_b128 v[200:203], v255 offset:16384
	ds_read_b128 v[206:209], v255 offset:18432
	v_mfma_f32_32x32x16_bf16 v[64:79], v[128:131], v[148:151], v[64:79]
	ds_read_b128 v[210:213], v255 offset:20480
	ds_read_b128 v[214:217], v255 offset:22528
	v_mfma_f32_32x32x16_bf16 v[48:63], v[132:135], v[136:139], v[48:63]
	v_mfma_f32_32x32x16_bf16 v[32:47], v[132:135], v[140:143], v[32:47]
	v_mfma_f32_32x32x16_bf16 v[16:31], v[132:135], v[144:147], v[16:31]
	v_mfma_f32_32x32x16_bf16 v[0:15], v[132:135], v[148:151], v[0:15]
	s_waitcnt vmcnt(0)
	s_waitcnt lgkmcnt(0)
	s_barrier
	ds_read_b128 v[128:131], v154 offset:32768
	ds_read_b128 v[132:135], v154 offset:34816
	ds_read_b128 v[136:139], v254 offset:49152
	ds_read_b128 v[140:143], v254 offset:51200
	ds_read_b128 v[144:147], v254 offset:53248
	ds_read_b128 v[148:151], v254 offset:55296
	v_xor_b32_e32 v154, 0x10000, v154
	v_xor_b32_e32 v254, 0x10000, v254
	v_mfma_f32_32x32x16_bf16 v[112:127], v[192:195], v[200:203], v[112:127]
	v_mfma_f32_32x32x16_bf16 v[96:111], v[192:195], v[206:209], v[96:111]
	v_mfma_f32_32x32x16_bf16 v[80:95], v[192:195], v[210:213], v[80:95]
	v_mfma_f32_32x32x16_bf16 v[64:79], v[192:195], v[214:217], v[64:79]
	v_mfma_f32_32x32x16_bf16 v[48:63], v[196:199], v[200:203], v[48:63]
	v_mfma_f32_32x32x16_bf16 v[32:47], v[196:199], v[206:209], v[32:47]
	v_mfma_f32_32x32x16_bf16 v[16:31], v[196:199], v[210:213], v[16:31]
	v_mfma_f32_32x32x16_bf16 v[0:15], v[196:199], v[214:217], v[0:15]
	s_waitcnt lgkmcnt(0)
	v_mfma_f32_32x32x16_bf16 v[112:127], v[128:131], v[136:139], v[112:127]
	v_mfma_f32_32x32x16_bf16 v[96:111], v[128:131], v[140:143], v[96:111]
	ds_read_b128 v[192:195], v253 offset:32768
	ds_read_b128 v[196:199], v253 offset:34816
	v_mfma_f32_32x32x16_bf16 v[80:95], v[128:131], v[144:147], v[80:95]
	ds_read_b128 v[200:203], v255 offset:49152
	ds_read_b128 v[206:209], v255 offset:51200
	v_mfma_f32_32x32x16_bf16 v[64:79], v[128:131], v[148:151], v[64:79]
	ds_read_b128 v[210:213], v255 offset:53248
	ds_read_b128 v[214:217], v255 offset:55296
	v_mfma_f32_32x32x16_bf16 v[48:63], v[132:135], v[136:139], v[48:63]
	v_mfma_f32_32x32x16_bf16 v[32:47], v[132:135], v[140:143], v[32:47]
	v_mfma_f32_32x32x16_bf16 v[16:31], v[132:135], v[144:147], v[16:31]
	v_mfma_f32_32x32x16_bf16 v[0:15], v[132:135], v[148:151], v[0:15]
	v_xor_b32_e32 v253, 0x10000, v253
	v_xor_b32_e32 v255, 0x10000, v255
	s_waitcnt lgkmcnt(0)
	v_mfma_f32_32x32x16_bf16 v[112:127], v[192:195], v[200:203], v[112:127]
	v_mfma_f32_32x32x16_bf16 v[96:111], v[192:195], v[206:209], v[96:111]
	v_mfma_f32_32x32x16_bf16 v[80:95], v[192:195], v[210:213], v[80:95]
	v_mfma_f32_32x32x16_bf16 v[64:79], v[192:195], v[214:217], v[64:79]
	v_mfma_f32_32x32x16_bf16 v[48:63], v[196:199], v[200:203], v[48:63]
	v_mfma_f32_32x32x16_bf16 v[32:47], v[196:199], v[206:209], v[32:47]
	v_mfma_f32_32x32x16_bf16 v[16:31], v[196:199], v[210:213], v[16:31]
	v_mfma_f32_32x32x16_bf16 v[0:15], v[196:199], v[214:217], v[0:15]
	s_nop 15
	s_branch .LBB0_180

; #define LGKM0_BAR asm volatile("s_waitcnt lgkmcnt(0)\n\ts_barrier" ::: "memory");
; __device__ __forceinline__ void gemm256_tile(const u16* Ab, int lda, const u16* Bb, int ldb, int K, char* smem,
;                                              f32x16 (&acc)[2][4]) {
;     ...
;     for (int s = 0; s < nks; ++s) {
;       const int q = s & 3;
;       G_MMA(afA, bfA)
;       __builtin_amdgcn_sched_barrier(0);
;       LGKM0_BAR
;       G_FRAGS(afB, bfB, q, fo1)
;       __builtin_amdgcn_sched_barrier(0);
;       LGKM0_BAR
;       G_MMA(afB, bfB)
;       __builtin_amdgcn_sched_barrier(0);
;       G_WAIT_BAR(s)
;       if (s + 4 < nks) DMA_STAGE(s + 4)
;       if (s + 1 < nks) G_FRAGS(afA, bfA, (s + 1) & 3, fo0)
;       __builtin_amdgcn_sched_barrier(0);
;       LGKM0_BAR
;     }
.Lmy_gemm_i1_loop:
	s_barrier
	ds_read_b128 v[128:131], v154
	ds_read_b128 v[132:135], v154 offset:2048
	ds_read_b128 v[136:139], v254 offset:16384
	ds_read_b128 v[140:143], v254 offset:18432
	ds_read_b128 v[144:147], v254 offset:20480
	ds_read_b128 v[148:151], v254 offset:22528
	s_add_u32 m0, s98, 0x18000
	v_mfma_f32_32x32x16_bf16 v[112:127], v[192:195], v[200:203], v[112:127]
	global_load_lds_dwordx4 v[164:165], off
	v_mfma_f32_32x32x16_bf16 v[96:111], v[192:195], v[206:209], v[96:111]
	s_add_u32 m0, s98, 0x1a000
	v_mfma_f32_32x32x16_bf16 v[80:95], v[192:195], v[210:213], v[80:95]
	global_load_lds_dwordx4 v[160:161], off
	v_mfma_f32_32x32x16_bf16 v[64:79], v[192:195], v[214:217], v[64:79]
	s_add_u32 m0, s98, 0x1c000
	v_mfma_f32_32x32x16_bf16 v[48:63], v[196:199], v[200:203], v[48:63]
	global_load_lds_dwordx4 v[166:167], off
	v_mfma_f32_32x32x16_bf16 v[32:47], v[196:199], v[206:209], v[32:47]
	s_add_u32 m0, s98, 0x1e000
	v_mfma_f32_32x32x16_bf16 v[16:31], v[196:199], v[210:213], v[16:31]
	global_load_lds_dwordx4 v[162:163], off
	v_mfma_f32_32x32x16_bf16 v[0:15], v[196:199], v[214:217], v[0:15]
	v_lshl_add_u64 v[164:165], v[164:165], 0, 64
	v_lshl_add_u64 v[160:161], v[160:161], 0, 64
	v_lshl_add_u64 v[166:167], v[166:167], 0, 64
	v_lshl_add_u64 v[162:163], v[162:163], 0, 64
	s_waitcnt lgkmcnt(0)
	v_mfma_f32_32x32x16_bf16 v[112:127], v[128:131], v[136:139], v[112:127]
	v_mfma_f32_32x32x16_bf16 v[96:111], v[128:131], v[140:143], v[96:111]
	ds_read_b128 v[192:195], v253
	ds_read_b128 v[196:199], v253 offset:2048
	v_mfma_f32_32x32x16_bf16 v[80:95], v[128:131], v[144:147], v[80:95]
	ds_read_b128 v[200:203], v255 offset:16384
	ds_read_b128 v[206:209], v255 offset:18432
	v_mfma_f32_32x32x16_bf16 v[64:79], v[128:131], v[148:151], v[64:79]
	ds_read_b128 v[210:213], v255 offset:20480
	ds_read_b128 v[214:217], v255 offset:22528
	v_mfma_f32_32x32x16_bf16 v[48:63], v[132:135], v[136:139], v[48:63]
	v_mfma_f32_32x32x16_bf16 v[32:47], v[132:135], v[140:143], v[32:47]
	v_mfma_f32_32x32x16_bf16 v[16:31], v[132:135], v[144:147], v[16:31]
	v_mfma_f32_32x32x16_bf16 v[0:15], v[132:135], v[148:151], v[0:15]
	s_waitcnt vmcnt(8)
	s_waitcnt lgkmcnt(0)
	s_barrier
	ds_read_b128 v[128:131], v154 offset:32768
	ds_read_b128 v[132:135], v154 offset:34816
	ds_read_b128 v[136:139], v254 offset:49152
	ds_read_b128 v[140:143], v254 offset:51200
	ds_read_b128 v[144:147], v254 offset:53248
	ds_read_b128 v[148:151], v254 offset:55296
	v_xor_b32_e32 v154, 0x10000, v154
	v_xor_b32_e32 v254, 0x10000, v254
	s_add_u32 m0, s98, 0x0
	v_mfma_f32_32x32x16_bf16 v[112:127], v[192:195], v[200:203], v[112:127]
	global_load_lds_dwordx4 v[164:165], off
	v_mfma_f32_32x32x16_bf16 v[96:111], v[192:195], v[206:209], v[96:111]
	s_add_u32 m0, s98, 0x2000
	v_mfma_f32_32x32x16_bf16 v[80:95], v[192:195], v[210:213], v[80:95]
	global_load_lds_dwordx4 v[160:161], off
	v_mfma_f32_32x32x16_bf16 v[64:79], v[192:195], v[214:217], v[64:79]
	s_add_u32 m0, s98, 0x4000
	v_mfma_f32_32x32x16_bf16 v[48:63], v[196:199], v[200:203], v[48:63]
	global_load_lds_dwordx4 v[166:167], off
	v_mfma_f32_32x32x16_bf16 v[32:47], v[196:199], v[206:209], v[32:47]
	s_add_u32 m0, s98, 0x6000
	v_mfma_f32_32x32x16_bf16 v[16:31], v[196:199], v[210:213], v[16:31]
	global_load_lds_dwordx4 v[162:163], off
	v_mfma_f32_32x32x16_bf16 v[0:15], v[196:199], v[214:217], v[0:15]
	v_lshl_add_u64 v[164:165], v[164:165], 0, 64
	v_lshl_add_u64 v[160:161], v[160:161], 0, 64
	v_lshl_add_u64 v[166:167], v[166:167], 0, 64
	v_lshl_add_u64 v[162:163], v[162:163], 0, 64
	s_waitcnt lgkmcnt(0)
	v_mfma_f32_32x32x16_bf16 v[112:127], v[128:131], v[136:139], v[112:127]
	v_mfma_f32_32x32x16_bf16 v[96:111], v[128:131], v[140:143], v[96:111]
	ds_read_b128 v[192:195], v253 offset:32768
	ds_read_b128 v[196:199], v253 offset:34816
	v_mfma_f32_32x32x16_bf16 v[80:95], v[128:131], v[144:147], v[80:95]
	ds_read_b128 v[200:203], v255 offset:49152
	ds_read_b128 v[206:209], v255 offset:51200
	v_mfma_f32_32x32x16_bf16 v[64:79], v[128:131], v[148:151], v[64:79]
	ds_read_b128 v[210:213], v255 offset:53248
	ds_read_b128 v[214:217], v255 offset:55296
	v_mfma_f32_32x32x16_bf16 v[48:63], v[132:135], v[136:139], v[48:63]
	v_mfma_f32_32x32x16_bf16 v[32:47], v[132:135], v[140:143], v[32:47]
	v_mfma_f32_32x32x16_bf16 v[16:31], v[132:135], v[144:147], v[16:31]
	v_mfma_f32_32x32x16_bf16 v[0:15], v[132:135], v[148:151], v[0:15]
	v_xor_b32_e32 v253, 0x10000, v253
	v_xor_b32_e32 v255, 0x10000, v255
	s_waitcnt vmcnt(8)
	s_waitcnt lgkmcnt(0)
	s_barrier
	ds_read_b128 v[128:131], v154
	ds_read_b128 v[132:135], v154 offset:2048
	ds_read_b128 v[136:139], v254 offset:16384
	ds_read_b128 v[140:143], v254 offset:18432
	ds_read_b128 v[144:147], v254 offset:20480
	ds_read_b128 v[148:151], v254 offset:22528
	s_add_u32 m0, s98, 0x8000
	v_mfma_f32_32x32x16_bf16 v[112:127], v[192:195], v[200:203], v[112:127]
	global_load_lds_dwordx4 v[164:165], off
	v_mfma_f32_32x32x16_bf16 v[96:111], v[192:195], v[206:209], v[96:111]
	s_add_u32 m0, s98, 0xa000
	v_mfma_f32_32x32x16_bf16 v[80:95], v[192:195], v[210:213], v[80:95]
	global_load_lds_dwordx4 v[160:161], off
	v_mfma_f32_32x32x16_bf16 v[64:79], v[192:195], v[214:217], v[64:79]
	s_add_u32 m0, s98, 0xc000
	v_mfma_f32_32x32x16_bf16 v[48:63], v[196:199], v[200:203], v[48:63]
	global_load_lds_dwordx4 v[166:167], off
	v_mfma_f32_32x32x16_bf16 v[32:47], v[196:199], v[206:209], v[32:47]
	s_add_u32 m0, s98, 0xe000
	v_mfma_f32_32x32x16_bf16 v[16:31], v[196:199], v[210:213], v[16:31]
	global_load_lds_dwordx4 v[162:163], off
	v_mfma_f32_32x32x16_bf16 v[0:15], v[196:199], v[214:217], v[0:15]
	v_lshl_add_u64 v[164:165], v[164:165], 0, 64
	v_lshl_add_u64 v[160:161], v[160:161], 0, 64
	v_lshl_add_u64 v[166:167], v[166:167], 0, 64
	v_lshl_add_u64 v[162:163], v[162:163], 0, 64
	s_waitcnt lgkmcnt(0)
	v_mfma_f32_32x32x16_bf16 v[112:127], v[128:131], v[136:139], v[112:127]
	v_mfma_f32_32x32x16_bf16 v[96:111], v[128:131], v[140:143], v[96:111]
	ds_read_b128 v[192:195], v253
	ds_read_b128 v[196:199], v253 offset:2048
	v_mfma_f32_32x32x16_bf16 v[80:95], v[128:131], v[144:147], v[80:95]
	ds_read_b128 v[200:203], v255 offset:16384
	ds_read_b128 v[206:209], v255 offset:18432
	v_mfma_f32_32x32x16_bf16 v[64:79], v[128:131], v[148:151], v[64:79]
	ds_read_b128 v[210:213], v255 offset:20480
	ds_read_b128 v[214:217], v255 offset:22528
	v_mfma_f32_32x32x16_bf16 v[48:63], v[132:135], v[136:139], v[48:63]
	v_mfma_f32_32x32x16_bf16 v[32:47], v[132:135], v[140:143], v[32:47]
	v_mfma_f32_32x32x16_bf16 v[16:31], v[132:135], v[144:147], v[16:31]
	v_mfma_f32_32x32x16_bf16 v[0:15], v[132:135], v[148:151], v[0:15]
	s_waitcnt vmcnt(8)
	s_waitcnt lgkmcnt(0)
	s_barrier
; #define LGKM0_BAR asm volatile("s_waitcnt lgkmcnt(0)\n\ts_barrier" ::: "memory");
; __device__ __forceinline__ void gemm256_tile(const u16* Ab, int lda, const u16* Bb, int ldb, int K, char* smem,
;                                              f32x16 (&acc)[2][4]) {
;     ...
;     for (int s = 0; s < nks; ++s) {
;       const int q = s & 3;
;       G_MMA(afA, bfA)
;       __builtin_amdgcn_sched_barrier(0);
;       LGKM0_BAR
;       G_FRAGS(afB, bfB, q, fo1)
;       __builtin_amdgcn_sched_barrier(0);
;       LGKM0_BAR
;       G_MMA(afB, bfB)
;       __builtin_amdgcn_sched_barrier(0);
;       G_WAIT_BAR(s)
;       if (s + 4 < nks) DMA_STAGE(s + 4)
;       if (s + 1 < nks) G_FRAGS(afA, bfA, (s + 1) & 3, fo0)
;       __builtin_amdgcn_sched_barrier(0);
;       LGKM0_BAR
;     }
	ds_read_b128 v[128:131], v154 offset:32768
	ds_read_b128 v[132:135], v154 offset:34816
	ds_read_b128 v[136:139], v254 offset:49152
	ds_read_b128 v[140:143], v254 offset:51200
	ds_read_b128 v[144:147], v254 offset:53248
	ds_read_b128 v[148:151], v254 offset:55296
	v_xor_b32_e32 v154, 0x10000, v154
	v_xor_b32_e32 v254, 0x10000, v254
	s_add_u32 m0, s98, 0x10000
	v_mfma_f32_32x32x16_bf16 v[112:127], v[192:195], v[200:203], v[112:127]
	global_load_lds_dwordx4 v[164:165], off
	v_mfma_f32_32x32x16_bf16 v[96:111], v[192:195], v[206:209], v[96:111]
	s_add_u32 m0, s98, 0x12000
	v_mfma_f32_32x32x16_bf16 v[80:95], v[192:195], v[210:213], v[80:95]
	global_load_lds_dwordx4 v[160:161], off
	v_mfma_f32_32x32x16_bf16 v[64:79], v[192:195], v[214:217], v[64:79]
	s_add_u32 m0, s98, 0x14000
	v_mfma_f32_32x32x16_bf16 v[48:63], v[196:199], v[200:203], v[48:63]
	global_load_lds_dwordx4 v[166:167], off
	v_mfma_f32_32x32x16_bf16 v[32:47], v[196:199], v[206:209], v[32:47]
	s_add_u32 m0, s98, 0x16000
	v_mfma_f32_32x32x16_bf16 v[16:31], v[196:199], v[210:213], v[16:31]
	global_load_lds_dwordx4 v[162:163], off
	v_mfma_f32_32x32x16_bf16 v[0:15], v[196:199], v[214:217], v[0:15]
	v_lshl_add_u64 v[164:165], v[164:165], 0, 64
	v_lshl_add_u64 v[160:161], v[160:161], 0, 64
	v_lshl_add_u64 v[166:167], v[166:167], 0, 64
	v_lshl_add_u64 v[162:163], v[162:163], 0, 64
	s_waitcnt lgkmcnt(0)
	v_mfma_f32_32x32x16_bf16 v[112:127], v[128:131], v[136:139], v[112:127]
	v_mfma_f32_32x32x16_bf16 v[96:111], v[128:131], v[140:143], v[96:111]
	ds_read_b128 v[192:195], v253 offset:32768
	ds_read_b128 v[196:199], v253 offset:34816
	v_mfma_f32_32x32x16_bf16 v[80:95], v[128:131], v[144:147], v[80:95]
	ds_read_b128 v[200:203], v255 offset:49152
	ds_read_b128 v[206:209], v255 offset:51200
	v_mfma_f32_32x32x16_bf16 v[64:79], v[128:131], v[148:151], v[64:79]
	ds_read_b128 v[210:213], v255 offset:53248
	ds_read_b128 v[214:217], v255 offset:55296
	v_mfma_f32_32x32x16_bf16 v[48:63], v[132:135], v[136:139], v[48:63]
	v_mfma_f32_32x32x16_bf16 v[32:47], v[132:135], v[140:143], v[32:47]
	v_mfma_f32_32x32x16_bf16 v[16:31], v[132:135], v[144:147], v[16:31]
	v_mfma_f32_32x32x16_bf16 v[0:15], v[132:135], v[148:151], v[0:15]
	v_xor_b32_e32 v253, 0x10000, v253
	v_xor_b32_e32 v255, 0x10000, v255
	s_waitcnt vmcnt(8)
	s_waitcnt lgkmcnt(0)
	s_sub_u32 s99, s99, 1
	s_cmp_lg_u32 s99, 0
	s_cbranch_scc1 .Lmy_gemm_i1_loop
	s_barrier
	ds_read_b128 v[128:131], v154
	ds_read_b128 v[132:135], v154 offset:2048
	ds_read_b128 v[136:139], v254 offset:16384
	ds_read_b128 v[140:143], v254 offset:18432
	ds_read_b128 v[144:147], v254 offset:20480
	ds_read_b128 v[148:151], v254 offset:22528
	s_add_u32 m0, s98, 0x18000
	v_mfma_f32_32x32x16_bf16 v[112:127], v[192:195], v[200:203], v[112:127]
	global_load_lds_dwordx4 v[164:165], off
	v_mfma_f32_32x32x16_bf16 v[96:111], v[192:195], v[206:209], v[96:111]
	s_add_u32 m0, s98, 0x1a000
	v_mfma_f32_32x32x16_bf16 v[80:95], v[192:195], v[210:213], v[80:95]
	global_load_lds_dwordx4 v[160:161], off
	v_mfma_f32_32x32x16_bf16 v[64:79], v[192:195], v[214:217], v[64:79]
	s_add_u32 m0, s98, 0x1c000
	v_mfma_f32_32x32x16_bf16 v[48:63], v[196:199], v[200:203], v[48:63]
	global_load_lds_dwordx4 v[166:167], off
	v_mfma_f32_32x32x16_bf16 v[32:47], v[196:199], v[206:209], v[32:47]
	s_add_u32 m0, s98, 0x1e000
	v_mfma_f32_32x32x16_bf16 v[16:31], v[196:199], v[210:213], v[16:31]
	global_load_lds_dwordx4 v[162:163], off
	v_mfma_f32_32x32x16_bf16 v[0:15], v[196:199], v[214:217], v[0:15]
	v_lshl_add_u64 v[164:165], v[164:165], 0, 64
	v_lshl_add_u64 v[160:161], v[160:161], 0, 64
	v_lshl_add_u64 v[166:167], v[166:167], 0, 64
	v_lshl_add_u64 v[162:163], v[162:163], 0, 64
	s_waitcnt lgkmcnt(0)
	v_mfma_f32_32x32x16_bf16 v[112:127], v[128:131], v[136:139], v[112:127]
	v_mfma_f32_32x32x16_bf16 v[96:111], v[128:131], v[140:143], v[96:111]
	ds_read_b128 v[192:195], v253
	ds_read_b128 v[196:199], v253 offset:2048
	v_mfma_f32_32x32x16_bf16 v[80:95], v[128:131], v[144:147], v[80:95]
	ds_read_b128 v[200:203], v255 offset:16384
	ds_read_b128 v[206:209], v255 offset:18432
	v_mfma_f32_32x32x16_bf16 v[64:79], v[128:131], v[148:151], v[64:79]
	ds_read_b128 v[210:213], v255 offset:20480
	ds_read_b128 v[214:217], v255 offset:22528
	v_mfma_f32_32x32x16_bf16 v[48:63], v[132:135], v[136:139], v[48:63]
	v_mfma_f32_32x32x16_bf16 v[32:47], v[132:135], v[140:143], v[32:47]
	v_mfma_f32_32x32x16_bf16 v[16:31], v[132:135], v[144:147], v[16:31]
	v_mfma_f32_32x32x16_bf16 v[0:15], v[132:135], v[148:151], v[0:15]
	s_waitcnt vmcnt(8)
	s_waitcnt lgkmcnt(0)
	s_barrier
; #define LGKM0_BAR asm volatile("s_waitcnt lgkmcnt(0)\n\ts_barrier" ::: "memory");
; __device__ __forceinline__ void gemm256_tile(const u16* Ab, int lda, const u16* Bb, int ldb, int K, char* smem,
;                                              f32x16 (&acc)[2][4]) {
;     ...
;     for (int s = 0; s < nks; ++s) {
;       const int q = s & 3;
;       G_MMA(afA, bfA)
;       __builtin_amdgcn_sched_barrier(0);
;       LGKM0_BAR
;       G_FRAGS(afB, bfB, q, fo1)
;       __builtin_amdgcn_sched_barrier(0);
;       LGKM0_BAR
;       G_MMA(afB, bfB)
;       __builtin_amdgcn_sched_barrier(0);
;       G_WAIT_BAR(s)
;       if (s + 4 < nks) DMA_STAGE(s + 4)
;       if (s + 1 < nks) G_FRAGS(afA, bfA, (s + 1) & 3, fo0)
;       __builtin_amdgcn_sched_barrier(0);
;       LGKM0_BAR
;     }
;   } else {
;     LGKM0_BAR
;     for (int s = 0; s < nks; ++s) {
;       const int q = s & 3;
;       G_FRAGS(afA, bfA, q, fo0)
;       __builtin_amdgcn_sched_barrier(0);
;       LGKM0_BAR
;       G_MMA(afA, bfA)
;       __builtin_amdgcn_sched_barrier(0);
;       LGKM0_BAR
;       G_FRAGS(afB, bfB, q, fo1)
;       __builtin_amdgcn_sched_barrier(0);
;       G_WAIT_BAR(s)
;       G_MMA(afB, bfB)
;       __builtin_amdgcn_sched_barrier(0);
;       if (s + 4 < nks) DMA_STAGE(s + 4)
;       __builtin_amdgcn_sched_barrier(0);
;       LGKM0_BAR
;     }
;   }
;     ...
;   __syncthreads();
	ds_read_b128 v[128:131], v154 offset:32768
	ds_read_b128 v[132:135], v154 offset:34816
	ds_read_b128 v[136:139], v254 offset:49152
	ds_read_b128 v[140:143], v254 offset:51200
	ds_read_b128 v[144:147], v254 offset:53248
	ds_read_b128 v[148:151], v254 offset:55296
	v_xor_b32_e32 v154, 0x10000, v154
	v_xor_b32_e32 v254, 0x10000, v254
	v_mfma_f32_32x32x16_bf16 v[112:127], v[192:195], v[200:203], v[112:127]
	v_mfma_f32_32x32x16_bf16 v[96:111], v[192:195], v[206:209], v[96:111]
	v_mfma_f32_32x32x16_bf16 v[80:95], v[192:195], v[210:213], v[80:95]
	v_mfma_f32_32x32x16_bf16 v[64:79], v[192:195], v[214:217], v[64:79]
	v_mfma_f32_32x32x16_bf16 v[48:63], v[196:199], v[200:203], v[48:63]
	v_mfma_f32_32x32x16_bf16 v[32:47], v[196:199], v[206:209], v[32:47]
	v_mfma_f32_32x32x16_bf16 v[16:31], v[196:199], v[210:213], v[16:31]
	v_mfma_f32_32x32x16_bf16 v[0:15], v[196:199], v[214:217], v[0:15]
	s_waitcnt lgkmcnt(0)
	v_mfma_f32_32x32x16_bf16 v[112:127], v[128:131], v[136:139], v[112:127]
	v_mfma_f32_32x32x16_bf16 v[96:111], v[128:131], v[140:143], v[96:111]
	ds_read_b128 v[192:195], v253 offset:32768
	ds_read_b128 v[196:199], v253 offset:34816
	v_mfma_f32_32x32x16_bf16 v[80:95], v[128:131], v[144:147], v[80:95]
	ds_read_b128 v[200:203], v255 offset:49152
	ds_read_b128 v[206:209], v255 offset:51200
	v_mfma_f32_32x32x16_bf16 v[64:79], v[128:131], v[148:151], v[64:79]
	ds_read_b128 v[210:213], v255 offset:53248
	ds_read_b128 v[214:217], v255 offset:55296
	v_mfma_f32_32x32x16_bf16 v[48:63], v[132:135], v[136:139], v[48:63]
	v_mfma_f32_32x32x16_bf16 v[32:47], v[132:135], v[140:143], v[32:47]
	v_mfma_f32_32x32x16_bf16 v[16:31], v[132:135], v[144:147], v[16:31]
	v_mfma_f32_32x32x16_bf16 v[0:15], v[132:135], v[148:151], v[0:15]
	v_xor_b32_e32 v253, 0x10000, v253
	v_xor_b32_e32 v255, 0x10000, v255
	s_waitcnt vmcnt(4)
	s_waitcnt lgkmcnt(0)
	s_barrier
	ds_read_b128 v[128:131], v154
	ds_read_b128 v[132:135], v154 offset:2048
	ds_read_b128 v[136:139], v254 offset:16384
	ds_read_b128 v[140:143], v254 offset:18432
	ds_read_b128 v[144:147], v254 offset:20480
	ds_read_b128 v[148:151], v254 offset:22528
	v_mfma_f32_32x32x16_bf16 v[112:127], v[192:195], v[200:203], v[112:127]
	v_mfma_f32_32x32x16_bf16 v[96:111], v[192:195], v[206:209], v[96:111]
	v_mfma_f32_32x32x16_bf16 v[80:95], v[192:195], v[210:213], v[80:95]
	v_mfma_f32_32x32x16_bf16 v[64:79], v[192:195], v[214:217], v[64:79]
	v_mfma_f32_32x32x16_bf16 v[48:63], v[196:199], v[200:203], v[48:63]
	v_mfma_f32_32x32x16_bf16 v[32:47], v[196:199], v[206:209], v[32:47]
	v_mfma_f32_32x32x16_bf16 v[16:31], v[196:199], v[210:213], v[16:31]
	v_mfma_f32_32x32x16_bf16 v[0:15], v[196:199], v[214:217], v[0:15]
	s_waitcnt lgkmcnt(0)
	v_mfma_f32_32x32x16_bf16 v[112:127], v[128:131], v[136:139], v[112:127]
	v_mfma_f32_32x32x16_bf16 v[96:111], v[128:131], v[140:143], v[96:111]
	ds_read_b128 v[192:195], v253
	ds_read_b128 v[196:199], v253 offset:2048
	v_mfma_f32_32x32x16_bf16 v[80:95], v[128:131], v[144:147], v[80:95]
	ds_read_b128 v[200:203], v255 offset:16384
	ds_read_b128 v[206:209], v255 offset:18432
	v_mfma_f32_32x32x16_bf16 v[64:79], v[128:131], v[148:151], v[64:79]
	ds_read_b128 v[210:213], v255 offset:20480
	ds_read_b128 v[214:217], v255 offset:22528
	v_mfma_f32_32x32x16_bf16 v[48:63], v[132:135], v[136:139], v[48:63]
	v_mfma_f32_32x32x16_bf16 v[32:47], v[132:135], v[140:143], v[32:47]
	v_mfma_f32_32x32x16_bf16 v[16:31], v[132:135], v[144:147], v[16:31]
	v_mfma_f32_32x32x16_bf16 v[0:15], v[132:135], v[148:151], v[0:15]
	s_waitcnt vmcnt(0)
	s_waitcnt lgkmcnt(0)
	s_barrier
	ds_read_b128 v[128:131], v154 offset:32768
	ds_read_b128 v[132:135], v154 offset:34816
	ds_read_b128 v[136:139], v254 offset:49152
	ds_read_b128 v[140:143], v254 offset:51200
	ds_read_b128 v[144:147], v254 offset:53248
	ds_read_b128 v[148:151], v254 offset:55296
	v_xor_b32_e32 v154, 0x10000, v154
	v_xor_b32_e32 v254, 0x10000, v254
	v_mfma_f32_32x32x16_bf16 v[112:127], v[192:195], v[200:203], v[112:127]
	v_mfma_f32_32x32x16_bf16 v[96:111], v[192:195], v[206:209], v[96:111]
	v_mfma_f32_32x32x16_bf16 v[80:95], v[192:195], v[210:213], v[80:95]
	v_mfma_f32_32x32x16_bf16 v[64:79], v[192:195], v[214:217], v[64:79]
	v_mfma_f32_32x32x16_bf16 v[48:63], v[196:199], v[200:203], v[48:63]
	v_mfma_f32_32x32x16_bf16 v[32:47], v[196:199], v[206:209], v[32:47]
	v_mfma_f32_32x32x16_bf16 v[16:31], v[196:199], v[210:213], v[16:31]
	v_mfma_f32_32x32x16_bf16 v[0:15], v[196:199], v[214:217], v[0:15]
	s_waitcnt lgkmcnt(0)
	v_mfma_f32_32x32x16_bf16 v[112:127], v[128:131], v[136:139], v[112:127]
	v_mfma_f32_32x32x16_bf16 v[96:111], v[128:131], v[140:143], v[96:111]
	ds_read_b128 v[192:195], v253 offset:32768
	ds_read_b128 v[196:199], v253 offset:34816
	v_mfma_f32_32x32x16_bf16 v[80:95], v[128:131], v[144:147], v[80:95]
	ds_read_b128 v[200:203], v255 offset:49152
	ds_read_b128 v[206:209], v255 offset:51200
	v_mfma_f32_32x32x16_bf16 v[64:79], v[128:131], v[148:151], v[64:79]
	ds_read_b128 v[210:213], v255 offset:53248
	ds_read_b128 v[214:217], v255 offset:55296
	v_mfma_f32_32x32x16_bf16 v[48:63], v[132:135], v[136:139], v[48:63]
	v_mfma_f32_32x32x16_bf16 v[32:47], v[132:135], v[140:143], v[32:47]
	v_mfma_f32_32x32x16_bf16 v[16:31], v[132:135], v[144:147], v[16:31]
	v_mfma_f32_32x32x16_bf16 v[0:15], v[132:135], v[148:151], v[0:15]
	v_xor_b32_e32 v253, 0x10000, v253
	v_xor_b32_e32 v255, 0x10000, v255
	s_waitcnt lgkmcnt(0)
	v_mfma_f32_32x32x16_bf16 v[112:127], v[192:195], v[200:203], v[112:127]
	v_mfma_f32_32x32x16_bf16 v[96:111], v[192:195], v[206:209], v[96:111]
	v_mfma_f32_32x32x16_bf16 v[80:95], v[192:195], v[210:213], v[80:95]
	v_mfma_f32_32x32x16_bf16 v[64:79], v[192:195], v[214:217], v[64:79]
	v_mfma_f32_32x32x16_bf16 v[48:63], v[196:199], v[200:203], v[48:63]
	v_mfma_f32_32x32x16_bf16 v[32:47], v[196:199], v[206:209], v[32:47]
	v_mfma_f32_32x32x16_bf16 v[16:31], v[196:199], v[210:213], v[16:31]
	v_mfma_f32_32x32x16_bf16 v[0:15], v[196:199], v[214:217], v[0:15]
	s_nop 15
	s_lshl_b64 s[8:9], s[8:9], 18
	s_branch .LBB0_818

; #define LGKM0_BAR asm volatile("s_waitcnt lgkmcnt(0)\n\ts_barrier" ::: "memory");
; __device__ __forceinline__ void gemm256_tile(const u16* Ab, int lda, const u16* Bb, int ldb, int K, char* smem,
;                                              f32x16 (&acc)[2][4]) {
;     ...
;   const int xsw = (lane >> 2) & 3, hh = lane >> 5;
;   const unsigned fo0 = (unsigned)((hh ^ xsw) * 16), fo1 = (unsigned)(((2 + hh) ^ xsw) * 16);
;   const unsigned fa = (unsigned)((wm * 64 + (lane & 31)) * 64);
;   const unsigned fb = (unsigned)(16384 + (wn * 128 + (lane & 31)) * 64);
;     ...
;   asm volatile("s_waitcnt vmcnt(0)" ::: "memory");
;   const bool h1 = __builtin_amdgcn_readfirstlane(wid) >= 4;
;     ...
;   DMA_STAGE(0)
;   if (nks > 1) DMA_STAGE(1)
;   if (nks > 2) DMA_STAGE(2)
;   if (nks > 3) DMA_STAGE(3)
;   if (nks > 3)      asm volatile("s_waitcnt vmcnt(12)\n\ts_barrier" ::: "memory");
;   else if (nks > 2) asm volatile("s_waitcnt vmcnt(8)\n\ts_barrier" ::: "memory");
;   else if (nks > 1) asm volatile("s_waitcnt vmcnt(4)\n\ts_barrier" ::: "memory");
;   else              asm volatile("s_waitcnt vmcnt(0)\n\ts_barrier" ::: "memory");
;   bf16x8 afA[2], bfA[4], afB[2], bfB[4];
;   if (!h1) {
;     G_FRAGS(afA, bfA, 0, fo0)
;     LGKM0_BAR
;     for (int s = 0; s < nks; ++s) {
;       const int q = s & 3;
;       G_MMA(afA, bfA)
;       __builtin_amdgcn_sched_barrier(0);
;       LGKM0_BAR
;       G_FRAGS(afB, bfB, q, fo1)
;       __builtin_amdgcn_sched_barrier(0);
;       LGKM0_BAR
;       G_MMA(afB, bfB)
;       __builtin_amdgcn_sched_barrier(0);
;       G_WAIT_BAR(s)
;       if (s + 4 < nks) DMA_STAGE(s + 4)
;       if (s + 1 < nks) G_FRAGS(afA, bfA, (s + 1) & 3, fo0)
;       __builtin_amdgcn_sched_barrier(0);
;       LGKM0_BAR
;     }
.LBB0_1041:
	v_lshrrev_b32_e32 v192, 6, v152
	v_bfe_u32 v193, v152, 2, 2
	v_readfirstlane_b32 s98, v192
	v_bfe_u32 v194, v152, 5, 1
	v_xor_b32_e32 v193, v194, v193
	v_lshlrev_b32_e32 v193, 4, v193
	v_xor_b32_e32 v194, 32, v193
	v_and_b32_e32 v195, 31, v152
	v_lshrrev_b32_e32 v196, 7, v152
	v_lshl_add_u32 v196, v196, 6, v195
	v_lshlrev_b32_e32 v196, 6, v196
	v_bfe_u32 v197, v152, 6, 1
	v_lshl_add_u32 v197, v197, 7, v195
	v_lshlrev_b32_e32 v197, 6, v197
	v_add3_u32 v154, v196, v193, 16
	v_add3_u32 v253, v196, v194, 16
	v_add3_u32 v254, v197, v193, 16
	v_add3_u32 v255, v197, v194, 16
	s_lshl_b32 s98, s98, 10
	s_add_u32 s98, s98, 16
	v_lshl_add_u64 v[164:165], 64, 2, v[164:165]
	v_lshl_add_u64 v[160:161], 64, 2, v[160:161]
	v_lshl_add_u64 v[166:167], 64, 2, v[166:167]
	v_lshl_add_u64 v[162:163], 64, 2, v[162:163]
	s_barrier
	ds_read_b128 v[128:131], v154
	ds_read_b128 v[132:135], v154 offset:2048
	ds_read_b128 v[136:139], v254 offset:16384
	ds_read_b128 v[140:143], v254 offset:18432
	ds_read_b128 v[144:147], v254 offset:20480
	ds_read_b128 v[148:151], v254 offset:22528
	s_waitcnt lgkmcnt(0)
	v_mfma_f32_32x32x16_bf16 v[96:111], v[128:131], v[136:139], 0
	v_mfma_f32_32x32x16_bf16 v[112:127], v[128:131], v[140:143], 0
	ds_read_b128 v[192:195], v253
	ds_read_b128 v[196:199], v253 offset:2048
	v_mfma_f32_32x32x16_bf16 v[64:79], v[128:131], v[144:147], 0
	ds_read_b128 v[200:203], v255 offset:16384
	ds_read_b128 v[206:209], v255 offset:18432
	v_mfma_f32_32x32x16_bf16 v[80:95], v[128:131], v[148:151], 0
	ds_read_b128 v[210:213], v255 offset:20480
	ds_read_b128 v[214:217], v255 offset:22528
	v_mfma_f32_32x32x16_bf16 v[32:47], v[132:135], v[136:139], 0
	v_mfma_f32_32x32x16_bf16 v[48:63], v[132:135], v[140:143], 0
	v_mfma_f32_32x32x16_bf16 v[0:15], v[132:135], v[144:147], 0
	v_mfma_f32_32x32x16_bf16 v[16:31], v[132:135], v[148:151], 0
	s_waitcnt vmcnt(8)
	s_waitcnt lgkmcnt(0)
	s_barrier
	ds_read_b128 v[128:131], v154 offset:32768
	ds_read_b128 v[132:135], v154 offset:34816
	ds_read_b128 v[136:139], v254 offset:49152
	ds_read_b128 v[140:143], v254 offset:51200
	ds_read_b128 v[144:147], v254 offset:53248
	ds_read_b128 v[148:151], v254 offset:55296
	v_xor_b32_e32 v154, 0x10000, v154
	v_xor_b32_e32 v254, 0x10000, v254
	s_add_u32 m0, s98, 0x0
	v_mfma_f32_32x32x16_bf16 v[96:111], v[192:195], v[200:203], v[96:111]
	global_load_lds_dwordx4 v[164:165], off
	v_mfma_f32_32x32x16_bf16 v[112:127], v[192:195], v[206:209], v[112:127]
	s_add_u32 m0, s98, 0x2000
	v_mfma_f32_32x32x16_bf16 v[64:79], v[192:195], v[210:213], v[64:79]
	global_load_lds_dwordx4 v[160:161], off
	v_mfma_f32_32x32x16_bf16 v[80:95], v[192:195], v[214:217], v[80:95]
	s_add_u32 m0, s98, 0x4000
	v_mfma_f32_32x32x16_bf16 v[32:47], v[196:199], v[200:203], v[32:47]
	global_load_lds_dwordx4 v[166:167], off
	v_mfma_f32_32x32x16_bf16 v[48:63], v[196:199], v[206:209], v[48:63]
	s_add_u32 m0, s98, 0x6000
	v_mfma_f32_32x32x16_bf16 v[0:15], v[196:199], v[210:213], v[0:15]
	global_load_lds_dwordx4 v[162:163], off
	v_mfma_f32_32x32x16_bf16 v[16:31], v[196:199], v[214:217], v[16:31]
	v_lshl_add_u64 v[164:165], v[164:165], 0, 64
	v_lshl_add_u64 v[160:161], v[160:161], 0, 64
	v_lshl_add_u64 v[166:167], v[166:167], 0, 64
	v_lshl_add_u64 v[162:163], v[162:163], 0, 64
	s_waitcnt lgkmcnt(0)
	v_mfma_f32_32x32x16_bf16 v[96:111], v[128:131], v[136:139], v[96:111]
	v_mfma_f32_32x32x16_bf16 v[112:127], v[128:131], v[140:143], v[112:127]
	ds_read_b128 v[192:195], v253 offset:32768
	ds_read_b128 v[196:199], v253 offset:34816
	v_mfma_f32_32x32x16_bf16 v[64:79], v[128:131], v[144:147], v[64:79]
	ds_read_b128 v[200:203], v255 offset:49152
	ds_read_b128 v[206:209], v255 offset:51200
	v_mfma_f32_32x32x16_bf16 v[80:95], v[128:131], v[148:151], v[80:95]
	ds_read_b128 v[210:213], v255 offset:53248
	ds_read_b128 v[214:217], v255 offset:55296
	v_mfma_f32_32x32x16_bf16 v[32:47], v[132:135], v[136:139], v[32:47]
	v_mfma_f32_32x32x16_bf16 v[48:63], v[132:135], v[140:143], v[48:63]
	v_mfma_f32_32x32x16_bf16 v[0:15], v[132:135], v[144:147], v[0:15]
	v_mfma_f32_32x32x16_bf16 v[16:31], v[132:135], v[148:151], v[16:31]
	v_xor_b32_e32 v253, 0x10000, v253
	v_xor_b32_e32 v255, 0x10000, v255
	s_waitcnt vmcnt(8)
	s_waitcnt lgkmcnt(0)
	s_barrier
	ds_read_b128 v[128:131], v154
	ds_read_b128 v[132:135], v154 offset:2048
	ds_read_b128 v[136:139], v254 offset:16384
	ds_read_b128 v[140:143], v254 offset:18432
	ds_read_b128 v[144:147], v254 offset:20480
	ds_read_b128 v[148:151], v254 offset:22528
	s_add_u32 m0, s98, 0x8000
	v_mfma_f32_32x32x16_bf16 v[96:111], v[192:195], v[200:203], v[96:111]
	global_load_lds_dwordx4 v[164:165], off
	v_mfma_f32_32x32x16_bf16 v[112:127], v[192:195], v[206:209], v[112:127]
	s_add_u32 m0, s98, 0xa000
	v_mfma_f32_32x32x16_bf16 v[64:79], v[192:195], v[210:213], v[64:79]
	global_load_lds_dwordx4 v[160:161], off
	v_mfma_f32_32x32x16_bf16 v[80:95], v[192:195], v[214:217], v[80:95]
	s_add_u32 m0, s98, 0xc000
	v_mfma_f32_32x32x16_bf16 v[32:47], v[196:199], v[200:203], v[32:47]
	global_load_lds_dwordx4 v[166:167], off
	v_mfma_f32_32x32x16_bf16 v[48:63], v[196:199], v[206:209], v[48:63]
	s_add_u32 m0, s98, 0xe000
	v_mfma_f32_32x32x16_bf16 v[0:15], v[196:199], v[210:213], v[0:15]
	global_load_lds_dwordx4 v[162:163], off
	v_mfma_f32_32x32x16_bf16 v[16:31], v[196:199], v[214:217], v[16:31]
	v_lshl_add_u64 v[164:165], v[164:165], 0, 64
	v_lshl_add_u64 v[160:161], v[160:161], 0, 64
	v_lshl_add_u64 v[166:167], v[166:167], 0, 64
	v_lshl_add_u64 v[162:163], v[162:163], 0, 64
	s_waitcnt lgkmcnt(0)
	v_mfma_f32_32x32x16_bf16 v[96:111], v[128:131], v[136:139], v[96:111]
	v_mfma_f32_32x32x16_bf16 v[112:127], v[128:131], v[140:143], v[112:127]
	ds_read_b128 v[192:195], v253
	ds_read_b128 v[196:199], v253 offset:2048
	v_mfma_f32_32x32x16_bf16 v[64:79], v[128:131], v[144:147], v[64:79]
	ds_read_b128 v[200:203], v255 offset:16384
	ds_read_b128 v[206:209], v255 offset:18432
	v_mfma_f32_32x32x16_bf16 v[80:95], v[128:131], v[148:151], v[80:95]
	ds_read_b128 v[210:213], v255 offset:20480
	ds_read_b128 v[214:217], v255 offset:22528
	v_mfma_f32_32x32x16_bf16 v[32:47], v[132:135], v[136:139], v[32:47]
	v_mfma_f32_32x32x16_bf16 v[48:63], v[132:135], v[140:143], v[48:63]
	v_mfma_f32_32x32x16_bf16 v[0:15], v[132:135], v[144:147], v[0:15]
	v_mfma_f32_32x32x16_bf16 v[16:31], v[132:135], v[148:151], v[16:31]
	s_waitcnt vmcnt(8)
	s_waitcnt lgkmcnt(0)
	s_barrier
; #define LGKM0_BAR asm volatile("s_waitcnt lgkmcnt(0)\n\ts_barrier" ::: "memory");
; __device__ __forceinline__ void gemm256_tile(const u16* Ab, int lda, const u16* Bb, int ldb, int K, char* smem,
;                                              f32x16 (&acc)[2][4]) {
;     ...
;     for (int s = 0; s < nks; ++s) {
;       const int q = s & 3;
;       G_MMA(afA, bfA)
;       __builtin_amdgcn_sched_barrier(0);
;       LGKM0_BAR
;       G_FRAGS(afB, bfB, q, fo1)
;       __builtin_amdgcn_sched_barrier(0);
;       LGKM0_BAR
;       G_MMA(afB, bfB)
;       __builtin_amdgcn_sched_barrier(0);
;       G_WAIT_BAR(s)
;       if (s + 4 < nks) DMA_STAGE(s + 4)
;       if (s + 1 < nks) G_FRAGS(afA, bfA, (s + 1) & 3, fo0)
;       __builtin_amdgcn_sched_barrier(0);
;       LGKM0_BAR
;     }
	ds_read_b128 v[128:131], v154 offset:32768
	ds_read_b128 v[132:135], v154 offset:34816
	ds_read_b128 v[136:139], v254 offset:49152
	ds_read_b128 v[140:143], v254 offset:51200
	ds_read_b128 v[144:147], v254 offset:53248
	ds_read_b128 v[148:151], v254 offset:55296
	v_xor_b32_e32 v154, 0x10000, v154
	v_xor_b32_e32 v254, 0x10000, v254
	s_add_u32 m0, s98, 0x10000
	v_mfma_f32_32x32x16_bf16 v[96:111], v[192:195], v[200:203], v[96:111]
	global_load_lds_dwordx4 v[164:165], off
	v_mfma_f32_32x32x16_bf16 v[112:127], v[192:195], v[206:209], v[112:127]
	s_add_u32 m0, s98, 0x12000
	v_mfma_f32_32x32x16_bf16 v[64:79], v[192:195], v[210:213], v[64:79]
	global_load_lds_dwordx4 v[160:161], off
	v_mfma_f32_32x32x16_bf16 v[80:95], v[192:195], v[214:217], v[80:95]
	s_add_u32 m0, s98, 0x14000
	v_mfma_f32_32x32x16_bf16 v[32:47], v[196:199], v[200:203], v[32:47]
	global_load_lds_dwordx4 v[166:167], off
	v_mfma_f32_32x32x16_bf16 v[48:63], v[196:199], v[206:209], v[48:63]
	s_add_u32 m0, s98, 0x16000
	v_mfma_f32_32x32x16_bf16 v[0:15], v[196:199], v[210:213], v[0:15]
	global_load_lds_dwordx4 v[162:163], off
	v_mfma_f32_32x32x16_bf16 v[16:31], v[196:199], v[214:217], v[16:31]
	v_lshl_add_u64 v[164:165], v[164:165], 0, 64
	v_lshl_add_u64 v[160:161], v[160:161], 0, 64
	v_lshl_add_u64 v[166:167], v[166:167], 0, 64
	v_lshl_add_u64 v[162:163], v[162:163], 0, 64
	s_waitcnt lgkmcnt(0)
	v_mfma_f32_32x32x16_bf16 v[96:111], v[128:131], v[136:139], v[96:111]
	v_mfma_f32_32x32x16_bf16 v[112:127], v[128:131], v[140:143], v[112:127]
	ds_read_b128 v[192:195], v253 offset:32768
	ds_read_b128 v[196:199], v253 offset:34816
	v_mfma_f32_32x32x16_bf16 v[64:79], v[128:131], v[144:147], v[64:79]
	ds_read_b128 v[200:203], v255 offset:49152
	ds_read_b128 v[206:209], v255 offset:51200
	v_mfma_f32_32x32x16_bf16 v[80:95], v[128:131], v[148:151], v[80:95]
	ds_read_b128 v[210:213], v255 offset:53248
	ds_read_b128 v[214:217], v255 offset:55296
	v_mfma_f32_32x32x16_bf16 v[32:47], v[132:135], v[136:139], v[32:47]
	v_mfma_f32_32x32x16_bf16 v[48:63], v[132:135], v[140:143], v[48:63]
	v_mfma_f32_32x32x16_bf16 v[0:15], v[132:135], v[144:147], v[0:15]
	v_mfma_f32_32x32x16_bf16 v[16:31], v[132:135], v[148:151], v[16:31]
	v_xor_b32_e32 v253, 0x10000, v253
	v_xor_b32_e32 v255, 0x10000, v255
	s_waitcnt vmcnt(8)
	s_waitcnt lgkmcnt(0)
	s_mov_b32 s99, 6
.Lmy_gemm_i2_loop:
	s_barrier
	ds_read_b128 v[128:131], v154
	ds_read_b128 v[132:135], v154 offset:2048
	ds_read_b128 v[136:139], v254 offset:16384
	ds_read_b128 v[140:143], v254 offset:18432
	ds_read_b128 v[144:147], v254 offset:20480
	ds_read_b128 v[148:151], v254 offset:22528
	s_add_u32 m0, s98, 0x18000
	v_mfma_f32_32x32x16_bf16 v[96:111], v[192:195], v[200:203], v[96:111]
	global_load_lds_dwordx4 v[164:165], off
	v_mfma_f32_32x32x16_bf16 v[112:127], v[192:195], v[206:209], v[112:127]
	s_add_u32 m0, s98, 0x1a000
	v_mfma_f32_32x32x16_bf16 v[64:79], v[192:195], v[210:213], v[64:79]
	global_load_lds_dwordx4 v[160:161], off
	v_mfma_f32_32x32x16_bf16 v[80:95], v[192:195], v[214:217], v[80:95]
	s_add_u32 m0, s98, 0x1c000
	v_mfma_f32_32x32x16_bf16 v[32:47], v[196:199], v[200:203], v[32:47]
	global_load_lds_dwordx4 v[166:167], off
	v_mfma_f32_32x32x16_bf16 v[48:63], v[196:199], v[206:209], v[48:63]
	s_add_u32 m0, s98, 0x1e000
	v_mfma_f32_32x32x16_bf16 v[0:15], v[196:199], v[210:213], v[0:15]
	global_load_lds_dwordx4 v[162:163], off
	v_mfma_f32_32x32x16_bf16 v[16:31], v[196:199], v[214:217], v[16:31]
	v_lshl_add_u64 v[164:165], v[164:165], 0, 64
	v_lshl_add_u64 v[160:161], v[160:161], 0, 64
	v_lshl_add_u64 v[166:167], v[166:167], 0, 64
	v_lshl_add_u64 v[162:163], v[162:163], 0, 64
	s_waitcnt lgkmcnt(0)
	v_mfma_f32_32x32x16_bf16 v[96:111], v[128:131], v[136:139], v[96:111]
	v_mfma_f32_32x32x16_bf16 v[112:127], v[128:131], v[140:143], v[112:127]
	ds_read_b128 v[192:195], v253
	ds_read_b128 v[196:199], v253 offset:2048
	v_mfma_f32_32x32x16_bf16 v[64:79], v[128:131], v[144:147], v[64:79]
	ds_read_b128 v[200:203], v255 offset:16384
	ds_read_b128 v[206:209], v255 offset:18432
	v_mfma_f32_32x32x16_bf16 v[80:95], v[128:131], v[148:151], v[80:95]
	ds_read_b128 v[210:213], v255 offset:20480
	ds_read_b128 v[214:217], v255 offset:22528
	v_mfma_f32_32x32x16_bf16 v[32:47], v[132:135], v[136:139], v[32:47]
	v_mfma_f32_32x32x16_bf16 v[48:63], v[132:135], v[140:143], v[48:63]
	v_mfma_f32_32x32x16_bf16 v[0:15], v[132:135], v[144:147], v[0:15]
	v_mfma_f32_32x32x16_bf16 v[16:31], v[132:135], v[148:151], v[16:31]
	s_waitcnt vmcnt(8)
	s_waitcnt lgkmcnt(0)
	s_barrier
; #define LGKM0_BAR asm volatile("s_waitcnt lgkmcnt(0)\n\ts_barrier" ::: "memory");
; __device__ __forceinline__ void gemm256_tile(const u16* Ab, int lda, const u16* Bb, int ldb, int K, char* smem,
;                                              f32x16 (&acc)[2][4]) {
;     ...
;     for (int s = 0; s < nks; ++s) {
;       const int q = s & 3;
;       G_MMA(afA, bfA)
;       __builtin_amdgcn_sched_barrier(0);
;       LGKM0_BAR
;       G_FRAGS(afB, bfB, q, fo1)
;       __builtin_amdgcn_sched_barrier(0);
;       LGKM0_BAR
;       G_MMA(afB, bfB)
;       __builtin_amdgcn_sched_barrier(0);
;       G_WAIT_BAR(s)
;       if (s + 4 < nks) DMA_STAGE(s + 4)
;       if (s + 1 < nks) G_FRAGS(afA, bfA, (s + 1) & 3, fo0)
;       __builtin_amdgcn_sched_barrier(0);
;       LGKM0_BAR
;     }
	ds_read_b128 v[128:131], v154 offset:32768
	ds_read_b128 v[132:135], v154 offset:34816
	ds_read_b128 v[136:139], v254 offset:49152
	ds_read_b128 v[140:143], v254 offset:51200
	ds_read_b128 v[144:147], v254 offset:53248
	ds_read_b128 v[148:151], v254 offset:55296
	v_xor_b32_e32 v154, 0x10000, v154
	v_xor_b32_e32 v254, 0x10000, v254
	s_add_u32 m0, s98, 0x0
	v_mfma_f32_32x32x16_bf16 v[96:111], v[192:195], v[200:203], v[96:111]
	global_load_lds_dwordx4 v[164:165], off
	v_mfma_f32_32x32x16_bf16 v[112:127], v[192:195], v[206:209], v[112:127]
	s_add_u32 m0, s98, 0x2000
	v_mfma_f32_32x32x16_bf16 v[64:79], v[192:195], v[210:213], v[64:79]
	global_load_lds_dwordx4 v[160:161], off
	v_mfma_f32_32x32x16_bf16 v[80:95], v[192:195], v[214:217], v[80:95]
	s_add_u32 m0, s98, 0x4000
	v_mfma_f32_32x32x16_bf16 v[32:47], v[196:199], v[200:203], v[32:47]
	global_load_lds_dwordx4 v[166:167], off
	v_mfma_f32_32x32x16_bf16 v[48:63], v[196:199], v[206:209], v[48:63]
	s_add_u32 m0, s98, 0x6000
	v_mfma_f32_32x32x16_bf16 v[0:15], v[196:199], v[210:213], v[0:15]
	global_load_lds_dwordx4 v[162:163], off
	v_mfma_f32_32x32x16_bf16 v[16:31], v[196:199], v[214:217], v[16:31]
	v_lshl_add_u64 v[164:165], v[164:165], 0, 64
	v_lshl_add_u64 v[160:161], v[160:161], 0, 64
	v_lshl_add_u64 v[166:167], v[166:167], 0, 64
	v_lshl_add_u64 v[162:163], v[162:163], 0, 64
	s_waitcnt lgkmcnt(0)
	v_mfma_f32_32x32x16_bf16 v[96:111], v[128:131], v[136:139], v[96:111]
	v_mfma_f32_32x32x16_bf16 v[112:127], v[128:131], v[140:143], v[112:127]
	ds_read_b128 v[192:195], v253 offset:32768
	ds_read_b128 v[196:199], v253 offset:34816
	v_mfma_f32_32x32x16_bf16 v[64:79], v[128:131], v[144:147], v[64:79]
	ds_read_b128 v[200:203], v255 offset:49152
	ds_read_b128 v[206:209], v255 offset:51200
	v_mfma_f32_32x32x16_bf16 v[80:95], v[128:131], v[148:151], v[80:95]
	ds_read_b128 v[210:213], v255 offset:53248
	ds_read_b128 v[214:217], v255 offset:55296
	v_mfma_f32_32x32x16_bf16 v[32:47], v[132:135], v[136:139], v[32:47]
	v_mfma_f32_32x32x16_bf16 v[48:63], v[132:135], v[140:143], v[48:63]
	v_mfma_f32_32x32x16_bf16 v[0:15], v[132:135], v[144:147], v[0:15]
	v_mfma_f32_32x32x16_bf16 v[16:31], v[132:135], v[148:151], v[16:31]
	v_xor_b32_e32 v253, 0x10000, v253
	v_xor_b32_e32 v255, 0x10000, v255
	s_waitcnt vmcnt(8)
	s_waitcnt lgkmcnt(0)
	s_barrier
	ds_read_b128 v[128:131], v154
	ds_read_b128 v[132:135], v154 offset:2048
	ds_read_b128 v[136:139], v254 offset:16384
	ds_read_b128 v[140:143], v254 offset:18432
	ds_read_b128 v[144:147], v254 offset:20480
	ds_read_b128 v[148:151], v254 offset:22528
	s_add_u32 m0, s98, 0x8000
	v_mfma_f32_32x32x16_bf16 v[96:111], v[192:195], v[200:203], v[96:111]
	global_load_lds_dwordx4 v[164:165], off
	v_mfma_f32_32x32x16_bf16 v[112:127], v[192:195], v[206:209], v[112:127]
	s_add_u32 m0, s98, 0xa000
	v_mfma_f32_32x32x16_bf16 v[64:79], v[192:195], v[210:213], v[64:79]
	global_load_lds_dwordx4 v[160:161], off
	v_mfma_f32_32x32x16_bf16 v[80:95], v[192:195], v[214:217], v[80:95]
	s_add_u32 m0, s98, 0xc000
	v_mfma_f32_32x32x16_bf16 v[32:47], v[196:199], v[200:203], v[32:47]
	global_load_lds_dwordx4 v[166:167], off
	v_mfma_f32_32x32x16_bf16 v[48:63], v[196:199], v[206:209], v[48:63]
	s_add_u32 m0, s98, 0xe000
	v_mfma_f32_32x32x16_bf16 v[0:15], v[196:199], v[210:213], v[0:15]
	global_load_lds_dwordx4 v[162:163], off
	v_mfma_f32_32x32x16_bf16 v[16:31], v[196:199], v[214:217], v[16:31]
	v_lshl_add_u64 v[164:165], v[164:165], 0, 64
	v_lshl_add_u64 v[160:161], v[160:161], 0, 64
	v_lshl_add_u64 v[166:167], v[166:167], 0, 64
	v_lshl_add_u64 v[162:163], v[162:163], 0, 64
	s_waitcnt lgkmcnt(0)
	v_mfma_f32_32x32x16_bf16 v[96:111], v[128:131], v[136:139], v[96:111]
	v_mfma_f32_32x32x16_bf16 v[112:127], v[128:131], v[140:143], v[112:127]
	ds_read_b128 v[192:195], v253
	ds_read_b128 v[196:199], v253 offset:2048
	v_mfma_f32_32x32x16_bf16 v[64:79], v[128:131], v[144:147], v[64:79]
	ds_read_b128 v[200:203], v255 offset:16384
	ds_read_b128 v[206:209], v255 offset:18432
	v_mfma_f32_32x32x16_bf16 v[80:95], v[128:131], v[148:151], v[80:95]
	ds_read_b128 v[210:213], v255 offset:20480
	ds_read_b128 v[214:217], v255 offset:22528
	v_mfma_f32_32x32x16_bf16 v[32:47], v[132:135], v[136:139], v[32:47]
	v_mfma_f32_32x32x16_bf16 v[48:63], v[132:135], v[140:143], v[48:63]
	v_mfma_f32_32x32x16_bf16 v[0:15], v[132:135], v[144:147], v[0:15]
	v_mfma_f32_32x32x16_bf16 v[16:31], v[132:135], v[148:151], v[16:31]
	s_waitcnt vmcnt(8)
	s_waitcnt lgkmcnt(0)
	s_barrier
; #define LGKM0_BAR asm volatile("s_waitcnt lgkmcnt(0)\n\ts_barrier" ::: "memory");
; __device__ __forceinline__ void gemm256_tile(const u16* Ab, int lda, const u16* Bb, int ldb, int K, char* smem,
;                                              f32x16 (&acc)[2][4]) {
;     ...
;     for (int s = 0; s < nks; ++s) {
;       const int q = s & 3;
;       G_MMA(afA, bfA)
;       __builtin_amdgcn_sched_barrier(0);
;       LGKM0_BAR
;       G_FRAGS(afB, bfB, q, fo1)
;       __builtin_amdgcn_sched_barrier(0);
;       LGKM0_BAR
;       G_MMA(afB, bfB)
;       __builtin_amdgcn_sched_barrier(0);
;       G_WAIT_BAR(s)
;       if (s + 4 < nks) DMA_STAGE(s + 4)
;       if (s + 1 < nks) G_FRAGS(afA, bfA, (s + 1) & 3, fo0)
;       __builtin_amdgcn_sched_barrier(0);
;       LGKM0_BAR
;     }
	ds_read_b128 v[128:131], v154 offset:32768
	ds_read_b128 v[132:135], v154 offset:34816
	ds_read_b128 v[136:139], v254 offset:49152
	ds_read_b128 v[140:143], v254 offset:51200
	ds_read_b128 v[144:147], v254 offset:53248
	ds_read_b128 v[148:151], v254 offset:55296
	v_xor_b32_e32 v154, 0x10000, v154
	v_xor_b32_e32 v254, 0x10000, v254
	s_add_u32 m0, s98, 0x10000
	v_mfma_f32_32x32x16_bf16 v[96:111], v[192:195], v[200:203], v[96:111]
	global_load_lds_dwordx4 v[164:165], off
	v_mfma_f32_32x32x16_bf16 v[112:127], v[192:195], v[206:209], v[112:127]
	s_add_u32 m0, s98, 0x12000
	v_mfma_f32_32x32x16_bf16 v[64:79], v[192:195], v[210:213], v[64:79]
	global_load_lds_dwordx4 v[160:161], off
	v_mfma_f32_32x32x16_bf16 v[80:95], v[192:195], v[214:217], v[80:95]
	s_add_u32 m0, s98, 0x14000
	v_mfma_f32_32x32x16_bf16 v[32:47], v[196:199], v[200:203], v[32:47]
	global_load_lds_dwordx4 v[166:167], off
	v_mfma_f32_32x32x16_bf16 v[48:63], v[196:199], v[206:209], v[48:63]
	s_add_u32 m0, s98, 0x16000
	v_mfma_f32_32x32x16_bf16 v[0:15], v[196:199], v[210:213], v[0:15]
	global_load_lds_dwordx4 v[162:163], off
	v_mfma_f32_32x32x16_bf16 v[16:31], v[196:199], v[214:217], v[16:31]
	v_lshl_add_u64 v[164:165], v[164:165], 0, 64
	v_lshl_add_u64 v[160:161], v[160:161], 0, 64
	v_lshl_add_u64 v[166:167], v[166:167], 0, 64
	v_lshl_add_u64 v[162:163], v[162:163], 0, 64
	s_waitcnt lgkmcnt(0)
	v_mfma_f32_32x32x16_bf16 v[96:111], v[128:131], v[136:139], v[96:111]
	v_mfma_f32_32x32x16_bf16 v[112:127], v[128:131], v[140:143], v[112:127]
	ds_read_b128 v[192:195], v253 offset:32768
	ds_read_b128 v[196:199], v253 offset:34816
	v_mfma_f32_32x32x16_bf16 v[64:79], v[128:131], v[144:147], v[64:79]
	ds_read_b128 v[200:203], v255 offset:49152
	ds_read_b128 v[206:209], v255 offset:51200
	v_mfma_f32_32x32x16_bf16 v[80:95], v[128:131], v[148:151], v[80:95]
	ds_read_b128 v[210:213], v255 offset:53248
	ds_read_b128 v[214:217], v255 offset:55296
	v_mfma_f32_32x32x16_bf16 v[32:47], v[132:135], v[136:139], v[32:47]
	v_mfma_f32_32x32x16_bf16 v[48:63], v[132:135], v[140:143], v[48:63]
	v_mfma_f32_32x32x16_bf16 v[0:15], v[132:135], v[144:147], v[0:15]
	v_mfma_f32_32x32x16_bf16 v[16:31], v[132:135], v[148:151], v[16:31]
	v_xor_b32_e32 v253, 0x10000, v253
	v_xor_b32_e32 v255, 0x10000, v255
	s_waitcnt vmcnt(8)
	s_waitcnt lgkmcnt(0)
	s_sub_u32 s99, s99, 1
	s_cmp_lg_u32 s99, 0
	s_cbranch_scc1 .Lmy_gemm_i2_loop
	s_barrier
	ds_read_b128 v[128:131], v154
	ds_read_b128 v[132:135], v154 offset:2048
	ds_read_b128 v[136:139], v254 offset:16384
	ds_read_b128 v[140:143], v254 offset:18432
	ds_read_b128 v[144:147], v254 offset:20480
	ds_read_b128 v[148:151], v254 offset:22528
	s_add_u32 m0, s98, 0x18000
	v_mfma_f32_32x32x16_bf16 v[96:111], v[192:195], v[200:203], v[96:111]
	global_load_lds_dwordx4 v[164:165], off
	v_mfma_f32_32x32x16_bf16 v[112:127], v[192:195], v[206:209], v[112:127]
	s_add_u32 m0, s98, 0x1a000
	v_mfma_f32_32x32x16_bf16 v[64:79], v[192:195], v[210:213], v[64:79]
	global_load_lds_dwordx4 v[160:161], off
	v_mfma_f32_32x32x16_bf16 v[80:95], v[192:195], v[214:217], v[80:95]
	s_add_u32 m0, s98, 0x1c000
	v_mfma_f32_32x32x16_bf16 v[32:47], v[196:199], v[200:203], v[32:47]
	global_load_lds_dwordx4 v[166:167], off
	v_mfma_f32_32x32x16_bf16 v[48:63], v[196:199], v[206:209], v[48:63]
	s_add_u32 m0, s98, 0x1e000
	v_mfma_f32_32x32x16_bf16 v[0:15], v[196:199], v[210:213], v[0:15]
	global_load_lds_dwordx4 v[162:163], off
	v_mfma_f32_32x32x16_bf16 v[16:31], v[196:199], v[214:217], v[16:31]
	v_lshl_add_u64 v[164:165], v[164:165], 0, 64
	v_lshl_add_u64 v[160:161], v[160:161], 0, 64
	v_lshl_add_u64 v[166:167], v[166:167], 0, 64
	v_lshl_add_u64 v[162:163], v[162:163], 0, 64
	s_waitcnt lgkmcnt(0)
	v_mfma_f32_32x32x16_bf16 v[96:111], v[128:131], v[136:139], v[96:111]
	v_mfma_f32_32x32x16_bf16 v[112:127], v[128:131], v[140:143], v[112:127]
	ds_read_b128 v[192:195], v253
	ds_read_b128 v[196:199], v253 offset:2048
	v_mfma_f32_32x32x16_bf16 v[64:79], v[128:131], v[144:147], v[64:79]
	ds_read_b128 v[200:203], v255 offset:16384
	ds_read_b128 v[206:209], v255 offset:18432
	v_mfma_f32_32x32x16_bf16 v[80:95], v[128:131], v[148:151], v[80:95]
	ds_read_b128 v[210:213], v255 offset:20480
	ds_read_b128 v[214:217], v255 offset:22528
	v_mfma_f32_32x32x16_bf16 v[32:47], v[132:135], v[136:139], v[32:47]
	v_mfma_f32_32x32x16_bf16 v[48:63], v[132:135], v[140:143], v[48:63]
	v_mfma_f32_32x32x16_bf16 v[0:15], v[132:135], v[144:147], v[0:15]
	v_mfma_f32_32x32x16_bf16 v[16:31], v[132:135], v[148:151], v[16:31]
	s_waitcnt vmcnt(8)
	s_waitcnt lgkmcnt(0)
	s_barrier
; #define LGKM0_BAR asm volatile("s_waitcnt lgkmcnt(0)\n\ts_barrier" ::: "memory");
; __device__ __forceinline__ void gemm256_tile(const u16* Ab, int lda, const u16* Bb, int ldb, int K, char* smem,
;                                              f32x16 (&acc)[2][4]) {
;     ...
;     for (int s = 0; s < nks; ++s) {
;       const int q = s & 3;
;       G_MMA(afA, bfA)
;       __builtin_amdgcn_sched_barrier(0);
;       LGKM0_BAR
;       G_FRAGS(afB, bfB, q, fo1)
;       __builtin_amdgcn_sched_barrier(0);
;       LGKM0_BAR
;       G_MMA(afB, bfB)
;       __builtin_amdgcn_sched_barrier(0);
;       G_WAIT_BAR(s)
;       if (s + 4 < nks) DMA_STAGE(s + 4)
;       if (s + 1 < nks) G_FRAGS(afA, bfA, (s + 1) & 3, fo0)
;       __builtin_amdgcn_sched_barrier(0);
;       LGKM0_BAR
;     }
;   } else {
;     LGKM0_BAR
;     for (int s = 0; s < nks; ++s) {
;       const int q = s & 3;
;       G_FRAGS(afA, bfA, q, fo0)
;       __builtin_amdgcn_sched_barrier(0);
;       LGKM0_BAR
;       G_MMA(afA, bfA)
;       __builtin_amdgcn_sched_barrier(0);
;       LGKM0_BAR
;       G_FRAGS(afB, bfB, q, fo1)
;       __builtin_amdgcn_sched_barrier(0);
;       G_WAIT_BAR(s)
;       G_MMA(afB, bfB)
;       __builtin_amdgcn_sched_barrier(0);
;       if (s + 4 < nks) DMA_STAGE(s + 4)
;       __builtin_amdgcn_sched_barrier(0);
;       LGKM0_BAR
;     }
;   }
;     ...
;   __syncthreads();
	ds_read_b128 v[128:131], v154 offset:32768
	ds_read_b128 v[132:135], v154 offset:34816
	ds_read_b128 v[136:139], v254 offset:49152
	ds_read_b128 v[140:143], v254 offset:51200
	ds_read_b128 v[144:147], v254 offset:53248
	ds_read_b128 v[148:151], v254 offset:55296
	v_xor_b32_e32 v154, 0x10000, v154
	v_xor_b32_e32 v254, 0x10000, v254
	v_mfma_f32_32x32x16_bf16 v[96:111], v[192:195], v[200:203], v[96:111]
	v_mfma_f32_32x32x16_bf16 v[112:127], v[192:195], v[206:209], v[112:127]
	v_mfma_f32_32x32x16_bf16 v[64:79], v[192:195], v[210:213], v[64:79]
	v_mfma_f32_32x32x16_bf16 v[80:95], v[192:195], v[214:217], v[80:95]
	v_mfma_f32_32x32x16_bf16 v[32:47], v[196:199], v[200:203], v[32:47]
	v_mfma_f32_32x32x16_bf16 v[48:63], v[196:199], v[206:209], v[48:63]
	v_mfma_f32_32x32x16_bf16 v[0:15], v[196:199], v[210:213], v[0:15]
	v_mfma_f32_32x32x16_bf16 v[16:31], v[196:199], v[214:217], v[16:31]
	s_waitcnt lgkmcnt(0)
	v_mfma_f32_32x32x16_bf16 v[96:111], v[128:131], v[136:139], v[96:111]
	v_mfma_f32_32x32x16_bf16 v[112:127], v[128:131], v[140:143], v[112:127]
	ds_read_b128 v[192:195], v253 offset:32768
	ds_read_b128 v[196:199], v253 offset:34816
	v_mfma_f32_32x32x16_bf16 v[64:79], v[128:131], v[144:147], v[64:79]
	ds_read_b128 v[200:203], v255 offset:49152
	ds_read_b128 v[206:209], v255 offset:51200
	v_mfma_f32_32x32x16_bf16 v[80:95], v[128:131], v[148:151], v[80:95]
	ds_read_b128 v[210:213], v255 offset:53248
	ds_read_b128 v[214:217], v255 offset:55296
	v_mfma_f32_32x32x16_bf16 v[32:47], v[132:135], v[136:139], v[32:47]
	v_mfma_f32_32x32x16_bf16 v[48:63], v[132:135], v[140:143], v[48:63]
	v_mfma_f32_32x32x16_bf16 v[0:15], v[132:135], v[144:147], v[0:15]
	v_mfma_f32_32x32x16_bf16 v[16:31], v[132:135], v[148:151], v[16:31]
	v_xor_b32_e32 v253, 0x10000, v253
	v_xor_b32_e32 v255, 0x10000, v255
	s_waitcnt vmcnt(4)
	s_waitcnt lgkmcnt(0)
	s_barrier
	ds_read_b128 v[128:131], v154
	ds_read_b128 v[132:135], v154 offset:2048
	ds_read_b128 v[136:139], v254 offset:16384
	ds_read_b128 v[140:143], v254 offset:18432
	ds_read_b128 v[144:147], v254 offset:20480
	ds_read_b128 v[148:151], v254 offset:22528
	v_mfma_f32_32x32x16_bf16 v[96:111], v[192:195], v[200:203], v[96:111]
	v_mfma_f32_32x32x16_bf16 v[112:127], v[192:195], v[206:209], v[112:127]
	v_mfma_f32_32x32x16_bf16 v[64:79], v[192:195], v[210:213], v[64:79]
	v_mfma_f32_32x32x16_bf16 v[80:95], v[192:195], v[214:217], v[80:95]
	v_mfma_f32_32x32x16_bf16 v[32:47], v[196:199], v[200:203], v[32:47]
	v_mfma_f32_32x32x16_bf16 v[48:63], v[196:199], v[206:209], v[48:63]
	v_mfma_f32_32x32x16_bf16 v[0:15], v[196:199], v[210:213], v[0:15]
	v_mfma_f32_32x32x16_bf16 v[16:31], v[196:199], v[214:217], v[16:31]
	s_waitcnt lgkmcnt(0)
	v_mfma_f32_32x32x16_bf16 v[96:111], v[128:131], v[136:139], v[96:111]
	v_mfma_f32_32x32x16_bf16 v[112:127], v[128:131], v[140:143], v[112:127]
	ds_read_b128 v[192:195], v253
	ds_read_b128 v[196:199], v253 offset:2048
	v_mfma_f32_32x32x16_bf16 v[64:79], v[128:131], v[144:147], v[64:79]
	ds_read_b128 v[200:203], v255 offset:16384
	ds_read_b128 v[206:209], v255 offset:18432
	v_mfma_f32_32x32x16_bf16 v[80:95], v[128:131], v[148:151], v[80:95]
	ds_read_b128 v[210:213], v255 offset:20480
	ds_read_b128 v[214:217], v255 offset:22528
	v_mfma_f32_32x32x16_bf16 v[32:47], v[132:135], v[136:139], v[32:47]
	v_mfma_f32_32x32x16_bf16 v[48:63], v[132:135], v[140:143], v[48:63]
	v_mfma_f32_32x32x16_bf16 v[0:15], v[132:135], v[144:147], v[0:15]
	v_mfma_f32_32x32x16_bf16 v[16:31], v[132:135], v[148:151], v[16:31]
	s_waitcnt vmcnt(0)
	s_waitcnt lgkmcnt(0)
	s_barrier
	ds_read_b128 v[128:131], v154 offset:32768
	ds_read_b128 v[132:135], v154 offset:34816
	ds_read_b128 v[136:139], v254 offset:49152
	ds_read_b128 v[140:143], v254 offset:51200
	ds_read_b128 v[144:147], v254 offset:53248
	ds_read_b128 v[148:151], v254 offset:55296
	v_xor_b32_e32 v154, 0x10000, v154
	v_xor_b32_e32 v254, 0x10000, v254
	v_mfma_f32_32x32x16_bf16 v[96:111], v[192:195], v[200:203], v[96:111]
	v_mfma_f32_32x32x16_bf16 v[112:127], v[192:195], v[206:209], v[112:127]
	v_mfma_f32_32x32x16_bf16 v[64:79], v[192:195], v[210:213], v[64:79]
	v_mfma_f32_32x32x16_bf16 v[80:95], v[192:195], v[214:217], v[80:95]
	v_mfma_f32_32x32x16_bf16 v[32:47], v[196:199], v[200:203], v[32:47]
	v_mfma_f32_32x32x16_bf16 v[48:63], v[196:199], v[206:209], v[48:63]
	v_mfma_f32_32x32x16_bf16 v[0:15], v[196:199], v[210:213], v[0:15]
	v_mfma_f32_32x32x16_bf16 v[16:31], v[196:199], v[214:217], v[16:31]
	s_waitcnt lgkmcnt(0)
	v_mfma_f32_32x32x16_bf16 v[96:111], v[128:131], v[136:139], v[96:111]
	v_mfma_f32_32x32x16_bf16 v[112:127], v[128:131], v[140:143], v[112:127]
	ds_read_b128 v[192:195], v253 offset:32768
	ds_read_b128 v[196:199], v253 offset:34816
	v_mfma_f32_32x32x16_bf16 v[64:79], v[128:131], v[144:147], v[64:79]
	ds_read_b128 v[200:203], v255 offset:49152
	ds_read_b128 v[206:209], v255 offset:51200
	v_mfma_f32_32x32x16_bf16 v[80:95], v[128:131], v[148:151], v[80:95]
	ds_read_b128 v[210:213], v255 offset:53248
	ds_read_b128 v[214:217], v255 offset:55296
	v_mfma_f32_32x32x16_bf16 v[32:47], v[132:135], v[136:139], v[32:47]
	v_mfma_f32_32x32x16_bf16 v[48:63], v[132:135], v[140:143], v[48:63]
	v_mfma_f32_32x32x16_bf16 v[0:15], v[132:135], v[144:147], v[0:15]
	v_mfma_f32_32x32x16_bf16 v[16:31], v[132:135], v[148:151], v[16:31]
	v_xor_b32_e32 v253, 0x10000, v253
	v_xor_b32_e32 v255, 0x10000, v255
	s_waitcnt lgkmcnt(0)
	v_mfma_f32_32x32x16_bf16 v[96:111], v[192:195], v[200:203], v[96:111]
	v_mfma_f32_32x32x16_bf16 v[112:127], v[192:195], v[206:209], v[112:127]
	v_mfma_f32_32x32x16_bf16 v[64:79], v[192:195], v[210:213], v[64:79]
	v_mfma_f32_32x32x16_bf16 v[80:95], v[192:195], v[214:217], v[80:95]
	v_mfma_f32_32x32x16_bf16 v[32:47], v[196:199], v[200:203], v[32:47]
	v_mfma_f32_32x32x16_bf16 v[48:63], v[196:199], v[206:209], v[48:63]
	v_mfma_f32_32x32x16_bf16 v[0:15], v[196:199], v[210:213], v[0:15]
	v_mfma_f32_32x32x16_bf16 v[16:31], v[196:199], v[214:217], v[16:31]
	s_nop 15
	s_branch .LBB0_1024

; #define LGKM0_BAR asm volatile("s_waitcnt lgkmcnt(0)\n\ts_barrier" ::: "memory");
; __device__ __forceinline__ void gemm256_tile(const u16* Ab, int lda, const u16* Bb, int ldb, int K, char* smem,
;                                              f32x16 (&acc)[2][4]) {
;     ...
;   const int xsw = (lane >> 2) & 3, hh = lane >> 5;
;   const unsigned fo0 = (unsigned)((hh ^ xsw) * 16), fo1 = (unsigned)(((2 + hh) ^ xsw) * 16);
;   const unsigned fa = (unsigned)((wm * 64 + (lane & 31)) * 64);
;   const unsigned fb = (unsigned)(16384 + (wn * 128 + (lane & 31)) * 64);
;     ...
;   asm volatile("s_waitcnt vmcnt(0)" ::: "memory");
;   const bool h1 = __builtin_amdgcn_readfirstlane(wid) >= 4;
;     ...
;   DMA_STAGE(0)
;   if (nks > 1) DMA_STAGE(1)
;   if (nks > 2) DMA_STAGE(2)
;   if (nks > 3) DMA_STAGE(3)
;   if (nks > 3)      asm volatile("s_waitcnt vmcnt(12)\n\ts_barrier" ::: "memory");
;   else if (nks > 2) asm volatile("s_waitcnt vmcnt(8)\n\ts_barrier" ::: "memory");
;   else if (nks > 1) asm volatile("s_waitcnt vmcnt(4)\n\ts_barrier" ::: "memory");
;   else              asm volatile("s_waitcnt vmcnt(0)\n\ts_barrier" ::: "memory");
;   bf16x8 afA[2], bfA[4], afB[2], bfB[4];
;   if (!h1) {
;     G_FRAGS(afA, bfA, 0, fo0)
;     LGKM0_BAR
;     for (int s = 0; s < nks; ++s) {
;       const int q = s & 3;
;       G_MMA(afA, bfA)
;       __builtin_amdgcn_sched_barrier(0);
;       LGKM0_BAR
;       G_FRAGS(afB, bfB, q, fo1)
;       __builtin_amdgcn_sched_barrier(0);
;       LGKM0_BAR
;       G_MMA(afB, bfB)
;       __builtin_amdgcn_sched_barrier(0);
;       G_WAIT_BAR(s)
;       if (s + 4 < nks) DMA_STAGE(s + 4)
;       if (s + 1 < nks) G_FRAGS(afA, bfA, (s + 1) & 3, fo0)
;       __builtin_amdgcn_sched_barrier(0);
;       LGKM0_BAR
;     }
.LBB0_1161:
	v_lshrrev_b32_e32 v192, 6, v152
	v_bfe_u32 v193, v152, 2, 2
	v_readfirstlane_b32 s98, v192
	v_bfe_u32 v194, v152, 5, 1
	v_xor_b32_e32 v193, v194, v193
	v_lshlrev_b32_e32 v193, 4, v193
	v_xor_b32_e32 v194, 32, v193
	v_and_b32_e32 v195, 31, v152
	v_lshrrev_b32_e32 v196, 7, v152
	v_lshl_add_u32 v196, v196, 6, v195
	v_lshlrev_b32_e32 v196, 6, v196
	v_bfe_u32 v197, v152, 6, 1
	v_lshl_add_u32 v197, v197, 7, v195
	v_lshlrev_b32_e32 v197, 6, v197
	v_add3_u32 v154, v196, v193, 16
	v_add3_u32 v253, v196, v194, 16
	v_add3_u32 v254, v197, v193, 16
	v_add3_u32 v255, v197, v194, 16
	s_lshl_b32 s98, s98, 10
	s_add_u32 s98, s98, 16
	v_lshl_add_u64 v[160:161], 64, 2, v[160:161]
	v_lshl_add_u64 v[162:163], 64, 2, v[162:163]
	v_lshl_add_u64 v[164:165], 64, 2, v[164:165]
	v_lshl_add_u64 v[166:167], 64, 2, v[166:167]
	s_barrier
	ds_read_b128 v[128:131], v154
	ds_read_b128 v[132:135], v154 offset:2048
	ds_read_b128 v[136:139], v254 offset:16384
	ds_read_b128 v[140:143], v254 offset:18432
	ds_read_b128 v[144:147], v254 offset:20480
	ds_read_b128 v[148:151], v254 offset:22528
	s_waitcnt lgkmcnt(0)
	v_mfma_f32_32x32x16_bf16 v[112:127], v[128:131], v[136:139], 0
	v_mfma_f32_32x32x16_bf16 v[96:111], v[128:131], v[140:143], 0
	ds_read_b128 v[192:195], v253
	ds_read_b128 v[196:199], v253 offset:2048
	v_mfma_f32_32x32x16_bf16 v[80:95], v[128:131], v[144:147], 0
	ds_read_b128 v[200:203], v255 offset:16384
	ds_read_b128 v[206:209], v255 offset:18432
	v_mfma_f32_32x32x16_bf16 v[64:79], v[128:131], v[148:151], 0
	ds_read_b128 v[210:213], v255 offset:20480
	ds_read_b128 v[214:217], v255 offset:22528
	v_mfma_f32_32x32x16_bf16 v[48:63], v[132:135], v[136:139], 0
	v_mfma_f32_32x32x16_bf16 v[32:47], v[132:135], v[140:143], 0
	v_mfma_f32_32x32x16_bf16 v[16:31], v[132:135], v[144:147], 0
	v_mfma_f32_32x32x16_bf16 v[0:15], v[132:135], v[148:151], 0
	s_waitcnt vmcnt(8)
	s_waitcnt lgkmcnt(0)
	s_barrier
	ds_read_b128 v[128:131], v154 offset:32768
	ds_read_b128 v[132:135], v154 offset:34816
	ds_read_b128 v[136:139], v254 offset:49152
	ds_read_b128 v[140:143], v254 offset:51200
	ds_read_b128 v[144:147], v254 offset:53248
	ds_read_b128 v[148:151], v254 offset:55296
	v_xor_b32_e32 v154, 0x10000, v154
	v_xor_b32_e32 v254, 0x10000, v254
	s_add_u32 m0, s98, 0x0
	v_mfma_f32_32x32x16_bf16 v[112:127], v[192:195], v[200:203], v[112:127]
	global_load_lds_dwordx4 v[160:161], off
	v_mfma_f32_32x32x16_bf16 v[96:111], v[192:195], v[206:209], v[96:111]
	s_add_u32 m0, s98, 0x2000
	v_mfma_f32_32x32x16_bf16 v[80:95], v[192:195], v[210:213], v[80:95]
	global_load_lds_dwordx4 v[162:163], off
	v_mfma_f32_32x32x16_bf16 v[64:79], v[192:195], v[214:217], v[64:79]
	s_add_u32 m0, s98, 0x4000
	v_mfma_f32_32x32x16_bf16 v[48:63], v[196:199], v[200:203], v[48:63]
	global_load_lds_dwordx4 v[164:165], off
	v_mfma_f32_32x32x16_bf16 v[32:47], v[196:199], v[206:209], v[32:47]
	s_add_u32 m0, s98, 0x6000
	v_mfma_f32_32x32x16_bf16 v[16:31], v[196:199], v[210:213], v[16:31]
	global_load_lds_dwordx4 v[166:167], off
	v_mfma_f32_32x32x16_bf16 v[0:15], v[196:199], v[214:217], v[0:15]
	v_lshl_add_u64 v[160:161], v[160:161], 0, 64
	v_lshl_add_u64 v[162:163], v[162:163], 0, 64
	v_lshl_add_u64 v[164:165], v[164:165], 0, 64
	v_lshl_add_u64 v[166:167], v[166:167], 0, 64
	s_waitcnt lgkmcnt(0)
	v_mfma_f32_32x32x16_bf16 v[112:127], v[128:131], v[136:139], v[112:127]
	v_mfma_f32_32x32x16_bf16 v[96:111], v[128:131], v[140:143], v[96:111]
	ds_read_b128 v[192:195], v253 offset:32768
	ds_read_b128 v[196:199], v253 offset:34816
	v_mfma_f32_32x32x16_bf16 v[80:95], v[128:131], v[144:147], v[80:95]
	ds_read_b128 v[200:203], v255 offset:49152
	ds_read_b128 v[206:209], v255 offset:51200
	v_mfma_f32_32x32x16_bf16 v[64:79], v[128:131], v[148:151], v[64:79]
	ds_read_b128 v[210:213], v255 offset:53248
	ds_read_b128 v[214:217], v255 offset:55296
	v_mfma_f32_32x32x16_bf16 v[48:63], v[132:135], v[136:139], v[48:63]
	v_mfma_f32_32x32x16_bf16 v[32:47], v[132:135], v[140:143], v[32:47]
	v_mfma_f32_32x32x16_bf16 v[16:31], v[132:135], v[144:147], v[16:31]
	v_mfma_f32_32x32x16_bf16 v[0:15], v[132:135], v[148:151], v[0:15]
	v_xor_b32_e32 v253, 0x10000, v253
	v_xor_b32_e32 v255, 0x10000, v255
	s_waitcnt vmcnt(8)
	s_waitcnt lgkmcnt(0)
	s_barrier
	ds_read_b128 v[128:131], v154
	ds_read_b128 v[132:135], v154 offset:2048
	ds_read_b128 v[136:139], v254 offset:16384
	ds_read_b128 v[140:143], v254 offset:18432
	ds_read_b128 v[144:147], v254 offset:20480
	ds_read_b128 v[148:151], v254 offset:22528
	s_add_u32 m0, s98, 0x8000
	v_mfma_f32_32x32x16_bf16 v[112:127], v[192:195], v[200:203], v[112:127]
	global_load_lds_dwordx4 v[160:161], off
	v_mfma_f32_32x32x16_bf16 v[96:111], v[192:195], v[206:209], v[96:111]
	s_add_u32 m0, s98, 0xa000
	v_mfma_f32_32x32x16_bf16 v[80:95], v[192:195], v[210:213], v[80:95]
	global_load_lds_dwordx4 v[162:163], off
	v_mfma_f32_32x32x16_bf16 v[64:79], v[192:195], v[214:217], v[64:79]
	s_add_u32 m0, s98, 0xc000
	v_mfma_f32_32x32x16_bf16 v[48:63], v[196:199], v[200:203], v[48:63]
	global_load_lds_dwordx4 v[164:165], off
	v_mfma_f32_32x32x16_bf16 v[32:47], v[196:199], v[206:209], v[32:47]
	s_add_u32 m0, s98, 0xe000
	v_mfma_f32_32x32x16_bf16 v[16:31], v[196:199], v[210:213], v[16:31]
	global_load_lds_dwordx4 v[166:167], off
	v_mfma_f32_32x32x16_bf16 v[0:15], v[196:199], v[214:217], v[0:15]
	v_lshl_add_u64 v[160:161], v[160:161], 0, 64
	v_lshl_add_u64 v[162:163], v[162:163], 0, 64
	v_lshl_add_u64 v[164:165], v[164:165], 0, 64
	v_lshl_add_u64 v[166:167], v[166:167], 0, 64
	s_waitcnt lgkmcnt(0)
	v_mfma_f32_32x32x16_bf16 v[112:127], v[128:131], v[136:139], v[112:127]
	v_mfma_f32_32x32x16_bf16 v[96:111], v[128:131], v[140:143], v[96:111]
	ds_read_b128 v[192:195], v253
	ds_read_b128 v[196:199], v253 offset:2048
	v_mfma_f32_32x32x16_bf16 v[80:95], v[128:131], v[144:147], v[80:95]
	ds_read_b128 v[200:203], v255 offset:16384
	ds_read_b128 v[206:209], v255 offset:18432
	v_mfma_f32_32x32x16_bf16 v[64:79], v[128:131], v[148:151], v[64:79]
	ds_read_b128 v[210:213], v255 offset:20480
	ds_read_b128 v[214:217], v255 offset:22528
	v_mfma_f32_32x32x16_bf16 v[48:63], v[132:135], v[136:139], v[48:63]
	v_mfma_f32_32x32x16_bf16 v[32:47], v[132:135], v[140:143], v[32:47]
	v_mfma_f32_32x32x16_bf16 v[16:31], v[132:135], v[144:147], v[16:31]
	v_mfma_f32_32x32x16_bf16 v[0:15], v[132:135], v[148:151], v[0:15]
	s_waitcnt vmcnt(8)
	s_waitcnt lgkmcnt(0)
	s_barrier
; #define LGKM0_BAR asm volatile("s_waitcnt lgkmcnt(0)\n\ts_barrier" ::: "memory");
; __device__ __forceinline__ void gemm256_tile(const u16* Ab, int lda, const u16* Bb, int ldb, int K, char* smem,
;                                              f32x16 (&acc)[2][4]) {
;     ...
;     for (int s = 0; s < nks; ++s) {
;       const int q = s & 3;
;       G_MMA(afA, bfA)
;       __builtin_amdgcn_sched_barrier(0);
;       LGKM0_BAR
;       G_FRAGS(afB, bfB, q, fo1)
;       __builtin_amdgcn_sched_barrier(0);
;       LGKM0_BAR
;       G_MMA(afB, bfB)
;       __builtin_amdgcn_sched_barrier(0);
;       G_WAIT_BAR(s)
;       if (s + 4 < nks) DMA_STAGE(s + 4)
;       if (s + 1 < nks) G_FRAGS(afA, bfA, (s + 1) & 3, fo0)
;       __builtin_amdgcn_sched_barrier(0);
;       LGKM0_BAR
;     }
	ds_read_b128 v[128:131], v154 offset:32768
	ds_read_b128 v[132:135], v154 offset:34816
	ds_read_b128 v[136:139], v254 offset:49152
	ds_read_b128 v[140:143], v254 offset:51200
	ds_read_b128 v[144:147], v254 offset:53248
	ds_read_b128 v[148:151], v254 offset:55296
	v_xor_b32_e32 v154, 0x10000, v154
	v_xor_b32_e32 v254, 0x10000, v254
	s_add_u32 m0, s98, 0x10000
	v_mfma_f32_32x32x16_bf16 v[112:127], v[192:195], v[200:203], v[112:127]
	global_load_lds_dwordx4 v[160:161], off
	v_mfma_f32_32x32x16_bf16 v[96:111], v[192:195], v[206:209], v[96:111]
	s_add_u32 m0, s98, 0x12000
	v_mfma_f32_32x32x16_bf16 v[80:95], v[192:195], v[210:213], v[80:95]
	global_load_lds_dwordx4 v[162:163], off
	v_mfma_f32_32x32x16_bf16 v[64:79], v[192:195], v[214:217], v[64:79]
	s_add_u32 m0, s98, 0x14000
	v_mfma_f32_32x32x16_bf16 v[48:63], v[196:199], v[200:203], v[48:63]
	global_load_lds_dwordx4 v[164:165], off
	v_mfma_f32_32x32x16_bf16 v[32:47], v[196:199], v[206:209], v[32:47]
	s_add_u32 m0, s98, 0x16000
	v_mfma_f32_32x32x16_bf16 v[16:31], v[196:199], v[210:213], v[16:31]
	global_load_lds_dwordx4 v[166:167], off
	v_mfma_f32_32x32x16_bf16 v[0:15], v[196:199], v[214:217], v[0:15]
	v_lshl_add_u64 v[160:161], v[160:161], 0, 64
	v_lshl_add_u64 v[162:163], v[162:163], 0, 64
	v_lshl_add_u64 v[164:165], v[164:165], 0, 64
	v_lshl_add_u64 v[166:167], v[166:167], 0, 64
	s_waitcnt lgkmcnt(0)
	v_mfma_f32_32x32x16_bf16 v[112:127], v[128:131], v[136:139], v[112:127]
	v_mfma_f32_32x32x16_bf16 v[96:111], v[128:131], v[140:143], v[96:111]
	ds_read_b128 v[192:195], v253 offset:32768
	ds_read_b128 v[196:199], v253 offset:34816
	v_mfma_f32_32x32x16_bf16 v[80:95], v[128:131], v[144:147], v[80:95]
	ds_read_b128 v[200:203], v255 offset:49152
	ds_read_b128 v[206:209], v255 offset:51200
	v_mfma_f32_32x32x16_bf16 v[64:79], v[128:131], v[148:151], v[64:79]
	ds_read_b128 v[210:213], v255 offset:53248
	ds_read_b128 v[214:217], v255 offset:55296
	v_mfma_f32_32x32x16_bf16 v[48:63], v[132:135], v[136:139], v[48:63]
	v_mfma_f32_32x32x16_bf16 v[32:47], v[132:135], v[140:143], v[32:47]
	v_mfma_f32_32x32x16_bf16 v[16:31], v[132:135], v[144:147], v[16:31]
	v_mfma_f32_32x32x16_bf16 v[0:15], v[132:135], v[148:151], v[0:15]
	v_xor_b32_e32 v253, 0x10000, v253
	v_xor_b32_e32 v255, 0x10000, v255
	s_waitcnt vmcnt(8)
	s_waitcnt lgkmcnt(0)
	s_mov_b32 s99, 20
.Lmy_gemm_i3_loop:
	s_barrier
	ds_read_b128 v[128:131], v154
	ds_read_b128 v[132:135], v154 offset:2048
	ds_read_b128 v[136:139], v254 offset:16384
	ds_read_b128 v[140:143], v254 offset:18432
	ds_read_b128 v[144:147], v254 offset:20480
	ds_read_b128 v[148:151], v254 offset:22528
	s_add_u32 m0, s98, 0x18000
	v_mfma_f32_32x32x16_bf16 v[112:127], v[192:195], v[200:203], v[112:127]
	global_load_lds_dwordx4 v[160:161], off
	v_mfma_f32_32x32x16_bf16 v[96:111], v[192:195], v[206:209], v[96:111]
	s_add_u32 m0, s98, 0x1a000
	v_mfma_f32_32x32x16_bf16 v[80:95], v[192:195], v[210:213], v[80:95]
	global_load_lds_dwordx4 v[162:163], off
	v_mfma_f32_32x32x16_bf16 v[64:79], v[192:195], v[214:217], v[64:79]
	s_add_u32 m0, s98, 0x1c000
	v_mfma_f32_32x32x16_bf16 v[48:63], v[196:199], v[200:203], v[48:63]
	global_load_lds_dwordx4 v[164:165], off
	v_mfma_f32_32x32x16_bf16 v[32:47], v[196:199], v[206:209], v[32:47]
	s_add_u32 m0, s98, 0x1e000
	v_mfma_f32_32x32x16_bf16 v[16:31], v[196:199], v[210:213], v[16:31]
	global_load_lds_dwordx4 v[166:167], off
	v_mfma_f32_32x32x16_bf16 v[0:15], v[196:199], v[214:217], v[0:15]
	v_lshl_add_u64 v[160:161], v[160:161], 0, 64
	v_lshl_add_u64 v[162:163], v[162:163], 0, 64
	v_lshl_add_u64 v[164:165], v[164:165], 0, 64
	v_lshl_add_u64 v[166:167], v[166:167], 0, 64
	s_waitcnt lgkmcnt(0)
	v_mfma_f32_32x32x16_bf16 v[112:127], v[128:131], v[136:139], v[112:127]
	v_mfma_f32_32x32x16_bf16 v[96:111], v[128:131], v[140:143], v[96:111]
	ds_read_b128 v[192:195], v253
	ds_read_b128 v[196:199], v253 offset:2048
	v_mfma_f32_32x32x16_bf16 v[80:95], v[128:131], v[144:147], v[80:95]
	ds_read_b128 v[200:203], v255 offset:16384
	ds_read_b128 v[206:209], v255 offset:18432
	v_mfma_f32_32x32x16_bf16 v[64:79], v[128:131], v[148:151], v[64:79]
	ds_read_b128 v[210:213], v255 offset:20480
	ds_read_b128 v[214:217], v255 offset:22528
	v_mfma_f32_32x32x16_bf16 v[48:63], v[132:135], v[136:139], v[48:63]
	v_mfma_f32_32x32x16_bf16 v[32:47], v[132:135], v[140:143], v[32:47]
	v_mfma_f32_32x32x16_bf16 v[16:31], v[132:135], v[144:147], v[16:31]
	v_mfma_f32_32x32x16_bf16 v[0:15], v[132:135], v[148:151], v[0:15]
	s_waitcnt vmcnt(8)
	s_waitcnt lgkmcnt(0)
	s_barrier
; #define LGKM0_BAR asm volatile("s_waitcnt lgkmcnt(0)\n\ts_barrier" ::: "memory");
; __device__ __forceinline__ void gemm256_tile(const u16* Ab, int lda, const u16* Bb, int ldb, int K, char* smem,
;                                              f32x16 (&acc)[2][4]) {
;     ...
;     for (int s = 0; s < nks; ++s) {
;       const int q = s & 3;
;       G_MMA(afA, bfA)
;       __builtin_amdgcn_sched_barrier(0);
;       LGKM0_BAR
;       G_FRAGS(afB, bfB, q, fo1)
;       __builtin_amdgcn_sched_barrier(0);
;       LGKM0_BAR
;       G_MMA(afB, bfB)
;       __builtin_amdgcn_sched_barrier(0);
;       G_WAIT_BAR(s)
;       if (s + 4 < nks) DMA_STAGE(s + 4)
;       if (s + 1 < nks) G_FRAGS(afA, bfA, (s + 1) & 3, fo0)
;       __builtin_amdgcn_sched_barrier(0);
;       LGKM0_BAR
;     }
	ds_read_b128 v[128:131], v154 offset:32768
	ds_read_b128 v[132:135], v154 offset:34816
	ds_read_b128 v[136:139], v254 offset:49152
	ds_read_b128 v[140:143], v254 offset:51200
	ds_read_b128 v[144:147], v254 offset:53248
	ds_read_b128 v[148:151], v254 offset:55296
	v_xor_b32_e32 v154, 0x10000, v154
	v_xor_b32_e32 v254, 0x10000, v254
	s_add_u32 m0, s98, 0x0
	v_mfma_f32_32x32x16_bf16 v[112:127], v[192:195], v[200:203], v[112:127]
	global_load_lds_dwordx4 v[160:161], off
	v_mfma_f32_32x32x16_bf16 v[96:111], v[192:195], v[206:209], v[96:111]
	s_add_u32 m0, s98, 0x2000
	v_mfma_f32_32x32x16_bf16 v[80:95], v[192:195], v[210:213], v[80:95]
	global_load_lds_dwordx4 v[162:163], off
	v_mfma_f32_32x32x16_bf16 v[64:79], v[192:195], v[214:217], v[64:79]
	s_add_u32 m0, s98, 0x4000
	v_mfma_f32_32x32x16_bf16 v[48:63], v[196:199], v[200:203], v[48:63]
	global_load_lds_dwordx4 v[164:165], off
	v_mfma_f32_32x32x16_bf16 v[32:47], v[196:199], v[206:209], v[32:47]
	s_add_u32 m0, s98, 0x6000
	v_mfma_f32_32x32x16_bf16 v[16:31], v[196:199], v[210:213], v[16:31]
	global_load_lds_dwordx4 v[166:167], off
	v_mfma_f32_32x32x16_bf16 v[0:15], v[196:199], v[214:217], v[0:15]
	v_lshl_add_u64 v[160:161], v[160:161], 0, 64
	v_lshl_add_u64 v[162:163], v[162:163], 0, 64
	v_lshl_add_u64 v[164:165], v[164:165], 0, 64
	v_lshl_add_u64 v[166:167], v[166:167], 0, 64
	s_waitcnt lgkmcnt(0)
	v_mfma_f32_32x32x16_bf16 v[112:127], v[128:131], v[136:139], v[112:127]
	v_mfma_f32_32x32x16_bf16 v[96:111], v[128:131], v[140:143], v[96:111]
	ds_read_b128 v[192:195], v253 offset:32768
	ds_read_b128 v[196:199], v253 offset:34816
	v_mfma_f32_32x32x16_bf16 v[80:95], v[128:131], v[144:147], v[80:95]
	ds_read_b128 v[200:203], v255 offset:49152
	ds_read_b128 v[206:209], v255 offset:51200
	v_mfma_f32_32x32x16_bf16 v[64:79], v[128:131], v[148:151], v[64:79]
	ds_read_b128 v[210:213], v255 offset:53248
	ds_read_b128 v[214:217], v255 offset:55296
	v_mfma_f32_32x32x16_bf16 v[48:63], v[132:135], v[136:139], v[48:63]
	v_mfma_f32_32x32x16_bf16 v[32:47], v[132:135], v[140:143], v[32:47]
	v_mfma_f32_32x32x16_bf16 v[16:31], v[132:135], v[144:147], v[16:31]
	v_mfma_f32_32x32x16_bf16 v[0:15], v[132:135], v[148:151], v[0:15]
	v_xor_b32_e32 v253, 0x10000, v253
	v_xor_b32_e32 v255, 0x10000, v255
	s_waitcnt vmcnt(8)
	s_waitcnt lgkmcnt(0)
	s_barrier
	ds_read_b128 v[128:131], v154
	ds_read_b128 v[132:135], v154 offset:2048
	ds_read_b128 v[136:139], v254 offset:16384
	ds_read_b128 v[140:143], v254 offset:18432
	ds_read_b128 v[144:147], v254 offset:20480
	ds_read_b128 v[148:151], v254 offset:22528
	s_add_u32 m0, s98, 0x8000
	v_mfma_f32_32x32x16_bf16 v[112:127], v[192:195], v[200:203], v[112:127]
	global_load_lds_dwordx4 v[160:161], off
	v_mfma_f32_32x32x16_bf16 v[96:111], v[192:195], v[206:209], v[96:111]
	s_add_u32 m0, s98, 0xa000
	v_mfma_f32_32x32x16_bf16 v[80:95], v[192:195], v[210:213], v[80:95]
	global_load_lds_dwordx4 v[162:163], off
	v_mfma_f32_32x32x16_bf16 v[64:79], v[192:195], v[214:217], v[64:79]
	s_add_u32 m0, s98, 0xc000
	v_mfma_f32_32x32x16_bf16 v[48:63], v[196:199], v[200:203], v[48:63]
	global_load_lds_dwordx4 v[164:165], off
	v_mfma_f32_32x32x16_bf16 v[32:47], v[196:199], v[206:209], v[32:47]
	s_add_u32 m0, s98, 0xe000
	v_mfma_f32_32x32x16_bf16 v[16:31], v[196:199], v[210:213], v[16:31]
	global_load_lds_dwordx4 v[166:167], off
	v_mfma_f32_32x32x16_bf16 v[0:15], v[196:199], v[214:217], v[0:15]
	v_lshl_add_u64 v[160:161], v[160:161], 0, 64
	v_lshl_add_u64 v[162:163], v[162:163], 0, 64
	v_lshl_add_u64 v[164:165], v[164:165], 0, 64
	v_lshl_add_u64 v[166:167], v[166:167], 0, 64
	s_waitcnt lgkmcnt(0)
	v_mfma_f32_32x32x16_bf16 v[112:127], v[128:131], v[136:139], v[112:127]
	v_mfma_f32_32x32x16_bf16 v[96:111], v[128:131], v[140:143], v[96:111]
	ds_read_b128 v[192:195], v253
	ds_read_b128 v[196:199], v253 offset:2048
	v_mfma_f32_32x32x16_bf16 v[80:95], v[128:131], v[144:147], v[80:95]
	ds_read_b128 v[200:203], v255 offset:16384
	ds_read_b128 v[206:209], v255 offset:18432
	v_mfma_f32_32x32x16_bf16 v[64:79], v[128:131], v[148:151], v[64:79]
	ds_read_b128 v[210:213], v255 offset:20480
	ds_read_b128 v[214:217], v255 offset:22528
	v_mfma_f32_32x32x16_bf16 v[48:63], v[132:135], v[136:139], v[48:63]
	v_mfma_f32_32x32x16_bf16 v[32:47], v[132:135], v[140:143], v[32:47]
	v_mfma_f32_32x32x16_bf16 v[16:31], v[132:135], v[144:147], v[16:31]
	v_mfma_f32_32x32x16_bf16 v[0:15], v[132:135], v[148:151], v[0:15]
	s_waitcnt vmcnt(8)
	s_waitcnt lgkmcnt(0)
	s_barrier
; #define LGKM0_BAR asm volatile("s_waitcnt lgkmcnt(0)\n\ts_barrier" ::: "memory");
; __device__ __forceinline__ void gemm256_tile(const u16* Ab, int lda, const u16* Bb, int ldb, int K, char* smem,
;                                              f32x16 (&acc)[2][4]) {
;     ...
;     for (int s = 0; s < nks; ++s) {
;       const int q = s & 3;
;       G_MMA(afA, bfA)
;       __builtin_amdgcn_sched_barrier(0);
;       LGKM0_BAR
;       G_FRAGS(afB, bfB, q, fo1)
;       __builtin_amdgcn_sched_barrier(0);
;       LGKM0_BAR
;       G_MMA(afB, bfB)
;       __builtin_amdgcn_sched_barrier(0);
;       G_WAIT_BAR(s)
;       if (s + 4 < nks) DMA_STAGE(s + 4)
;       if (s + 1 < nks) G_FRAGS(afA, bfA, (s + 1) & 3, fo0)
;       __builtin_amdgcn_sched_barrier(0);
;       LGKM0_BAR
;     }
	ds_read_b128 v[128:131], v154 offset:32768
	ds_read_b128 v[132:135], v154 offset:34816
	ds_read_b128 v[136:139], v254 offset:49152
	ds_read_b128 v[140:143], v254 offset:51200
	ds_read_b128 v[144:147], v254 offset:53248
	ds_read_b128 v[148:151], v254 offset:55296
	v_xor_b32_e32 v154, 0x10000, v154
	v_xor_b32_e32 v254, 0x10000, v254
	s_add_u32 m0, s98, 0x10000
	v_mfma_f32_32x32x16_bf16 v[112:127], v[192:195], v[200:203], v[112:127]
	global_load_lds_dwordx4 v[160:161], off
	v_mfma_f32_32x32x16_bf16 v[96:111], v[192:195], v[206:209], v[96:111]
	s_add_u32 m0, s98, 0x12000
	v_mfma_f32_32x32x16_bf16 v[80:95], v[192:195], v[210:213], v[80:95]
	global_load_lds_dwordx4 v[162:163], off
	v_mfma_f32_32x32x16_bf16 v[64:79], v[192:195], v[214:217], v[64:79]
	s_add_u32 m0, s98, 0x14000
	v_mfma_f32_32x32x16_bf16 v[48:63], v[196:199], v[200:203], v[48:63]
	global_load_lds_dwordx4 v[164:165], off
	v_mfma_f32_32x32x16_bf16 v[32:47], v[196:199], v[206:209], v[32:47]
	s_add_u32 m0, s98, 0x16000
	v_mfma_f32_32x32x16_bf16 v[16:31], v[196:199], v[210:213], v[16:31]
	global_load_lds_dwordx4 v[166:167], off
	v_mfma_f32_32x32x16_bf16 v[0:15], v[196:199], v[214:217], v[0:15]
	v_lshl_add_u64 v[160:161], v[160:161], 0, 64
	v_lshl_add_u64 v[162:163], v[162:163], 0, 64
	v_lshl_add_u64 v[164:165], v[164:165], 0, 64
	v_lshl_add_u64 v[166:167], v[166:167], 0, 64
	s_waitcnt lgkmcnt(0)
	v_mfma_f32_32x32x16_bf16 v[112:127], v[128:131], v[136:139], v[112:127]
	v_mfma_f32_32x32x16_bf16 v[96:111], v[128:131], v[140:143], v[96:111]
	ds_read_b128 v[192:195], v253 offset:32768
	ds_read_b128 v[196:199], v253 offset:34816
	v_mfma_f32_32x32x16_bf16 v[80:95], v[128:131], v[144:147], v[80:95]
	ds_read_b128 v[200:203], v255 offset:49152
	ds_read_b128 v[206:209], v255 offset:51200
	v_mfma_f32_32x32x16_bf16 v[64:79], v[128:131], v[148:151], v[64:79]
	ds_read_b128 v[210:213], v255 offset:53248
	ds_read_b128 v[214:217], v255 offset:55296
	v_mfma_f32_32x32x16_bf16 v[48:63], v[132:135], v[136:139], v[48:63]
	v_mfma_f32_32x32x16_bf16 v[32:47], v[132:135], v[140:143], v[32:47]
	v_mfma_f32_32x32x16_bf16 v[16:31], v[132:135], v[144:147], v[16:31]
	v_mfma_f32_32x32x16_bf16 v[0:15], v[132:135], v[148:151], v[0:15]
	v_xor_b32_e32 v253, 0x10000, v253
	v_xor_b32_e32 v255, 0x10000, v255
	s_waitcnt vmcnt(8)
	s_waitcnt lgkmcnt(0)
	s_sub_u32 s99, s99, 1
	s_cmp_lg_u32 s99, 0
	s_cbranch_scc1 .Lmy_gemm_i3_loop
	s_barrier
	ds_read_b128 v[128:131], v154
	ds_read_b128 v[132:135], v154 offset:2048
	ds_read_b128 v[136:139], v254 offset:16384
	ds_read_b128 v[140:143], v254 offset:18432
	ds_read_b128 v[144:147], v254 offset:20480
	ds_read_b128 v[148:151], v254 offset:22528
	s_add_u32 m0, s98, 0x18000
	v_mfma_f32_32x32x16_bf16 v[112:127], v[192:195], v[200:203], v[112:127]
	global_load_lds_dwordx4 v[160:161], off
	v_mfma_f32_32x32x16_bf16 v[96:111], v[192:195], v[206:209], v[96:111]
	s_add_u32 m0, s98, 0x1a000
	v_mfma_f32_32x32x16_bf16 v[80:95], v[192:195], v[210:213], v[80:95]
	global_load_lds_dwordx4 v[162:163], off
	v_mfma_f32_32x32x16_bf16 v[64:79], v[192:195], v[214:217], v[64:79]
	s_add_u32 m0, s98, 0x1c000
	v_mfma_f32_32x32x16_bf16 v[48:63], v[196:199], v[200:203], v[48:63]
	global_load_lds_dwordx4 v[164:165], off
	v_mfma_f32_32x32x16_bf16 v[32:47], v[196:199], v[206:209], v[32:47]
	s_add_u32 m0, s98, 0x1e000
	v_mfma_f32_32x32x16_bf16 v[16:31], v[196:199], v[210:213], v[16:31]
	global_load_lds_dwordx4 v[166:167], off
	v_mfma_f32_32x32x16_bf16 v[0:15], v[196:199], v[214:217], v[0:15]
	v_lshl_add_u64 v[160:161], v[160:161], 0, 64
	v_lshl_add_u64 v[162:163], v[162:163], 0, 64
	v_lshl_add_u64 v[164:165], v[164:165], 0, 64
	v_lshl_add_u64 v[166:167], v[166:167], 0, 64
	s_waitcnt lgkmcnt(0)
	v_mfma_f32_32x32x16_bf16 v[112:127], v[128:131], v[136:139], v[112:127]
	v_mfma_f32_32x32x16_bf16 v[96:111], v[128:131], v[140:143], v[96:111]
	ds_read_b128 v[192:195], v253
	ds_read_b128 v[196:199], v253 offset:2048
	v_mfma_f32_32x32x16_bf16 v[80:95], v[128:131], v[144:147], v[80:95]
	ds_read_b128 v[200:203], v255 offset:16384
	ds_read_b128 v[206:209], v255 offset:18432
	v_mfma_f32_32x32x16_bf16 v[64:79], v[128:131], v[148:151], v[64:79]
	ds_read_b128 v[210:213], v255 offset:20480
	ds_read_b128 v[214:217], v255 offset:22528
	v_mfma_f32_32x32x16_bf16 v[48:63], v[132:135], v[136:139], v[48:63]
	v_mfma_f32_32x32x16_bf16 v[32:47], v[132:135], v[140:143], v[32:47]
	v_mfma_f32_32x32x16_bf16 v[16:31], v[132:135], v[144:147], v[16:31]
	v_mfma_f32_32x32x16_bf16 v[0:15], v[132:135], v[148:151], v[0:15]
	s_waitcnt vmcnt(8)
	s_waitcnt lgkmcnt(0)
	s_barrier
; #define LGKM0_BAR asm volatile("s_waitcnt lgkmcnt(0)\n\ts_barrier" ::: "memory");
; __device__ __forceinline__ void gemm256_tile(const u16* Ab, int lda, const u16* Bb, int ldb, int K, char* smem,
;                                              f32x16 (&acc)[2][4]) {
;     ...
;     for (int s = 0; s < nks; ++s) {
;       const int q = s & 3;
;       G_MMA(afA, bfA)
;       __builtin_amdgcn_sched_barrier(0);
;       LGKM0_BAR
;       G_FRAGS(afB, bfB, q, fo1)
;       __builtin_amdgcn_sched_barrier(0);
;       LGKM0_BAR
;       G_MMA(afB, bfB)
;       __builtin_amdgcn_sched_barrier(0);
;       G_WAIT_BAR(s)
;       if (s + 4 < nks) DMA_STAGE(s + 4)
;       if (s + 1 < nks) G_FRAGS(afA, bfA, (s + 1) & 3, fo0)
;       __builtin_amdgcn_sched_barrier(0);
;       LGKM0_BAR
;     }
;   } else {
;     LGKM0_BAR
;     for (int s = 0; s < nks; ++s) {
;       const int q = s & 3;
;       G_FRAGS(afA, bfA, q, fo0)
;       __builtin_amdgcn_sched_barrier(0);
;       LGKM0_BAR
;       G_MMA(afA, bfA)
;       __builtin_amdgcn_sched_barrier(0);
;       LGKM0_BAR
;       G_FRAGS(afB, bfB, q, fo1)
;       __builtin_amdgcn_sched_barrier(0);
;       G_WAIT_BAR(s)
;       G_MMA(afB, bfB)
;       __builtin_amdgcn_sched_barrier(0);
;       if (s + 4 < nks) DMA_STAGE(s + 4)
;       __builtin_amdgcn_sched_barrier(0);
;       LGKM0_BAR
;     }
;   }
;     ...
;   __syncthreads();
	ds_read_b128 v[128:131], v154 offset:32768
	ds_read_b128 v[132:135], v154 offset:34816
	ds_read_b128 v[136:139], v254 offset:49152
	ds_read_b128 v[140:143], v254 offset:51200
	ds_read_b128 v[144:147], v254 offset:53248
	ds_read_b128 v[148:151], v254 offset:55296
	v_xor_b32_e32 v154, 0x10000, v154
	v_xor_b32_e32 v254, 0x10000, v254
	v_mfma_f32_32x32x16_bf16 v[112:127], v[192:195], v[200:203], v[112:127]
	v_mfma_f32_32x32x16_bf16 v[96:111], v[192:195], v[206:209], v[96:111]
	v_mfma_f32_32x32x16_bf16 v[80:95], v[192:195], v[210:213], v[80:95]
	v_mfma_f32_32x32x16_bf16 v[64:79], v[192:195], v[214:217], v[64:79]
	v_mfma_f32_32x32x16_bf16 v[48:63], v[196:199], v[200:203], v[48:63]
	v_mfma_f32_32x32x16_bf16 v[32:47], v[196:199], v[206:209], v[32:47]
	v_mfma_f32_32x32x16_bf16 v[16:31], v[196:199], v[210:213], v[16:31]
	v_mfma_f32_32x32x16_bf16 v[0:15], v[196:199], v[214:217], v[0:15]
	s_waitcnt lgkmcnt(0)
	v_mfma_f32_32x32x16_bf16 v[112:127], v[128:131], v[136:139], v[112:127]
	v_mfma_f32_32x32x16_bf16 v[96:111], v[128:131], v[140:143], v[96:111]
	ds_read_b128 v[192:195], v253 offset:32768
	ds_read_b128 v[196:199], v253 offset:34816
	v_mfma_f32_32x32x16_bf16 v[80:95], v[128:131], v[144:147], v[80:95]
	ds_read_b128 v[200:203], v255 offset:49152
	ds_read_b128 v[206:209], v255 offset:51200
	v_mfma_f32_32x32x16_bf16 v[64:79], v[128:131], v[148:151], v[64:79]
	ds_read_b128 v[210:213], v255 offset:53248
	ds_read_b128 v[214:217], v255 offset:55296
	v_mfma_f32_32x32x16_bf16 v[48:63], v[132:135], v[136:139], v[48:63]
	v_mfma_f32_32x32x16_bf16 v[32:47], v[132:135], v[140:143], v[32:47]
	v_mfma_f32_32x32x16_bf16 v[16:31], v[132:135], v[144:147], v[16:31]
	v_mfma_f32_32x32x16_bf16 v[0:15], v[132:135], v[148:151], v[0:15]
	v_xor_b32_e32 v253, 0x10000, v253
	v_xor_b32_e32 v255, 0x10000, v255
	s_waitcnt vmcnt(4)
	s_waitcnt lgkmcnt(0)
	s_barrier
	ds_read_b128 v[128:131], v154
	ds_read_b128 v[132:135], v154 offset:2048
	ds_read_b128 v[136:139], v254 offset:16384
	ds_read_b128 v[140:143], v254 offset:18432
	ds_read_b128 v[144:147], v254 offset:20480
	ds_read_b128 v[148:151], v254 offset:22528
	v_mfma_f32_32x32x16_bf16 v[112:127], v[192:195], v[200:203], v[112:127]
	v_mfma_f32_32x32x16_bf16 v[96:111], v[192:195], v[206:209], v[96:111]
	v_mfma_f32_32x32x16_bf16 v[80:95], v[192:195], v[210:213], v[80:95]
	v_mfma_f32_32x32x16_bf16 v[64:79], v[192:195], v[214:217], v[64:79]
	v_mfma_f32_32x32x16_bf16 v[48:63], v[196:199], v[200:203], v[48:63]
	v_mfma_f32_32x32x16_bf16 v[32:47], v[196:199], v[206:209], v[32:47]
	v_mfma_f32_32x32x16_bf16 v[16:31], v[196:199], v[210:213], v[16:31]
	v_mfma_f32_32x32x16_bf16 v[0:15], v[196:199], v[214:217], v[0:15]
	s_waitcnt lgkmcnt(0)
	v_mfma_f32_32x32x16_bf16 v[112:127], v[128:131], v[136:139], v[112:127]
	v_mfma_f32_32x32x16_bf16 v[96:111], v[128:131], v[140:143], v[96:111]
	ds_read_b128 v[192:195], v253
	ds_read_b128 v[196:199], v253 offset:2048
	v_mfma_f32_32x32x16_bf16 v[80:95], v[128:131], v[144:147], v[80:95]
	ds_read_b128 v[200:203], v255 offset:16384
	ds_read_b128 v[206:209], v255 offset:18432
	v_mfma_f32_32x32x16_bf16 v[64:79], v[128:131], v[148:151], v[64:79]
	ds_read_b128 v[210:213], v255 offset:20480
	ds_read_b128 v[214:217], v255 offset:22528
	v_mfma_f32_32x32x16_bf16 v[48:63], v[132:135], v[136:139], v[48:63]
	v_mfma_f32_32x32x16_bf16 v[32:47], v[132:135], v[140:143], v[32:47]
	v_mfma_f32_32x32x16_bf16 v[16:31], v[132:135], v[144:147], v[16:31]
	v_mfma_f32_32x32x16_bf16 v[0:15], v[132:135], v[148:151], v[0:15]
	s_waitcnt vmcnt(0)
	s_waitcnt lgkmcnt(0)
	s_barrier
	ds_read_b128 v[128:131], v154 offset:32768
	ds_read_b128 v[132:135], v154 offset:34816
	ds_read_b128 v[136:139], v254 offset:49152
	ds_read_b128 v[140:143], v254 offset:51200
	ds_read_b128 v[144:147], v254 offset:53248
	ds_read_b128 v[148:151], v254 offset:55296
	v_xor_b32_e32 v154, 0x10000, v154
	v_xor_b32_e32 v254, 0x10000, v254
	v_mfma_f32_32x32x16_bf16 v[112:127], v[192:195], v[200:203], v[112:127]
	v_mfma_f32_32x32x16_bf16 v[96:111], v[192:195], v[206:209], v[96:111]
	v_mfma_f32_32x32x16_bf16 v[80:95], v[192:195], v[210:213], v[80:95]
	v_mfma_f32_32x32x16_bf16 v[64:79], v[192:195], v[214:217], v[64:79]
	v_mfma_f32_32x32x16_bf16 v[48:63], v[196:199], v[200:203], v[48:63]
	v_mfma_f32_32x32x16_bf16 v[32:47], v[196:199], v[206:209], v[32:47]
	v_mfma_f32_32x32x16_bf16 v[16:31], v[196:199], v[210:213], v[16:31]
	v_mfma_f32_32x32x16_bf16 v[0:15], v[196:199], v[214:217], v[0:15]
	s_waitcnt lgkmcnt(0)
	v_mfma_f32_32x32x16_bf16 v[112:127], v[128:131], v[136:139], v[112:127]
	v_mfma_f32_32x32x16_bf16 v[96:111], v[128:131], v[140:143], v[96:111]
	ds_read_b128 v[192:195], v253 offset:32768
	ds_read_b128 v[196:199], v253 offset:34816
	v_mfma_f32_32x32x16_bf16 v[80:95], v[128:131], v[144:147], v[80:95]
	ds_read_b128 v[200:203], v255 offset:49152
	ds_read_b128 v[206:209], v255 offset:51200
	v_mfma_f32_32x32x16_bf16 v[64:79], v[128:131], v[148:151], v[64:79]
	ds_read_b128 v[210:213], v255 offset:53248
	ds_read_b128 v[214:217], v255 offset:55296
	v_mfma_f32_32x32x16_bf16 v[48:63], v[132:135], v[136:139], v[48:63]
	v_mfma_f32_32x32x16_bf16 v[32:47], v[132:135], v[140:143], v[32:47]
	v_mfma_f32_32x32x16_bf16 v[16:31], v[132:135], v[144:147], v[16:31]
	v_mfma_f32_32x32x16_bf16 v[0:15], v[132:135], v[148:151], v[0:15]
	v_xor_b32_e32 v253, 0x10000, v253
	v_xor_b32_e32 v255, 0x10000, v255
	s_waitcnt lgkmcnt(0)
	v_mfma_f32_32x32x16_bf16 v[112:127], v[192:195], v[200:203], v[112:127]
	v_mfma_f32_32x32x16_bf16 v[96:111], v[192:195], v[206:209], v[96:111]
	v_mfma_f32_32x32x16_bf16 v[80:95], v[192:195], v[210:213], v[80:95]
	v_mfma_f32_32x32x16_bf16 v[64:79], v[192:195], v[214:217], v[64:79]
	v_mfma_f32_32x32x16_bf16 v[48:63], v[196:199], v[200:203], v[48:63]
	v_mfma_f32_32x32x16_bf16 v[32:47], v[196:199], v[206:209], v[32:47]
	v_mfma_f32_32x32x16_bf16 v[16:31], v[196:199], v[210:213], v[16:31]
	v_mfma_f32_32x32x16_bf16 v[0:15], v[196:199], v[214:217], v[0:15]
	s_nop 15
	s_ashr_i32 s7, s6, 31
	s_branch .LBB0_1144

; #define LGKM0_BAR asm volatile("s_waitcnt lgkmcnt(0)\n\ts_barrier" ::: "memory");
; __device__ __forceinline__ void gemm256_tile(const u16* Ab, int lda, const u16* Bb, int ldb, int K, char* smem,
;                                              f32x16 (&acc)[2][4]) {
;     ...
;   const int xsw = (lane >> 2) & 3, hh = lane >> 5;
;   const unsigned fo0 = (unsigned)((hh ^ xsw) * 16), fo1 = (unsigned)(((2 + hh) ^ xsw) * 16);
;   const unsigned fa = (unsigned)((wm * 64 + (lane & 31)) * 64);
;   const unsigned fb = (unsigned)(16384 + (wn * 128 + (lane & 31)) * 64);
;     ...
;   asm volatile("s_waitcnt vmcnt(0)" ::: "memory");
;   const bool h1 = __builtin_amdgcn_readfirstlane(wid) >= 4;
;     ...
;   DMA_STAGE(0)
;   if (nks > 1) DMA_STAGE(1)
;   if (nks > 2) DMA_STAGE(2)
;   if (nks > 3) DMA_STAGE(3)
;   if (nks > 3)      asm volatile("s_waitcnt vmcnt(12)\n\ts_barrier" ::: "memory");
;   else if (nks > 2) asm volatile("s_waitcnt vmcnt(8)\n\ts_barrier" ::: "memory");
;   else if (nks > 1) asm volatile("s_waitcnt vmcnt(4)\n\ts_barrier" ::: "memory");
;   else              asm volatile("s_waitcnt vmcnt(0)\n\ts_barrier" ::: "memory");
;   bf16x8 afA[2], bfA[4], afB[2], bfB[4];
;   if (!h1) {
;     G_FRAGS(afA, bfA, 0, fo0)
;     LGKM0_BAR
;     for (int s = 0; s < nks; ++s) {
;       const int q = s & 3;
;       G_MMA(afA, bfA)
;       __builtin_amdgcn_sched_barrier(0);
;       LGKM0_BAR
;       G_FRAGS(afB, bfB, q, fo1)
;       __builtin_amdgcn_sched_barrier(0);
;       LGKM0_BAR
;       G_MMA(afB, bfB)
;       __builtin_amdgcn_sched_barrier(0);
;       G_WAIT_BAR(s)
;       if (s + 4 < nks) DMA_STAGE(s + 4)
;       if (s + 1 < nks) G_FRAGS(afA, bfA, (s + 1) & 3, fo0)
;       __builtin_amdgcn_sched_barrier(0);
;       LGKM0_BAR
;     }
.LBB0_1395:
	v_lshrrev_b32_e32 v194, 6, v152
	v_bfe_u32 v195, v152, 2, 2
	v_readfirstlane_b32 s98, v194
	v_bfe_u32 v196, v152, 5, 1
	v_xor_b32_e32 v195, v196, v195
	v_lshlrev_b32_e32 v195, 4, v195
	v_xor_b32_e32 v196, 32, v195
	v_and_b32_e32 v197, 31, v152
	v_lshrrev_b32_e32 v198, 7, v152
	v_lshl_add_u32 v198, v198, 6, v197
	v_lshlrev_b32_e32 v198, 6, v198
	v_bfe_u32 v199, v152, 6, 1
	v_lshl_add_u32 v199, v199, 7, v197
	v_lshlrev_b32_e32 v199, 6, v199
	v_add3_u32 v154, v198, v195, 16
	v_add3_u32 v193, v198, v196, 16
	v_add3_u32 v202, v199, v195, 16
	v_add3_u32 v203, v199, v196, 16
	s_lshl_b32 s98, s98, 10
	s_add_u32 s98, s98, 16
	v_lshl_add_u64 v[164:165], 64, 2, v[164:165]
	v_lshl_add_u64 v[160:161], 64, 2, v[160:161]
	v_lshl_add_u64 v[166:167], 64, 2, v[166:167]
	v_lshl_add_u64 v[162:163], 64, 2, v[162:163]
	s_barrier
	ds_read_b128 v[128:131], v154
	ds_read_b128 v[132:135], v154 offset:2048
	ds_read_b128 v[136:139], v202 offset:16384
	ds_read_b128 v[140:143], v202 offset:18432
	ds_read_b128 v[144:147], v202 offset:20480
	ds_read_b128 v[148:151], v202 offset:22528
	s_waitcnt lgkmcnt(0)
	v_mfma_f32_32x32x16_bf16 v[112:127], v[128:131], v[136:139], 0
	v_mfma_f32_32x32x16_bf16 v[96:111], v[128:131], v[140:143], 0
	ds_read_b128 v[194:197], v193
	ds_read_b128 v[198:201], v193 offset:2048
	v_mfma_f32_32x32x16_bf16 v[80:95], v[128:131], v[144:147], 0
	ds_read_b128 v[206:209], v203 offset:16384
	ds_read_b128 v[210:213], v203 offset:18432
	v_mfma_f32_32x32x16_bf16 v[64:79], v[128:131], v[148:151], 0
	ds_read_b128 v[214:217], v203 offset:20480
	ds_read_b128 v[218:221], v203 offset:22528
	v_mfma_f32_32x32x16_bf16 v[48:63], v[132:135], v[136:139], 0
	v_mfma_f32_32x32x16_bf16 v[32:47], v[132:135], v[140:143], 0
	v_mfma_f32_32x32x16_bf16 v[16:31], v[132:135], v[144:147], 0
	v_mfma_f32_32x32x16_bf16 v[0:15], v[132:135], v[148:151], 0
	s_waitcnt vmcnt(8)
	s_waitcnt lgkmcnt(0)
	s_barrier
	ds_read_b128 v[128:131], v154 offset:32768
	ds_read_b128 v[132:135], v154 offset:34816
	ds_read_b128 v[136:139], v202 offset:49152
	ds_read_b128 v[140:143], v202 offset:51200
	ds_read_b128 v[144:147], v202 offset:53248
	ds_read_b128 v[148:151], v202 offset:55296
	v_xor_b32_e32 v154, 0x10000, v154
	v_xor_b32_e32 v202, 0x10000, v202
	s_add_u32 m0, s98, 0x0
	v_mfma_f32_32x32x16_bf16 v[112:127], v[194:197], v[206:209], v[112:127]
	global_load_lds_dwordx4 v[164:165], off
	v_mfma_f32_32x32x16_bf16 v[96:111], v[194:197], v[210:213], v[96:111]
	s_add_u32 m0, s98, 0x2000
	v_mfma_f32_32x32x16_bf16 v[80:95], v[194:197], v[214:217], v[80:95]
	global_load_lds_dwordx4 v[160:161], off
	v_mfma_f32_32x32x16_bf16 v[64:79], v[194:197], v[218:221], v[64:79]
	s_add_u32 m0, s98, 0x4000
	v_mfma_f32_32x32x16_bf16 v[48:63], v[198:201], v[206:209], v[48:63]
	global_load_lds_dwordx4 v[166:167], off
	v_mfma_f32_32x32x16_bf16 v[32:47], v[198:201], v[210:213], v[32:47]
	s_add_u32 m0, s98, 0x6000
	v_mfma_f32_32x32x16_bf16 v[16:31], v[198:201], v[214:217], v[16:31]
	global_load_lds_dwordx4 v[162:163], off
	v_mfma_f32_32x32x16_bf16 v[0:15], v[198:201], v[218:221], v[0:15]
	v_lshl_add_u64 v[164:165], v[164:165], 0, 64
	v_lshl_add_u64 v[160:161], v[160:161], 0, 64
	v_lshl_add_u64 v[166:167], v[166:167], 0, 64
	v_lshl_add_u64 v[162:163], v[162:163], 0, 64
	s_waitcnt lgkmcnt(0)
	v_mfma_f32_32x32x16_bf16 v[112:127], v[128:131], v[136:139], v[112:127]
	v_mfma_f32_32x32x16_bf16 v[96:111], v[128:131], v[140:143], v[96:111]
	ds_read_b128 v[194:197], v193 offset:32768
	ds_read_b128 v[198:201], v193 offset:34816
	v_mfma_f32_32x32x16_bf16 v[80:95], v[128:131], v[144:147], v[80:95]
	ds_read_b128 v[206:209], v203 offset:49152
	ds_read_b128 v[210:213], v203 offset:51200
	v_mfma_f32_32x32x16_bf16 v[64:79], v[128:131], v[148:151], v[64:79]
	ds_read_b128 v[214:217], v203 offset:53248
	ds_read_b128 v[218:221], v203 offset:55296
	v_mfma_f32_32x32x16_bf16 v[48:63], v[132:135], v[136:139], v[48:63]
	v_mfma_f32_32x32x16_bf16 v[32:47], v[132:135], v[140:143], v[32:47]
	v_mfma_f32_32x32x16_bf16 v[16:31], v[132:135], v[144:147], v[16:31]
	v_mfma_f32_32x32x16_bf16 v[0:15], v[132:135], v[148:151], v[0:15]
	v_xor_b32_e32 v193, 0x10000, v193
	v_xor_b32_e32 v203, 0x10000, v203
	s_waitcnt vmcnt(8)
	s_waitcnt lgkmcnt(0)
	s_barrier
	ds_read_b128 v[128:131], v154
	ds_read_b128 v[132:135], v154 offset:2048
	ds_read_b128 v[136:139], v202 offset:16384
	ds_read_b128 v[140:143], v202 offset:18432
	ds_read_b128 v[144:147], v202 offset:20480
	ds_read_b128 v[148:151], v202 offset:22528
	s_add_u32 m0, s98, 0x8000
	v_mfma_f32_32x32x16_bf16 v[112:127], v[194:197], v[206:209], v[112:127]
	global_load_lds_dwordx4 v[164:165], off
	v_mfma_f32_32x32x16_bf16 v[96:111], v[194:197], v[210:213], v[96:111]
	s_add_u32 m0, s98, 0xa000
	v_mfma_f32_32x32x16_bf16 v[80:95], v[194:197], v[214:217], v[80:95]
	global_load_lds_dwordx4 v[160:161], off
	v_mfma_f32_32x32x16_bf16 v[64:79], v[194:197], v[218:221], v[64:79]
	s_add_u32 m0, s98, 0xc000
	v_mfma_f32_32x32x16_bf16 v[48:63], v[198:201], v[206:209], v[48:63]
	global_load_lds_dwordx4 v[166:167], off
	v_mfma_f32_32x32x16_bf16 v[32:47], v[198:201], v[210:213], v[32:47]
	s_add_u32 m0, s98, 0xe000
	v_mfma_f32_32x32x16_bf16 v[16:31], v[198:201], v[214:217], v[16:31]
	global_load_lds_dwordx4 v[162:163], off
	v_mfma_f32_32x32x16_bf16 v[0:15], v[198:201], v[218:221], v[0:15]
	v_lshl_add_u64 v[164:165], v[164:165], 0, 64
	v_lshl_add_u64 v[160:161], v[160:161], 0, 64
	v_lshl_add_u64 v[166:167], v[166:167], 0, 64
	v_lshl_add_u64 v[162:163], v[162:163], 0, 64
	s_waitcnt lgkmcnt(0)
	v_mfma_f32_32x32x16_bf16 v[112:127], v[128:131], v[136:139], v[112:127]
	v_mfma_f32_32x32x16_bf16 v[96:111], v[128:131], v[140:143], v[96:111]
	ds_read_b128 v[194:197], v193
	ds_read_b128 v[198:201], v193 offset:2048
	v_mfma_f32_32x32x16_bf16 v[80:95], v[128:131], v[144:147], v[80:95]
	ds_read_b128 v[206:209], v203 offset:16384
	ds_read_b128 v[210:213], v203 offset:18432
	v_mfma_f32_32x32x16_bf16 v[64:79], v[128:131], v[148:151], v[64:79]
	ds_read_b128 v[214:217], v203 offset:20480
	ds_read_b128 v[218:221], v203 offset:22528
	v_mfma_f32_32x32x16_bf16 v[48:63], v[132:135], v[136:139], v[48:63]
	v_mfma_f32_32x32x16_bf16 v[32:47], v[132:135], v[140:143], v[32:47]
	v_mfma_f32_32x32x16_bf16 v[16:31], v[132:135], v[144:147], v[16:31]
	v_mfma_f32_32x32x16_bf16 v[0:15], v[132:135], v[148:151], v[0:15]
	s_waitcnt vmcnt(8)
	s_waitcnt lgkmcnt(0)
	s_barrier
; #define LGKM0_BAR asm volatile("s_waitcnt lgkmcnt(0)\n\ts_barrier" ::: "memory");
; __device__ __forceinline__ void gemm256_tile(const u16* Ab, int lda, const u16* Bb, int ldb, int K, char* smem,
;                                              f32x16 (&acc)[2][4]) {
;     ...
;     for (int s = 0; s < nks; ++s) {
;       const int q = s & 3;
;       G_MMA(afA, bfA)
;       __builtin_amdgcn_sched_barrier(0);
;       LGKM0_BAR
;       G_FRAGS(afB, bfB, q, fo1)
;       __builtin_amdgcn_sched_barrier(0);
;       LGKM0_BAR
;       G_MMA(afB, bfB)
;       __builtin_amdgcn_sched_barrier(0);
;       G_WAIT_BAR(s)
;       if (s + 4 < nks) DMA_STAGE(s + 4)
;       if (s + 1 < nks) G_FRAGS(afA, bfA, (s + 1) & 3, fo0)
;       __builtin_amdgcn_sched_barrier(0);
;       LGKM0_BAR
;     }
	ds_read_b128 v[128:131], v154 offset:32768
	ds_read_b128 v[132:135], v154 offset:34816
	ds_read_b128 v[136:139], v202 offset:49152
	ds_read_b128 v[140:143], v202 offset:51200
	ds_read_b128 v[144:147], v202 offset:53248
	ds_read_b128 v[148:151], v202 offset:55296
	v_xor_b32_e32 v154, 0x10000, v154
	v_xor_b32_e32 v202, 0x10000, v202
	s_add_u32 m0, s98, 0x10000
	v_mfma_f32_32x32x16_bf16 v[112:127], v[194:197], v[206:209], v[112:127]
	global_load_lds_dwordx4 v[164:165], off
	v_mfma_f32_32x32x16_bf16 v[96:111], v[194:197], v[210:213], v[96:111]
	s_add_u32 m0, s98, 0x12000
	v_mfma_f32_32x32x16_bf16 v[80:95], v[194:197], v[214:217], v[80:95]
	global_load_lds_dwordx4 v[160:161], off
	v_mfma_f32_32x32x16_bf16 v[64:79], v[194:197], v[218:221], v[64:79]
	s_add_u32 m0, s98, 0x14000
	v_mfma_f32_32x32x16_bf16 v[48:63], v[198:201], v[206:209], v[48:63]
	global_load_lds_dwordx4 v[166:167], off
	v_mfma_f32_32x32x16_bf16 v[32:47], v[198:201], v[210:213], v[32:47]
	s_add_u32 m0, s98, 0x16000
	v_mfma_f32_32x32x16_bf16 v[16:31], v[198:201], v[214:217], v[16:31]
	global_load_lds_dwordx4 v[162:163], off
	v_mfma_f32_32x32x16_bf16 v[0:15], v[198:201], v[218:221], v[0:15]
	v_lshl_add_u64 v[164:165], v[164:165], 0, 64
	v_lshl_add_u64 v[160:161], v[160:161], 0, 64
	v_lshl_add_u64 v[166:167], v[166:167], 0, 64
	v_lshl_add_u64 v[162:163], v[162:163], 0, 64
	s_waitcnt lgkmcnt(0)
	v_mfma_f32_32x32x16_bf16 v[112:127], v[128:131], v[136:139], v[112:127]
	v_mfma_f32_32x32x16_bf16 v[96:111], v[128:131], v[140:143], v[96:111]
	ds_read_b128 v[194:197], v193 offset:32768
	ds_read_b128 v[198:201], v193 offset:34816
	v_mfma_f32_32x32x16_bf16 v[80:95], v[128:131], v[144:147], v[80:95]
	ds_read_b128 v[206:209], v203 offset:49152
	ds_read_b128 v[210:213], v203 offset:51200
	v_mfma_f32_32x32x16_bf16 v[64:79], v[128:131], v[148:151], v[64:79]
	ds_read_b128 v[214:217], v203 offset:53248
	ds_read_b128 v[218:221], v203 offset:55296
	v_mfma_f32_32x32x16_bf16 v[48:63], v[132:135], v[136:139], v[48:63]
	v_mfma_f32_32x32x16_bf16 v[32:47], v[132:135], v[140:143], v[32:47]
	v_mfma_f32_32x32x16_bf16 v[16:31], v[132:135], v[144:147], v[16:31]
	v_mfma_f32_32x32x16_bf16 v[0:15], v[132:135], v[148:151], v[0:15]
	v_xor_b32_e32 v193, 0x10000, v193
	v_xor_b32_e32 v203, 0x10000, v203
	s_waitcnt vmcnt(8)
	s_waitcnt lgkmcnt(0)
	s_mov_b32 s99, 6
.Lmy_gemm_i4_loop:
	s_barrier
	ds_read_b128 v[128:131], v154
	ds_read_b128 v[132:135], v154 offset:2048
	ds_read_b128 v[136:139], v202 offset:16384
	ds_read_b128 v[140:143], v202 offset:18432
	ds_read_b128 v[144:147], v202 offset:20480
	ds_read_b128 v[148:151], v202 offset:22528
	s_add_u32 m0, s98, 0x18000
	v_mfma_f32_32x32x16_bf16 v[112:127], v[194:197], v[206:209], v[112:127]
	global_load_lds_dwordx4 v[164:165], off
	v_mfma_f32_32x32x16_bf16 v[96:111], v[194:197], v[210:213], v[96:111]
	s_add_u32 m0, s98, 0x1a000
	v_mfma_f32_32x32x16_bf16 v[80:95], v[194:197], v[214:217], v[80:95]
	global_load_lds_dwordx4 v[160:161], off
	v_mfma_f32_32x32x16_bf16 v[64:79], v[194:197], v[218:221], v[64:79]
	s_add_u32 m0, s98, 0x1c000
	v_mfma_f32_32x32x16_bf16 v[48:63], v[198:201], v[206:209], v[48:63]
	global_load_lds_dwordx4 v[166:167], off
	v_mfma_f32_32x32x16_bf16 v[32:47], v[198:201], v[210:213], v[32:47]
	s_add_u32 m0, s98, 0x1e000
	v_mfma_f32_32x32x16_bf16 v[16:31], v[198:201], v[214:217], v[16:31]
	global_load_lds_dwordx4 v[162:163], off
	v_mfma_f32_32x32x16_bf16 v[0:15], v[198:201], v[218:221], v[0:15]
	v_lshl_add_u64 v[164:165], v[164:165], 0, 64
	v_lshl_add_u64 v[160:161], v[160:161], 0, 64
	v_lshl_add_u64 v[166:167], v[166:167], 0, 64
	v_lshl_add_u64 v[162:163], v[162:163], 0, 64
	s_waitcnt lgkmcnt(0)
	v_mfma_f32_32x32x16_bf16 v[112:127], v[128:131], v[136:139], v[112:127]
	v_mfma_f32_32x32x16_bf16 v[96:111], v[128:131], v[140:143], v[96:111]
	ds_read_b128 v[194:197], v193
	ds_read_b128 v[198:201], v193 offset:2048
	v_mfma_f32_32x32x16_bf16 v[80:95], v[128:131], v[144:147], v[80:95]
	ds_read_b128 v[206:209], v203 offset:16384
	ds_read_b128 v[210:213], v203 offset:18432
	v_mfma_f32_32x32x16_bf16 v[64:79], v[128:131], v[148:151], v[64:79]
	ds_read_b128 v[214:217], v203 offset:20480
	ds_read_b128 v[218:221], v203 offset:22528
	v_mfma_f32_32x32x16_bf16 v[48:63], v[132:135], v[136:139], v[48:63]
	v_mfma_f32_32x32x16_bf16 v[32:47], v[132:135], v[140:143], v[32:47]
	v_mfma_f32_32x32x16_bf16 v[16:31], v[132:135], v[144:147], v[16:31]
	v_mfma_f32_32x32x16_bf16 v[0:15], v[132:135], v[148:151], v[0:15]
	s_waitcnt vmcnt(8)
	s_waitcnt lgkmcnt(0)
	s_barrier
; #define LGKM0_BAR asm volatile("s_waitcnt lgkmcnt(0)\n\ts_barrier" ::: "memory");
; __device__ __forceinline__ void gemm256_tile(const u16* Ab, int lda, const u16* Bb, int ldb, int K, char* smem,
;                                              f32x16 (&acc)[2][4]) {
;     ...
;     for (int s = 0; s < nks; ++s) {
;       const int q = s & 3;
;       G_MMA(afA, bfA)
;       __builtin_amdgcn_sched_barrier(0);
;       LGKM0_BAR
;       G_FRAGS(afB, bfB, q, fo1)
;       __builtin_amdgcn_sched_barrier(0);
;       LGKM0_BAR
;       G_MMA(afB, bfB)
;       __builtin_amdgcn_sched_barrier(0);
;       G_WAIT_BAR(s)
;       if (s + 4 < nks) DMA_STAGE(s + 4)
;       if (s + 1 < nks) G_FRAGS(afA, bfA, (s + 1) & 3, fo0)
;       __builtin_amdgcn_sched_barrier(0);
;       LGKM0_BAR
;     }
	ds_read_b128 v[128:131], v154 offset:32768
	ds_read_b128 v[132:135], v154 offset:34816
	ds_read_b128 v[136:139], v202 offset:49152
	ds_read_b128 v[140:143], v202 offset:51200
	ds_read_b128 v[144:147], v202 offset:53248
	ds_read_b128 v[148:151], v202 offset:55296
	v_xor_b32_e32 v154, 0x10000, v154
	v_xor_b32_e32 v202, 0x10000, v202
	s_add_u32 m0, s98, 0x0
	v_mfma_f32_32x32x16_bf16 v[112:127], v[194:197], v[206:209], v[112:127]
	global_load_lds_dwordx4 v[164:165], off
	v_mfma_f32_32x32x16_bf16 v[96:111], v[194:197], v[210:213], v[96:111]
	s_add_u32 m0, s98, 0x2000
	v_mfma_f32_32x32x16_bf16 v[80:95], v[194:197], v[214:217], v[80:95]
	global_load_lds_dwordx4 v[160:161], off
	v_mfma_f32_32x32x16_bf16 v[64:79], v[194:197], v[218:221], v[64:79]
	s_add_u32 m0, s98, 0x4000
	v_mfma_f32_32x32x16_bf16 v[48:63], v[198:201], v[206:209], v[48:63]
	global_load_lds_dwordx4 v[166:167], off
	v_mfma_f32_32x32x16_bf16 v[32:47], v[198:201], v[210:213], v[32:47]
	s_add_u32 m0, s98, 0x6000
	v_mfma_f32_32x32x16_bf16 v[16:31], v[198:201], v[214:217], v[16:31]
	global_load_lds_dwordx4 v[162:163], off
	v_mfma_f32_32x32x16_bf16 v[0:15], v[198:201], v[218:221], v[0:15]
	v_lshl_add_u64 v[164:165], v[164:165], 0, 64
	v_lshl_add_u64 v[160:161], v[160:161], 0, 64
	v_lshl_add_u64 v[166:167], v[166:167], 0, 64
	v_lshl_add_u64 v[162:163], v[162:163], 0, 64
	s_waitcnt lgkmcnt(0)
	v_mfma_f32_32x32x16_bf16 v[112:127], v[128:131], v[136:139], v[112:127]
	v_mfma_f32_32x32x16_bf16 v[96:111], v[128:131], v[140:143], v[96:111]
	ds_read_b128 v[194:197], v193 offset:32768
	ds_read_b128 v[198:201], v193 offset:34816
	v_mfma_f32_32x32x16_bf16 v[80:95], v[128:131], v[144:147], v[80:95]
	ds_read_b128 v[206:209], v203 offset:49152
	ds_read_b128 v[210:213], v203 offset:51200
	v_mfma_f32_32x32x16_bf16 v[64:79], v[128:131], v[148:151], v[64:79]
	ds_read_b128 v[214:217], v203 offset:53248
	ds_read_b128 v[218:221], v203 offset:55296
	v_mfma_f32_32x32x16_bf16 v[48:63], v[132:135], v[136:139], v[48:63]
	v_mfma_f32_32x32x16_bf16 v[32:47], v[132:135], v[140:143], v[32:47]
	v_mfma_f32_32x32x16_bf16 v[16:31], v[132:135], v[144:147], v[16:31]
	v_mfma_f32_32x32x16_bf16 v[0:15], v[132:135], v[148:151], v[0:15]
	v_xor_b32_e32 v193, 0x10000, v193
	v_xor_b32_e32 v203, 0x10000, v203
	s_waitcnt vmcnt(8)
	s_waitcnt lgkmcnt(0)
	s_barrier
	ds_read_b128 v[128:131], v154
	ds_read_b128 v[132:135], v154 offset:2048
	ds_read_b128 v[136:139], v202 offset:16384
	ds_read_b128 v[140:143], v202 offset:18432
	ds_read_b128 v[144:147], v202 offset:20480
	ds_read_b128 v[148:151], v202 offset:22528
	s_add_u32 m0, s98, 0x8000
	v_mfma_f32_32x32x16_bf16 v[112:127], v[194:197], v[206:209], v[112:127]
	global_load_lds_dwordx4 v[164:165], off
	v_mfma_f32_32x32x16_bf16 v[96:111], v[194:197], v[210:213], v[96:111]
	s_add_u32 m0, s98, 0xa000
	v_mfma_f32_32x32x16_bf16 v[80:95], v[194:197], v[214:217], v[80:95]
	global_load_lds_dwordx4 v[160:161], off
	v_mfma_f32_32x32x16_bf16 v[64:79], v[194:197], v[218:221], v[64:79]
	s_add_u32 m0, s98, 0xc000
	v_mfma_f32_32x32x16_bf16 v[48:63], v[198:201], v[206:209], v[48:63]
	global_load_lds_dwordx4 v[166:167], off
	v_mfma_f32_32x32x16_bf16 v[32:47], v[198:201], v[210:213], v[32:47]
	s_add_u32 m0, s98, 0xe000
	v_mfma_f32_32x32x16_bf16 v[16:31], v[198:201], v[214:217], v[16:31]
	global_load_lds_dwordx4 v[162:163], off
	v_mfma_f32_32x32x16_bf16 v[0:15], v[198:201], v[218:221], v[0:15]
	v_lshl_add_u64 v[164:165], v[164:165], 0, 64
	v_lshl_add_u64 v[160:161], v[160:161], 0, 64
	v_lshl_add_u64 v[166:167], v[166:167], 0, 64
	v_lshl_add_u64 v[162:163], v[162:163], 0, 64
	s_waitcnt lgkmcnt(0)
	v_mfma_f32_32x32x16_bf16 v[112:127], v[128:131], v[136:139], v[112:127]
	v_mfma_f32_32x32x16_bf16 v[96:111], v[128:131], v[140:143], v[96:111]
	ds_read_b128 v[194:197], v193
	ds_read_b128 v[198:201], v193 offset:2048
	v_mfma_f32_32x32x16_bf16 v[80:95], v[128:131], v[144:147], v[80:95]
	ds_read_b128 v[206:209], v203 offset:16384
	ds_read_b128 v[210:213], v203 offset:18432
	v_mfma_f32_32x32x16_bf16 v[64:79], v[128:131], v[148:151], v[64:79]
	ds_read_b128 v[214:217], v203 offset:20480
	ds_read_b128 v[218:221], v203 offset:22528
	v_mfma_f32_32x32x16_bf16 v[48:63], v[132:135], v[136:139], v[48:63]
	v_mfma_f32_32x32x16_bf16 v[32:47], v[132:135], v[140:143], v[32:47]
	v_mfma_f32_32x32x16_bf16 v[16:31], v[132:135], v[144:147], v[16:31]
	v_mfma_f32_32x32x16_bf16 v[0:15], v[132:135], v[148:151], v[0:15]
	s_waitcnt vmcnt(8)
	s_waitcnt lgkmcnt(0)
	s_barrier
; #define LGKM0_BAR asm volatile("s_waitcnt lgkmcnt(0)\n\ts_barrier" ::: "memory");
; __device__ __forceinline__ void gemm256_tile(const u16* Ab, int lda, const u16* Bb, int ldb, int K, char* smem,
;                                              f32x16 (&acc)[2][4]) {
;     ...
;   const int xsw = (lane >> 2) & 3, hh = lane >> 5;
;   const unsigned fo0 = (unsigned)((hh ^ xsw) * 16), fo1 = (unsigned)(((2 + hh) ^ xsw) * 16);
;   const unsigned fa = (unsigned)((wm * 64 + (lane & 31)) * 64);
;   const unsigned fb = (unsigned)(16384 + (wn * 128 + (lane & 31)) * 64);
;     ...
;   asm volatile("s_waitcnt vmcnt(0)" ::: "memory");
;   const bool h1 = __builtin_amdgcn_readfirstlane(wid) >= 4;
;     ...
;   DMA_STAGE(0)
;   if (nks > 1) DMA_STAGE(1)
;   if (nks > 2) DMA_STAGE(2)
;   if (nks > 3) DMA_STAGE(3)
;   if (nks > 3)      asm volatile("s_waitcnt vmcnt(12)\n\ts_barrier" ::: "memory");
;   else if (nks > 2) asm volatile("s_waitcnt vmcnt(8)\n\ts_barrier" ::: "memory");
;   else if (nks > 1) asm volatile("s_waitcnt vmcnt(4)\n\ts_barrier" ::: "memory");
;   else              asm volatile("s_waitcnt vmcnt(0)\n\ts_barrier" ::: "memory");
;   bf16x8 afA[2], bfA[4], afB[2], bfB[4];
;   if (!h1) {
;     G_FRAGS(afA, bfA, 0, fo0)
;     LGKM0_BAR
;     for (int s = 0; s < nks; ++s) {
;       const int q = s & 3;
;       G_MMA(afA, bfA)
;       __builtin_amdgcn_sched_barrier(0);
;       LGKM0_BAR
;       G_FRAGS(afB, bfB, q, fo1)
;       __builtin_amdgcn_sched_barrier(0);
;       LGKM0_BAR
;       G_MMA(afB, bfB)
;       __builtin_amdgcn_sched_barrier(0);
;       G_WAIT_BAR(s)
;       if (s + 4 < nks) DMA_STAGE(s + 4)
;       if (s + 1 < nks) G_FRAGS(afA, bfA, (s + 1) & 3, fo0)
;       __builtin_amdgcn_sched_barrier(0);
;       LGKM0_BAR
;     }
	ds_read_b128 v[128:131], v154 offset:32768
	ds_read_b128 v[132:135], v154 offset:34816
	ds_read_b128 v[136:139], v202 offset:49152
	ds_read_b128 v[140:143], v202 offset:51200
	ds_read_b128 v[144:147], v202 offset:53248
	ds_read_b128 v[148:151], v202 offset:55296
	v_xor_b32_e32 v154, 0x10000, v154
	v_xor_b32_e32 v202, 0x10000, v202
	s_add_u32 m0, s98, 0x10000
	v_mfma_f32_32x32x16_bf16 v[112:127], v[194:197], v[206:209], v[112:127]
	global_load_lds_dwordx4 v[164:165], off
	v_mfma_f32_32x32x16_bf16 v[96:111], v[194:197], v[210:213], v[96:111]
	s_add_u32 m0, s98, 0x12000
	v_mfma_f32_32x32x16_bf16 v[80:95], v[194:197], v[214:217], v[80:95]
	global_load_lds_dwordx4 v[160:161], off
	v_mfma_f32_32x32x16_bf16 v[64:79], v[194:197], v[218:221], v[64:79]
	s_add_u32 m0, s98, 0x14000
	v_mfma_f32_32x32x16_bf16 v[48:63], v[198:201], v[206:209], v[48:63]
	global_load_lds_dwordx4 v[166:167], off
	v_mfma_f32_32x32x16_bf16 v[32:47], v[198:201], v[210:213], v[32:47]
	s_add_u32 m0, s98, 0x16000
	v_mfma_f32_32x32x16_bf16 v[16:31], v[198:201], v[214:217], v[16:31]
	global_load_lds_dwordx4 v[162:163], off
	v_mfma_f32_32x32x16_bf16 v[0:15], v[198:201], v[218:221], v[0:15]
	v_lshl_add_u64 v[164:165], v[164:165], 0, 64
	v_lshl_add_u64 v[160:161], v[160:161], 0, 64
	v_lshl_add_u64 v[166:167], v[166:167], 0, 64
	v_lshl_add_u64 v[162:163], v[162:163], 0, 64
	s_waitcnt lgkmcnt(0)
	v_mfma_f32_32x32x16_bf16 v[112:127], v[128:131], v[136:139], v[112:127]
	v_mfma_f32_32x32x16_bf16 v[96:111], v[128:131], v[140:143], v[96:111]
	ds_read_b128 v[194:197], v193 offset:32768
	ds_read_b128 v[198:201], v193 offset:34816
	v_mfma_f32_32x32x16_bf16 v[80:95], v[128:131], v[144:147], v[80:95]
	ds_read_b128 v[206:209], v203 offset:49152
	ds_read_b128 v[210:213], v203 offset:51200
	v_mfma_f32_32x32x16_bf16 v[64:79], v[128:131], v[148:151], v[64:79]
	ds_read_b128 v[214:217], v203 offset:53248
	ds_read_b128 v[218:221], v203 offset:55296
	v_mfma_f32_32x32x16_bf16 v[48:63], v[132:135], v[136:139], v[48:63]
	v_mfma_f32_32x32x16_bf16 v[32:47], v[132:135], v[140:143], v[32:47]
	v_mfma_f32_32x32x16_bf16 v[16:31], v[132:135], v[144:147], v[16:31]
	v_mfma_f32_32x32x16_bf16 v[0:15], v[132:135], v[148:151], v[0:15]
	v_xor_b32_e32 v193, 0x10000, v193
	v_xor_b32_e32 v203, 0x10000, v203
	s_waitcnt vmcnt(8)
	s_waitcnt lgkmcnt(0)
	s_sub_u32 s99, s99, 1
	s_cmp_lg_u32 s99, 0
	s_cbranch_scc1 .Lmy_gemm_i4_loop
	s_barrier
	ds_read_b128 v[128:131], v154
	ds_read_b128 v[132:135], v154 offset:2048
	ds_read_b128 v[136:139], v202 offset:16384
	ds_read_b128 v[140:143], v202 offset:18432
	ds_read_b128 v[144:147], v202 offset:20480
	ds_read_b128 v[148:151], v202 offset:22528
	s_add_u32 m0, s98, 0x18000
	v_mfma_f32_32x32x16_bf16 v[112:127], v[194:197], v[206:209], v[112:127]
	global_load_lds_dwordx4 v[164:165], off
	v_mfma_f32_32x32x16_bf16 v[96:111], v[194:197], v[210:213], v[96:111]
	s_add_u32 m0, s98, 0x1a000
	v_mfma_f32_32x32x16_bf16 v[80:95], v[194:197], v[214:217], v[80:95]
	global_load_lds_dwordx4 v[160:161], off
	v_mfma_f32_32x32x16_bf16 v[64:79], v[194:197], v[218:221], v[64:79]
	s_add_u32 m0, s98, 0x1c000
	v_mfma_f32_32x32x16_bf16 v[48:63], v[198:201], v[206:209], v[48:63]
	global_load_lds_dwordx4 v[166:167], off
	v_mfma_f32_32x32x16_bf16 v[32:47], v[198:201], v[210:213], v[32:47]
	s_add_u32 m0, s98, 0x1e000
	v_mfma_f32_32x32x16_bf16 v[16:31], v[198:201], v[214:217], v[16:31]
	global_load_lds_dwordx4 v[162:163], off
	v_mfma_f32_32x32x16_bf16 v[0:15], v[198:201], v[218:221], v[0:15]
	v_lshl_add_u64 v[164:165], v[164:165], 0, 64
	v_lshl_add_u64 v[160:161], v[160:161], 0, 64
	v_lshl_add_u64 v[166:167], v[166:167], 0, 64
	v_lshl_add_u64 v[162:163], v[162:163], 0, 64
	s_waitcnt lgkmcnt(0)
	v_mfma_f32_32x32x16_bf16 v[112:127], v[128:131], v[136:139], v[112:127]
	v_mfma_f32_32x32x16_bf16 v[96:111], v[128:131], v[140:143], v[96:111]
	ds_read_b128 v[194:197], v193
	ds_read_b128 v[198:201], v193 offset:2048
	v_mfma_f32_32x32x16_bf16 v[80:95], v[128:131], v[144:147], v[80:95]
	ds_read_b128 v[206:209], v203 offset:16384
	ds_read_b128 v[210:213], v203 offset:18432
	v_mfma_f32_32x32x16_bf16 v[64:79], v[128:131], v[148:151], v[64:79]
	ds_read_b128 v[214:217], v203 offset:20480
	ds_read_b128 v[218:221], v203 offset:22528
	v_mfma_f32_32x32x16_bf16 v[48:63], v[132:135], v[136:139], v[48:63]
	v_mfma_f32_32x32x16_bf16 v[32:47], v[132:135], v[140:143], v[32:47]
	v_mfma_f32_32x32x16_bf16 v[16:31], v[132:135], v[144:147], v[16:31]
	v_mfma_f32_32x32x16_bf16 v[0:15], v[132:135], v[148:151], v[0:15]
	s_waitcnt vmcnt(8)
	s_waitcnt lgkmcnt(0)
	s_barrier
; #define LGKM0_BAR asm volatile("s_waitcnt lgkmcnt(0)\n\ts_barrier" ::: "memory");
; __device__ __forceinline__ void gemm256_tile(const u16* Ab, int lda, const u16* Bb, int ldb, int K, char* smem,
;                                              f32x16 (&acc)[2][4]) {
;     ...
;   asm volatile("s_waitcnt vmcnt(0)" ::: "memory");
;   const bool h1 = __builtin_amdgcn_readfirstlane(wid) >= 4;
;     ...
;   DMA_STAGE(0)
;   if (nks > 1) DMA_STAGE(1)
;   if (nks > 2) DMA_STAGE(2)
;   if (nks > 3) DMA_STAGE(3)
;   if (nks > 3)      asm volatile("s_waitcnt vmcnt(12)\n\ts_barrier" ::: "memory");
;   else if (nks > 2) asm volatile("s_waitcnt vmcnt(8)\n\ts_barrier" ::: "memory");
;   else if (nks > 1) asm volatile("s_waitcnt vmcnt(4)\n\ts_barrier" ::: "memory");
;   else              asm volatile("s_waitcnt vmcnt(0)\n\ts_barrier" ::: "memory");
;   bf16x8 afA[2], bfA[4], afB[2], bfB[4];
;   if (!h1) {
;     G_FRAGS(afA, bfA, 0, fo0)
;     LGKM0_BAR
;     for (int s = 0; s < nks; ++s) {
;       const int q = s & 3;
;       G_MMA(afA, bfA)
;       __builtin_amdgcn_sched_barrier(0);
;       LGKM0_BAR
;       G_FRAGS(afB, bfB, q, fo1)
;       __builtin_amdgcn_sched_barrier(0);
;       LGKM0_BAR
;       G_MMA(afB, bfB)
;       __builtin_amdgcn_sched_barrier(0);
;       G_WAIT_BAR(s)
;       if (s + 4 < nks) DMA_STAGE(s + 4)
;       if (s + 1 < nks) G_FRAGS(afA, bfA, (s + 1) & 3, fo0)
;       __builtin_amdgcn_sched_barrier(0);
;       LGKM0_BAR
;     }
;   } else {
;     LGKM0_BAR
;     for (int s = 0; s < nks; ++s) {
;       const int q = s & 3;
;       G_FRAGS(afA, bfA, q, fo0)
;       __builtin_amdgcn_sched_barrier(0);
;       LGKM0_BAR
;       G_MMA(afA, bfA)
;       __builtin_amdgcn_sched_barrier(0);
;       LGKM0_BAR
;       G_FRAGS(afB, bfB, q, fo1)
;       __builtin_amdgcn_sched_barrier(0);
;       G_WAIT_BAR(s)
;       G_MMA(afB, bfB)
;       __builtin_amdgcn_sched_barrier(0);
;       if (s + 4 < nks) DMA_STAGE(s + 4)
;       __builtin_amdgcn_sched_barrier(0);
;       LGKM0_BAR
;     }
;   }
;     ...
;   __syncthreads();
	ds_read_b128 v[128:131], v154 offset:32768
	ds_read_b128 v[132:135], v154 offset:34816
	ds_read_b128 v[136:139], v202 offset:49152
	ds_read_b128 v[140:143], v202 offset:51200
	ds_read_b128 v[144:147], v202 offset:53248
	ds_read_b128 v[148:151], v202 offset:55296
	v_xor_b32_e32 v154, 0x10000, v154
	v_xor_b32_e32 v202, 0x10000, v202
	v_mfma_f32_32x32x16_bf16 v[112:127], v[194:197], v[206:209], v[112:127]
	v_mfma_f32_32x32x16_bf16 v[96:111], v[194:197], v[210:213], v[96:111]
	v_mfma_f32_32x32x16_bf16 v[80:95], v[194:197], v[214:217], v[80:95]
	v_mfma_f32_32x32x16_bf16 v[64:79], v[194:197], v[218:221], v[64:79]
	v_mfma_f32_32x32x16_bf16 v[48:63], v[198:201], v[206:209], v[48:63]
	v_mfma_f32_32x32x16_bf16 v[32:47], v[198:201], v[210:213], v[32:47]
	v_mfma_f32_32x32x16_bf16 v[16:31], v[198:201], v[214:217], v[16:31]
	v_mfma_f32_32x32x16_bf16 v[0:15], v[198:201], v[218:221], v[0:15]
	s_waitcnt lgkmcnt(0)
	v_mfma_f32_32x32x16_bf16 v[112:127], v[128:131], v[136:139], v[112:127]
	v_mfma_f32_32x32x16_bf16 v[96:111], v[128:131], v[140:143], v[96:111]
	ds_read_b128 v[194:197], v193 offset:32768
	ds_read_b128 v[198:201], v193 offset:34816
	v_mfma_f32_32x32x16_bf16 v[80:95], v[128:131], v[144:147], v[80:95]
	ds_read_b128 v[206:209], v203 offset:49152
	ds_read_b128 v[210:213], v203 offset:51200
	v_mfma_f32_32x32x16_bf16 v[64:79], v[128:131], v[148:151], v[64:79]
	ds_read_b128 v[214:217], v203 offset:53248
	ds_read_b128 v[218:221], v203 offset:55296
	v_mfma_f32_32x32x16_bf16 v[48:63], v[132:135], v[136:139], v[48:63]
	v_mfma_f32_32x32x16_bf16 v[32:47], v[132:135], v[140:143], v[32:47]
	v_mfma_f32_32x32x16_bf16 v[16:31], v[132:135], v[144:147], v[16:31]
	v_mfma_f32_32x32x16_bf16 v[0:15], v[132:135], v[148:151], v[0:15]
	v_xor_b32_e32 v193, 0x10000, v193
	v_xor_b32_e32 v203, 0x10000, v203
	s_waitcnt vmcnt(4)
	s_waitcnt lgkmcnt(0)
	s_barrier
	ds_read_b128 v[128:131], v154
	ds_read_b128 v[132:135], v154 offset:2048
	ds_read_b128 v[136:139], v202 offset:16384
	ds_read_b128 v[140:143], v202 offset:18432
	ds_read_b128 v[144:147], v202 offset:20480
	ds_read_b128 v[148:151], v202 offset:22528
	v_mfma_f32_32x32x16_bf16 v[112:127], v[194:197], v[206:209], v[112:127]
	v_mfma_f32_32x32x16_bf16 v[96:111], v[194:197], v[210:213], v[96:111]
	v_mfma_f32_32x32x16_bf16 v[80:95], v[194:197], v[214:217], v[80:95]
	v_mfma_f32_32x32x16_bf16 v[64:79], v[194:197], v[218:221], v[64:79]
	v_mfma_f32_32x32x16_bf16 v[48:63], v[198:201], v[206:209], v[48:63]
	v_mfma_f32_32x32x16_bf16 v[32:47], v[198:201], v[210:213], v[32:47]
	v_mfma_f32_32x32x16_bf16 v[16:31], v[198:201], v[214:217], v[16:31]
	v_mfma_f32_32x32x16_bf16 v[0:15], v[198:201], v[218:221], v[0:15]
	s_waitcnt lgkmcnt(0)
	v_mfma_f32_32x32x16_bf16 v[112:127], v[128:131], v[136:139], v[112:127]
	v_mfma_f32_32x32x16_bf16 v[96:111], v[128:131], v[140:143], v[96:111]
	ds_read_b128 v[194:197], v193
	ds_read_b128 v[198:201], v193 offset:2048
	v_mfma_f32_32x32x16_bf16 v[80:95], v[128:131], v[144:147], v[80:95]
	ds_read_b128 v[206:209], v203 offset:16384
	ds_read_b128 v[210:213], v203 offset:18432
	v_mfma_f32_32x32x16_bf16 v[64:79], v[128:131], v[148:151], v[64:79]
	ds_read_b128 v[214:217], v203 offset:20480
	ds_read_b128 v[218:221], v203 offset:22528
	v_mfma_f32_32x32x16_bf16 v[48:63], v[132:135], v[136:139], v[48:63]
	v_mfma_f32_32x32x16_bf16 v[32:47], v[132:135], v[140:143], v[32:47]
	v_mfma_f32_32x32x16_bf16 v[16:31], v[132:135], v[144:147], v[16:31]
	v_mfma_f32_32x32x16_bf16 v[0:15], v[132:135], v[148:151], v[0:15]
	s_waitcnt vmcnt(0)
	s_waitcnt lgkmcnt(0)
	s_barrier
	ds_read_b128 v[128:131], v154 offset:32768
	ds_read_b128 v[132:135], v154 offset:34816
	ds_read_b128 v[136:139], v202 offset:49152
	ds_read_b128 v[140:143], v202 offset:51200
	ds_read_b128 v[144:147], v202 offset:53248
	ds_read_b128 v[148:151], v202 offset:55296
	v_xor_b32_e32 v154, 0x10000, v154
	v_xor_b32_e32 v202, 0x10000, v202
	v_mfma_f32_32x32x16_bf16 v[112:127], v[194:197], v[206:209], v[112:127]
	v_mfma_f32_32x32x16_bf16 v[96:111], v[194:197], v[210:213], v[96:111]
	v_mfma_f32_32x32x16_bf16 v[80:95], v[194:197], v[214:217], v[80:95]
	v_mfma_f32_32x32x16_bf16 v[64:79], v[194:197], v[218:221], v[64:79]
	v_mfma_f32_32x32x16_bf16 v[48:63], v[198:201], v[206:209], v[48:63]
	v_mfma_f32_32x32x16_bf16 v[32:47], v[198:201], v[210:213], v[32:47]
	v_mfma_f32_32x32x16_bf16 v[16:31], v[198:201], v[214:217], v[16:31]
	v_mfma_f32_32x32x16_bf16 v[0:15], v[198:201], v[218:221], v[0:15]
	s_waitcnt lgkmcnt(0)
	v_mfma_f32_32x32x16_bf16 v[112:127], v[128:131], v[136:139], v[112:127]
	v_mfma_f32_32x32x16_bf16 v[96:111], v[128:131], v[140:143], v[96:111]
	ds_read_b128 v[194:197], v193 offset:32768
	ds_read_b128 v[198:201], v193 offset:34816
	v_mfma_f32_32x32x16_bf16 v[80:95], v[128:131], v[144:147], v[80:95]
	ds_read_b128 v[206:209], v203 offset:49152
	ds_read_b128 v[210:213], v203 offset:51200
	v_mfma_f32_32x32x16_bf16 v[64:79], v[128:131], v[148:151], v[64:79]
	ds_read_b128 v[214:217], v203 offset:53248
	ds_read_b128 v[218:221], v203 offset:55296
	v_mfma_f32_32x32x16_bf16 v[48:63], v[132:135], v[136:139], v[48:63]
	v_mfma_f32_32x32x16_bf16 v[32:47], v[132:135], v[140:143], v[32:47]
	v_mfma_f32_32x32x16_bf16 v[16:31], v[132:135], v[144:147], v[16:31]
	v_mfma_f32_32x32x16_bf16 v[0:15], v[132:135], v[148:151], v[0:15]
	v_xor_b32_e32 v193, 0x10000, v193
	v_xor_b32_e32 v203, 0x10000, v203
	s_waitcnt lgkmcnt(0)
	v_mfma_f32_32x32x16_bf16 v[112:127], v[194:197], v[206:209], v[112:127]
	v_mfma_f32_32x32x16_bf16 v[96:111], v[194:197], v[210:213], v[96:111]
	v_mfma_f32_32x32x16_bf16 v[80:95], v[194:197], v[214:217], v[80:95]
	v_mfma_f32_32x32x16_bf16 v[64:79], v[194:197], v[218:221], v[64:79]
	v_mfma_f32_32x32x16_bf16 v[48:63], v[198:201], v[206:209], v[48:63]
	v_mfma_f32_32x32x16_bf16 v[32:47], v[198:201], v[210:213], v[32:47]
	v_mfma_f32_32x32x16_bf16 v[16:31], v[198:201], v[214:217], v[16:31]
	v_mfma_f32_32x32x16_bf16 v[0:15], v[198:201], v[218:221], v[0:15]
	s_nop 15
	s_branch .LBB0_1428

; #define LAS __attribute__((address_space(3)))
; #define RUN_PH(n) if (lo <= (n) && (n) < hi) { run_phase(P, (n), smem_raw); if ((DUPMASK >> (n)) & 1) run_phase(P, (n), smem_raw); if ((n) + 1 < hi) { XcdBarrier xb_; xb_.bar = P.bar; xb_.x = xb_xcc_id(); xb_.st = (volatile LAS unsigned*)&xb_words; xcd_barrier(xb_); } }
; __global__ void __launch_bounds__(NTHR) mega_kernel(Params P, int lo, int hi) {
;   extern __shared__ __attribute__((aligned(16))) char smem_raw[];
;   __shared__ uint4 xb_words;
;   cg::grid_group grid = cg::this_grid();
;   if (threadIdx.x == 0) xb_words = make_uint4(0u, 0u, 0u, 0u);
;   if (blockIdx.x == 0) for (int i = threadIdx.x; i < XCD_BAR_WORDS; i += NTHR) P.bar[i] = 0u;
;   __syncthreads();
;   if (lo <= 0 && 0 < hi) { run_phase(P, 0, smem_raw); if (1 < hi) { grid.sync(); (void)xcd_barrier_post(P.bar, (volatile LAS unsigned*)&xb_words); } }
;     ...
;   RUN_PH(1) RUN_PH(2) RUN_PH(3) RUN_PH(4) RUN_PH(5) RUN_PH(6) RUN_PH(7) RUN_PH(8)
;   RUN_PH(9) RUN_PH(10) RUN_PH(11) RUN_PH(12) RUN_PH(13) RUN_PH(14) RUN_PH(15) RUN_PH(16) RUN_PH(17)
; }
	.amdhsa_kernel _Z11mega_kernel6Paramsii
		.amdhsa_group_segment_fixed_size 16
		.amdhsa_private_segment_fixed_size 0
		.amdhsa_kernarg_size 624
		.amdhsa_user_sgpr_count 2
		.amdhsa_user_sgpr_dispatch_ptr 0
		.amdhsa_user_sgpr_queue_ptr 0
		.amdhsa_user_sgpr_kernarg_segment_ptr 1
		.amdhsa_user_sgpr_dispatch_id 0
		.amdhsa_user_sgpr_kernarg_preload_length 0
		.amdhsa_user_sgpr_kernarg_preload_offset 0
		.amdhsa_user_sgpr_private_segment_size 0
		.amdhsa_uses_dynamic_stack 0
		.amdhsa_enable_private_segment 0
		.amdhsa_system_sgpr_workgroup_id_x 1
		.amdhsa_system_sgpr_workgroup_id_y 0
		.amdhsa_system_sgpr_workgroup_id_z 0
		.amdhsa_system_sgpr_workgroup_info 0
		.amdhsa_system_vgpr_workitem_id 2
		.amdhsa_next_free_vgpr 256
		.amdhsa_next_free_sgpr 102
		.amdhsa_accum_offset 256
		.amdhsa_reserve_vcc 1
		.amdhsa_float_round_mode_32 0
		.amdhsa_float_round_mode_16_64 0
		.amdhsa_float_denorm_mode_32 3
		.amdhsa_float_denorm_mode_16_64 3
		.amdhsa_dx10_clamp 1
		.amdhsa_ieee_mode 1
		.amdhsa_fp16_overflow 0
		.amdhsa_tg_split 0
		.amdhsa_exception_fp_ieee_invalid_op 0
		.amdhsa_exception_fp_denorm_src 0
		.amdhsa_exception_fp_ieee_div_zero 0
		.amdhsa_exception_fp_ieee_overflow 0
		.amdhsa_exception_fp_ieee_underflow 0
		.amdhsa_exception_fp_ieee_inexact 0
		.amdhsa_exception_int_div_zero 0
	.end_amdhsa_kernel

; __global__ void __launch_bounds__(NTHR) mega_kernel(Params P, int lo, int hi) {
;   extern __shared__ __attribute__((aligned(16))) char smem_raw[];
amdhsa.kernels:
  - .agpr_count:     0
    .args:
      - .offset:         0
        .size:           360
        .value_kind:     by_value
      - .offset:         360
        .size:           4
        .value_kind:     by_value
      - .offset:         364
        .size:           4
        .value_kind:     by_value
      - .offset:         368
        .size:           4
        .value_kind:     hidden_block_count_x
      - .offset:         372
        .size:           4
        .value_kind:     hidden_block_count_y
      - .offset:         376
        .size:           4
        .value_kind:     hidden_block_count_z
      - .offset:         380
        .size:           2
        .value_kind:     hidden_group_size_x
      - .offset:         382
        .size:           2
        .value_kind:     hidden_group_size_y
      - .offset:         384
        .size:           2
        .value_kind:     hidden_group_size_z
      - .offset:         386
        .size:           2
        .value_kind:     hidden_remainder_x
      - .offset:         388
        .size:           2
        .value_kind:     hidden_remainder_y
      - .offset:         390
        .size:           2
        .value_kind:     hidden_remainder_z
      - .offset:         408
        .size:           8
        .value_kind:     hidden_global_offset_x
      - .offset:         416
        .size:           8
        .value_kind:     hidden_global_offset_y
      - .offset:         424
        .size:           8
        .value_kind:     hidden_global_offset_z
      - .offset:         432
        .size:           2
        .value_kind:     hidden_grid_dims
      - .offset:         456
        .size:           8
        .value_kind:     hidden_multigrid_sync_arg
      - .offset:         488
        .size:           4
        .value_kind:     hidden_dynamic_lds_size
    .group_segment_fixed_size: 16
    .kernarg_segment_align: 8
    .kernarg_segment_size: 624
    .language:       OpenCL C
    .language_version:
      - 2
      - 0
    .max_flat_workgroup_size: 512
    .name:           _Z11mega_kernel6Paramsii
    .private_segment_fixed_size: 0
    .sgpr_count:     108
    .sgpr_spill_count: 54
    .symbol:         _Z11mega_kernel6Paramsii.kd
    .uniform_work_group_size: 1
    .uses_dynamic_stack: false
    .vgpr_count:     256
    .vgpr_spill_count: 0
    .wavefront_size: 64
